# sample-task seg_attend: q-vector LDS reads renamed into scratch quads and kept 5 deep in flight (counted lgkmcnt) instead of read-wait-use per quad
# speedup vs baseline: 1.0264x; 1.0037x over previous
; #define LAS __attribute__((address_space(3)))
; __device__ __forceinline__ void seg_attend(SegAcc& A, const float* base, int kvh, int nk, bool valid, const LAS float* qs, LAS float* pt, int lane) {
;     f32x4 kv[16]; float vv[64];
;     const f32x4* kp = (const f32x4*)(base + (size_t)(lane < nk ? lane : 0) * 256 + kvh * 64);
; #pragma unroll
;     for (int c4 = 0; c4 < 16; ++c4) kv[c4] = kp[c4];
;     const float* vb = base + 128 + kvh * 64 + lane;
; #pragma unroll
;     for (int k = 0; k < 64; ++k) vv[k] = vb[(size_t)(k < nk ? k : 0) * 256];
; __device__ __forceinline__ void sample_task_part2(const Prm& P, Ctx& C, int b, int kvh, int ts) {
;     ...
; #pragma unroll 1
;     for (int si = C.wave; si < 16; si += NWAVES) { const bool last = blist[si] >= 256; seg_attend(As, (const float*)(uintptr_t)segb[si], kvh, last ? 4 : 64, last ? lane <= ts : true, qs, ptab, lane); }
.LBB0_1573:
	v_mov_b32_e32 v0, s2
	ds_read_b32 v0, v0
	v_mov_b32_e32 v83, v110
	v_mov_b32_e32 v81, v108
	v_mov_b32_e32 v79, v106
	v_mov_b32_e32 v77, v104
	s_waitcnt lgkmcnt(0)
	v_readfirstlane_b32 s0, v0
	s_cmpk_lt_i32 s0, 0x100
	s_cselect_b64 s[4:5], -1, 0
	v_mov_b32_e32 v0, s3
	s_and_b64 s[0:1], s[4:5], exec
	ds_read_b64 v[66:67], v0
	s_cselect_b32 s6, 64, 4
	v_cmp_gt_i32_e32 vcc, s6, v98
	s_lshl_b32 s78, s33, 2
	s_or_b64 s[0:1], s[46:47], s[4:5]
	v_cndmask_b32_e32 v2, 0, v98, vcc
	v_ashrrev_i32_e32 v3, 31, v2
	v_lshlrev_b64 v[2:3], 10, v[2:3]
	s_waitcnt lgkmcnt(0)
	v_lshl_add_u64 v[2:3], v[66:67], 0, v[2:3]
	v_lshl_add_u64 v[2:3], v[2:3], 0, s[78:79]
	flat_load_dwordx4 v[62:65], v[2:3]
	flat_load_dwordx4 v[58:61], v[2:3] offset:16
	flat_load_dwordx4 v[54:57], v[2:3] offset:32
	flat_load_dwordx4 v[50:53], v[2:3] offset:48
	flat_load_dwordx4 v[46:49], v[2:3] offset:64
	flat_load_dwordx4 v[42:45], v[2:3] offset:80
	flat_load_dwordx4 v[38:41], v[2:3] offset:96
	flat_load_dwordx4 v[34:37], v[2:3] offset:112
	flat_load_dwordx4 v[30:33], v[2:3] offset:128
	flat_load_dwordx4 v[26:29], v[2:3] offset:144
	flat_load_dwordx4 v[22:25], v[2:3] offset:160
	flat_load_dwordx4 v[18:21], v[2:3] offset:176
	flat_load_dwordx4 v[14:17], v[2:3] offset:192
	flat_load_dwordx4 v[10:13], v[2:3] offset:208
	flat_load_dwordx4 v[6:9], v[2:3] offset:224
	s_nop 0
	flat_load_dwordx4 v[2:5], v[2:3] offset:240
	v_lshl_add_u64 v[66:67], v[66:67], 0, s[78:79]
	s_and_b64 s[4:5], s[4:5], exec
	v_lshl_add_u64 v[66:67], v[98:99], 2, v[66:67]
	s_cselect_b32 s78, 0x1000, 0
	v_lshl_add_u64 v[68:69], v[66:67], 0, s[78:79]
	s_cselect_b32 s78, 0x1400, 0
	flat_load_dword v138, v[66:67] offset:512
	flat_load_dword v132, v[66:67] offset:1536
	flat_load_dword v134, v[66:67] offset:2560
	flat_load_dword v136, v[66:67] offset:3584
	flat_load_dword v174, v[68:69] offset:512
	v_lshl_add_u64 v[68:69], v[66:67], 0, s[78:79]
	s_cselect_b32 s78, 0x1800, 0
	flat_load_dword v186, v[68:69] offset:512
	v_lshl_add_u64 v[68:69], v[66:67], 0, s[78:79]
	s_cselect_b32 s78, 0x1c00, 0
	flat_load_dword v198, v[68:69] offset:512
	v_lshl_add_u64 v[68:69], v[66:67], 0, s[78:79]
	s_cselect_b32 s78, 0x2000, 0
	flat_load_dword v210, v[68:69] offset:512
	v_lshl_add_u64 v[68:69], v[66:67], 0, s[78:79]
	s_cselect_b32 s78, 0x2400, 0
	flat_load_dword v222, v[68:69] offset:512
	v_lshl_add_u64 v[68:69], v[66:67], 0, s[78:79]
	s_cselect_b32 s78, 0x2800, 0
	flat_load_dword v0, v[68:69] offset:512
	v_lshl_add_u64 v[68:69], v[66:67], 0, s[78:79]
	s_cselect_b32 s78, 0x2c00, 0
	flat_load_dword v78, v[68:69] offset:512
	v_lshl_add_u64 v[68:69], v[66:67], 0, s[78:79]
	s_cselect_b32 s78, 0x3000, 0
	flat_load_dword v88, v[68:69] offset:512
	v_lshl_add_u64 v[68:69], v[66:67], 0, s[78:79]
	s_cselect_b32 s78, 0x3400, 0
	flat_load_dword v112, v[68:69] offset:512
	v_lshl_add_u64 v[68:69], v[66:67], 0, s[78:79]
	s_cselect_b32 s78, 0x3800, 0
	flat_load_dword v122, v[68:69] offset:512
	v_lshl_add_u64 v[68:69], v[66:67], 0, s[78:79]
	s_cselect_b32 s78, 0x3c00, 0
	flat_load_dword v140, v[68:69] offset:512
	v_lshl_add_u64 v[68:69], v[66:67], 0, s[78:79]
	s_cselect_b32 s78, 0x4000, 0
	flat_load_dword v176, v[68:69] offset:512
	v_lshl_add_u64 v[68:69], v[66:67], 0, s[78:79]
	s_cselect_b32 s78, 0x4400, 0
	flat_load_dword v188, v[68:69] offset:512
	v_lshl_add_u64 v[68:69], v[66:67], 0, s[78:79]
	s_cselect_b32 s78, 0x4800, 0
	flat_load_dword v200, v[68:69] offset:512
	v_lshl_add_u64 v[68:69], v[66:67], 0, s[78:79]
	s_cselect_b32 s78, 0x4c00, 0
	flat_load_dword v212, v[68:69] offset:512
	v_lshl_add_u64 v[68:69], v[66:67], 0, s[78:79]
	s_cselect_b32 s78, 0x5000, 0
	flat_load_dword v224, v[68:69] offset:512
	v_lshl_add_u64 v[68:69], v[66:67], 0, s[78:79]
	s_cselect_b32 s78, 0x5400, 0
	flat_load_dword v70, v[68:69] offset:512
	v_lshl_add_u64 v[68:69], v[66:67], 0, s[78:79]
	s_cselect_b32 s78, 0x5800, 0
	flat_load_dword v80, v[68:69] offset:512
	v_lshl_add_u64 v[68:69], v[66:67], 0, s[78:79]
	s_cselect_b32 s78, 0x5c00, 0
	flat_load_dword v90, v[68:69] offset:512
	v_lshl_add_u64 v[68:69], v[66:67], 0, s[78:79]
	s_cselect_b32 s78, 0x6000, 0
	flat_load_dword v114, v[68:69] offset:512
	v_lshl_add_u64 v[68:69], v[66:67], 0, s[78:79]
	s_cselect_b32 s78, 0x6400, 0
	flat_load_dword v124, v[68:69] offset:512
	v_lshl_add_u64 v[68:69], v[66:67], 0, s[78:79]
	s_cselect_b32 s78, 0x6800, 0
	flat_load_dword v142, v[68:69] offset:512
	v_lshl_add_u64 v[68:69], v[66:67], 0, s[78:79]
	s_cselect_b32 s78, 0x6c00, 0
	flat_load_dword v178, v[68:69] offset:512
	v_lshl_add_u64 v[68:69], v[66:67], 0, s[78:79]
	s_cselect_b32 s78, 0x7000, 0
	flat_load_dword v190, v[68:69] offset:512
	v_lshl_add_u64 v[68:69], v[66:67], 0, s[78:79]
	s_cselect_b32 s78, 0x7400, 0
	flat_load_dword v202, v[68:69] offset:512
	v_lshl_add_u64 v[68:69], v[66:67], 0, s[78:79]
	s_cselect_b32 s78, 0x7800, 0
	flat_load_dword v214, v[68:69] offset:512
	v_lshl_add_u64 v[68:69], v[66:67], 0, s[78:79]
	s_cselect_b32 s78, 0x7c00, 0
	flat_load_dword v226, v[68:69] offset:512
	v_lshl_add_u64 v[68:69], v[66:67], 0, s[78:79]
	s_cselect_b32 s78, 0x8000, 0
	flat_load_dword v72, v[68:69] offset:512
	v_lshl_add_u64 v[68:69], v[66:67], 0, s[78:79]
	s_cselect_b32 s78, 0x8400, 0
	flat_load_dword v82, v[68:69] offset:512
	v_lshl_add_u64 v[68:69], v[66:67], 0, s[78:79]
	s_cselect_b32 s78, 0x8800, 0
	flat_load_dword v92, v[68:69] offset:512
	v_lshl_add_u64 v[68:69], v[66:67], 0, s[78:79]
	s_cselect_b32 s78, 0x8c00, 0
	flat_load_dword v116, v[68:69] offset:512
	v_lshl_add_u64 v[68:69], v[66:67], 0, s[78:79]
	s_cselect_b32 s78, 0x9000, 0
	flat_load_dword v126, v[68:69] offset:512
	v_lshl_add_u64 v[68:69], v[66:67], 0, s[78:79]
; #define LAS __attribute__((address_space(3)))
; __device__ __forceinline__ void seg_attend(SegAcc& A, const float* base, int kvh, int nk, bool valid, const LAS float* qs, LAS float* pt, int lane) {
;     ...
;     float s[4] = {0.f, 0.f, 0.f, 0.f};
; #pragma unroll
;     for (int c4 = 0; c4 < 16; ++c4)
; #pragma unroll
;         for (int gq = 0; gq < 4; ++gq) { const f32x4 qv = *(const LAS f32x4*)(qs + gq * 64 + 4 * c4); s[gq] += kv[c4][0] * qv[0] + kv[c4][1] * qv[1] + kv[c4][2] * qv[2] + kv[c4][3] * qv[3]; }
	s_cselect_b32 s78, 0x9400, 0
	flat_load_dword v144, v[68:69] offset:512
	v_lshl_add_u64 v[68:69], v[66:67], 0, s[78:79]
	s_cselect_b32 s78, 0x9800, 0
	flat_load_dword v180, v[68:69] offset:512
	v_lshl_add_u64 v[68:69], v[66:67], 0, s[78:79]
	s_cselect_b32 s78, 0x9c00, 0
	flat_load_dword v192, v[68:69] offset:512
	v_lshl_add_u64 v[68:69], v[66:67], 0, s[78:79]
	s_cselect_b32 s78, 0xa000, 0
	flat_load_dword v204, v[68:69] offset:512
	v_lshl_add_u64 v[68:69], v[66:67], 0, s[78:79]
	s_cselect_b32 s78, 0xa400, 0
	flat_load_dword v216, v[68:69] offset:512
	v_lshl_add_u64 v[68:69], v[66:67], 0, s[78:79]
	s_cselect_b32 s78, 0xa800, 0
	flat_load_dword v228, v[68:69] offset:512
	v_lshl_add_u64 v[68:69], v[66:67], 0, s[78:79]
	s_cselect_b32 s78, 0xac00, 0
	flat_load_dword v74, v[68:69] offset:512
	v_lshl_add_u64 v[68:69], v[66:67], 0, s[78:79]
	s_cselect_b32 s78, 0xb000, 0
	flat_load_dword v84, v[68:69] offset:512
	v_lshl_add_u64 v[68:69], v[66:67], 0, s[78:79]
	s_cselect_b32 s78, 0xb400, 0
	flat_load_dword v94, v[68:69] offset:512
	v_lshl_add_u64 v[68:69], v[66:67], 0, s[78:79]
	s_cselect_b32 s78, 0xb800, 0
	flat_load_dword v118, v[68:69] offset:512
	v_lshl_add_u64 v[68:69], v[66:67], 0, s[78:79]
	s_cselect_b32 s78, 0xbc00, 0
	flat_load_dword v128, v[68:69] offset:512
	v_lshl_add_u64 v[68:69], v[66:67], 0, s[78:79]
	s_cselect_b32 s78, 0xc000, 0
	flat_load_dword v170, v[68:69] offset:512
	v_lshl_add_u64 v[68:69], v[66:67], 0, s[78:79]
	s_cselect_b32 s78, 0xc400, 0
	flat_load_dword v182, v[68:69] offset:512
	v_lshl_add_u64 v[68:69], v[66:67], 0, s[78:79]
	s_cselect_b32 s78, 0xc800, 0
	flat_load_dword v194, v[68:69] offset:512
	v_lshl_add_u64 v[68:69], v[66:67], 0, s[78:79]
	s_cselect_b32 s78, 0xcc00, 0
	flat_load_dword v206, v[68:69] offset:512
	v_lshl_add_u64 v[68:69], v[66:67], 0, s[78:79]
	s_cselect_b32 s78, 0xd000, 0
	flat_load_dword v218, v[68:69] offset:512
	v_lshl_add_u64 v[68:69], v[66:67], 0, s[78:79]
	s_cselect_b32 s78, 0xd400, 0
	flat_load_dword v230, v[68:69] offset:512
	v_lshl_add_u64 v[68:69], v[66:67], 0, s[78:79]
	s_cselect_b32 s78, 0xd800, 0
	flat_load_dword v76, v[68:69] offset:512
	v_lshl_add_u64 v[68:69], v[66:67], 0, s[78:79]
	s_cselect_b32 s78, 0xdc00, 0
	flat_load_dword v86, v[68:69] offset:512
	v_lshl_add_u64 v[68:69], v[66:67], 0, s[78:79]
	s_cselect_b32 s78, 0xe000, 0
	flat_load_dword v96, v[68:69] offset:512
	v_lshl_add_u64 v[68:69], v[66:67], 0, s[78:79]
	s_cselect_b32 s78, 0xe400, 0
	flat_load_dword v120, v[68:69] offset:512
	v_lshl_add_u64 v[68:69], v[66:67], 0, s[78:79]
	s_cselect_b32 s78, 0xe800, 0
	flat_load_dword v130, v[68:69] offset:512
	v_lshl_add_u64 v[68:69], v[66:67], 0, s[78:79]
	s_cselect_b32 s78, 0xec00, 0
	flat_load_dword v172, v[68:69] offset:512
	v_lshl_add_u64 v[68:69], v[66:67], 0, s[78:79]
	s_cselect_b32 s78, 0xf000, 0
	flat_load_dword v184, v[68:69] offset:512
	v_lshl_add_u64 v[68:69], v[66:67], 0, s[78:79]
	s_cselect_b32 s78, 0xf400, 0
	flat_load_dword v196, v[68:69] offset:512
	v_lshl_add_u64 v[68:69], v[66:67], 0, s[78:79]
	s_cselect_b32 s78, 0xf800, 0
	flat_load_dword v208, v[68:69] offset:512
	v_lshl_add_u64 v[68:69], v[66:67], 0, s[78:79]
	s_cselect_b32 s78, 0xfc00, 0
	v_lshl_add_u64 v[66:67], v[66:67], 0, s[78:79]
	flat_load_dword v220, v[68:69] offset:512
	flat_load_dword v232, v[66:67] offset:512
	ds_read_b128 v[234:237], v1 offset:55296
	ds_read_b128 v[238:241], v1 offset:55312
	ds_read_b128 v[242:245], v1 offset:55328
	ds_read_b128 v[66:69], v1 offset:55344
	s_and_b64 vcc, s[0:1], vcc
	s_waitcnt vmcnt(0) lgkmcnt(0)
	ds_read_b128 v[146:149], v1 offset:55552
	ds_read_b128 v[150:153], v1 offset:55808
	ds_read_b128 v[154:157], v1 offset:56064
	ds_read_b128 v[158:161], v1 offset:55568
	ds_read_b128 v[162:165], v1 offset:55824
	s_waitcnt lgkmcnt(4)
	ds_read_b128 v[166:169], v1 offset:56080
	v_mul_f32_e32 v85, v63, v235
	v_fmac_f32_e32 v85, v62, v234
	v_fmac_f32_e32 v85, v64, v236
	v_fmac_f32_e32 v85, v65, v237
	v_add_f32_e32 v85, 0, v85
	v_mov_b32_e32 v75, v119
	s_add_i32 s3, s3, 64
	s_add_i32 s2, s2, 32
	v_mul_f32_e32 v87, v63, v147
	v_fmac_f32_e32 v87, v62, v146
	v_fmac_f32_e32 v87, v64, v148
	v_fmac_f32_e32 v87, v65, v149
	s_waitcnt lgkmcnt(4)
	ds_read_b128 v[146:149], v1 offset:55584
	v_add_f32_e32 v87, 0, v87
	v_mul_f32_e32 v89, v63, v151
	v_fmac_f32_e32 v89, v62, v150
	v_fmac_f32_e32 v89, v64, v152
	v_fmac_f32_e32 v89, v65, v153
	s_waitcnt lgkmcnt(4)
	ds_read_b128 v[150:153], v1 offset:55840
	v_add_f32_e32 v89, 0, v89
	v_mul_f32_e32 v63, v63, v155
	v_fmac_f32_e32 v63, v62, v154
	v_mul_f32_e32 v62, v59, v239
	v_fmac_f32_e32 v62, v58, v238
	v_fmac_f32_e32 v63, v64, v156
	v_fmac_f32_e32 v62, v60, v240
	v_fmac_f32_e32 v63, v65, v157
	v_fmac_f32_e32 v62, v61, v241
	v_add_f32_e32 v91, 0, v63
	v_add_f32_e32 v85, v85, v62
	s_waitcnt lgkmcnt(4)
	v_mul_f32_e32 v63, v59, v159
	v_fmac_f32_e32 v63, v58, v158
	v_fmac_f32_e32 v63, v60, v160
	v_fmac_f32_e32 v63, v61, v161
	ds_read_b128 v[158:161], v1 offset:56096
	v_add_f32_e32 v87, v87, v63
	s_waitcnt lgkmcnt(4)
	v_mul_f32_e32 v63, v59, v163
	v_fmac_f32_e32 v63, v58, v162
	v_fmac_f32_e32 v63, v60, v164
	v_fmac_f32_e32 v63, v61, v165
	ds_read_b128 v[162:165], v1 offset:55600
	v_add_f32_e32 v89, v89, v63
	s_waitcnt lgkmcnt(4)
	v_mul_f32_e32 v59, v59, v167
	v_fmac_f32_e32 v59, v58, v166
	v_mul_f32_e32 v58, v55, v243
	v_fmac_f32_e32 v58, v54, v242
	v_fmac_f32_e32 v59, v60, v168
	v_fmac_f32_e32 v58, v56, v244
	v_fmac_f32_e32 v59, v61, v169
	ds_read_b128 v[166:169], v1 offset:55856
	v_fmac_f32_e32 v58, v57, v245
	v_add_f32_e32 v62, v91, v59
	v_add_f32_e32 v63, v85, v58
	s_waitcnt lgkmcnt(4)
; #define LAS __attribute__((address_space(3)))
; __device__ __forceinline__ void seg_attend(SegAcc& A, const float* base, int kvh, int nk, bool valid, const LAS float* qs, LAS float* pt, int lane) {
;     ...
;     float s[4] = {0.f, 0.f, 0.f, 0.f};
; #pragma unroll
;     for (int c4 = 0; c4 < 16; ++c4)
; #pragma unroll
;         for (int gq = 0; gq < 4; ++gq) { const f32x4 qv = *(const LAS f32x4*)(qs + gq * 64 + 4 * c4); s[gq] += kv[c4][0] * qv[0] + kv[c4][1] * qv[1] + kv[c4][2] * qv[2] + kv[c4][3] * qv[3]; }
	v_mul_f32_e32 v59, v55, v147
	v_fmac_f32_e32 v59, v54, v146
	v_fmac_f32_e32 v59, v56, v148
	v_fmac_f32_e32 v59, v57, v149
	ds_read_b128 v[146:149], v1 offset:56112
	v_add_f32_e32 v64, v87, v59
	s_waitcnt lgkmcnt(4)
	v_mul_f32_e32 v59, v55, v151
	v_fmac_f32_e32 v59, v54, v150
	v_fmac_f32_e32 v59, v56, v152
	v_fmac_f32_e32 v59, v57, v153
	ds_read_b128 v[150:153], v1 offset:55360
	v_add_f32_e32 v65, v89, v59
	s_waitcnt lgkmcnt(4)
	v_mul_f32_e32 v55, v55, v159
	v_fmac_f32_e32 v55, v54, v158
	v_mul_f32_e32 v54, v51, v67
	v_fmac_f32_e32 v54, v50, v66
	v_fmac_f32_e32 v55, v56, v160
	v_fmac_f32_e32 v54, v52, v68
	v_fmac_f32_e32 v55, v57, v161
	ds_read_b128 v[158:161], v1 offset:55616
	v_fmac_f32_e32 v54, v53, v69
	v_add_f32_e32 v58, v62, v55
	v_add_f32_e32 v59, v63, v54
	s_waitcnt lgkmcnt(4)
	v_mul_f32_e32 v55, v51, v163
	v_fmac_f32_e32 v55, v50, v162
	v_fmac_f32_e32 v55, v52, v164
	v_fmac_f32_e32 v55, v53, v165
	ds_read_b128 v[162:165], v1 offset:55872
	v_add_f32_e32 v60, v64, v55
	s_waitcnt lgkmcnt(4)
	v_mul_f32_e32 v55, v51, v167
	v_fmac_f32_e32 v55, v50, v166
	v_fmac_f32_e32 v55, v52, v168
	v_fmac_f32_e32 v55, v53, v169
	ds_read_b128 v[166:169], v1 offset:56128
	v_add_f32_e32 v61, v65, v55
	s_waitcnt lgkmcnt(4)
	v_mul_f32_e32 v51, v51, v147
	v_fmac_f32_e32 v51, v50, v146
	v_fmac_f32_e32 v51, v52, v148
	v_fmac_f32_e32 v51, v53, v149
	ds_read_b128 v[146:149], v1 offset:55376
	v_add_f32_e32 v54, v58, v51
	s_waitcnt lgkmcnt(4)
	v_mul_f32_e32 v51, v47, v151
	v_fmac_f32_e32 v51, v46, v150
	v_fmac_f32_e32 v51, v48, v152
	v_fmac_f32_e32 v51, v49, v153
	ds_read_b128 v[150:153], v1 offset:55632
	v_add_f32_e32 v55, v59, v51
	s_waitcnt lgkmcnt(4)
	v_mul_f32_e32 v51, v47, v159
	v_fmac_f32_e32 v51, v46, v158
	v_fmac_f32_e32 v51, v48, v160
	v_fmac_f32_e32 v51, v49, v161
	ds_read_b128 v[158:161], v1 offset:55888
	v_add_f32_e32 v56, v60, v51
	s_waitcnt lgkmcnt(4)
	v_mul_f32_e32 v51, v47, v163
	v_fmac_f32_e32 v51, v46, v162
	v_fmac_f32_e32 v51, v48, v164
	v_fmac_f32_e32 v51, v49, v165
	ds_read_b128 v[162:165], v1 offset:56144
	v_add_f32_e32 v57, v61, v51
	s_waitcnt lgkmcnt(4)
	v_mul_f32_e32 v47, v47, v167
	v_fmac_f32_e32 v47, v46, v166
	v_fmac_f32_e32 v47, v48, v168
	v_fmac_f32_e32 v47, v49, v169
	ds_read_b128 v[166:169], v1 offset:55392
	v_add_f32_e32 v50, v54, v47
	v_mov_b32_e32 v54, v30
	s_waitcnt lgkmcnt(4)
	v_mul_f32_e32 v47, v43, v147
	v_fmac_f32_e32 v47, v42, v146
	v_fmac_f32_e32 v47, v44, v148
	v_fmac_f32_e32 v47, v45, v149
	ds_read_b128 v[146:149], v1 offset:55648
	v_add_f32_e32 v51, v55, v47
	v_mov_b32_e32 v55, v26
	v_mov_b32_e32 v26, v31
	s_waitcnt lgkmcnt(4)
	v_mul_f32_e32 v47, v43, v151
	v_fmac_f32_e32 v47, v42, v150
	v_fmac_f32_e32 v47, v44, v152
	v_fmac_f32_e32 v47, v45, v153
	ds_read_b128 v[150:153], v1 offset:55904
	v_add_f32_e32 v52, v56, v47
	s_waitcnt lgkmcnt(4)
	v_mul_f32_e32 v47, v43, v159
	v_fmac_f32_e32 v47, v42, v158
	v_fmac_f32_e32 v47, v44, v160
	v_fmac_f32_e32 v47, v45, v161
	ds_read_b128 v[158:161], v1 offset:56160
	v_add_f32_e32 v53, v57, v47
	s_waitcnt lgkmcnt(4)
	v_mul_f32_e32 v43, v43, v163
	v_fmac_f32_e32 v43, v42, v162
	v_fmac_f32_e32 v43, v44, v164
	v_fmac_f32_e32 v43, v45, v165
	ds_read_b128 v[162:165], v1 offset:55408
	v_add_f32_e32 v46, v50, v43
	s_waitcnt lgkmcnt(4)
	v_mul_f32_e32 v43, v39, v167
	v_fmac_f32_e32 v43, v38, v166
	v_fmac_f32_e32 v43, v40, v168
	v_fmac_f32_e32 v43, v41, v169
	ds_read_b128 v[166:169], v1 offset:55664
	v_add_f32_e32 v47, v51, v43
	s_waitcnt lgkmcnt(4)
	v_mul_f32_e32 v43, v39, v147
	v_fmac_f32_e32 v43, v38, v146
	v_fmac_f32_e32 v43, v40, v148
	v_fmac_f32_e32 v43, v41, v149
	ds_read_b128 v[146:149], v1 offset:55920
	v_add_f32_e32 v48, v52, v43
	s_waitcnt lgkmcnt(4)
	v_mul_f32_e32 v43, v39, v151
	v_fmac_f32_e32 v43, v38, v150
	v_fmac_f32_e32 v43, v40, v152
	v_fmac_f32_e32 v43, v41, v153
	ds_read_b128 v[150:153], v1 offset:56176
	v_add_f32_e32 v49, v53, v43
	s_waitcnt lgkmcnt(4)
	v_mul_f32_e32 v39, v39, v159
	v_fmac_f32_e32 v39, v38, v158
	v_fmac_f32_e32 v39, v40, v160
	v_fmac_f32_e32 v39, v41, v161
	ds_read_b128 v[158:161], v1 offset:55424
	v_add_f32_e32 v42, v46, v39
	s_waitcnt lgkmcnt(4)
	v_mul_f32_e32 v39, v35, v163
	v_fmac_f32_e32 v39, v34, v162
	v_fmac_f32_e32 v39, v36, v164
	v_fmac_f32_e32 v39, v37, v165
	ds_read_b128 v[162:165], v1 offset:55680
	v_add_f32_e32 v58, v47, v39
	s_waitcnt lgkmcnt(4)
	v_mul_f32_e32 v39, v35, v167
	v_fmac_f32_e32 v39, v34, v166
	v_fmac_f32_e32 v39, v36, v168
	v_fmac_f32_e32 v39, v37, v169
	ds_read_b128 v[166:169], v1 offset:55936
	v_add_f32_e32 v59, v48, v39
	s_waitcnt lgkmcnt(4)
	v_mul_f32_e32 v39, v35, v147
	v_fmac_f32_e32 v39, v34, v146
	v_fmac_f32_e32 v39, v36, v148
	v_fmac_f32_e32 v39, v37, v149
	ds_read_b128 v[146:149], v1 offset:56192
	v_add_f32_e32 v60, v49, v39
	s_waitcnt lgkmcnt(4)
	v_mul_f32_e32 v35, v35, v151
	v_fmac_f32_e32 v35, v34, v150
	v_fmac_f32_e32 v35, v36, v152
	v_fmac_f32_e32 v35, v37, v153
	ds_read_b128 v[150:153], v1 offset:55440
	v_add_f32_e32 v61, v42, v35
	s_waitcnt lgkmcnt(4)
	v_mov_b32_e32 v56, v158
	v_mov_b32_e32 v38, v32
	s_waitcnt lgkmcnt(0)
	v_mov_b32_e32 v57, v150
	v_mov_b32_e32 v50, v159
	v_mov_b32_e32 v51, v151
	v_pk_mul_f32 v[30:31], v[26:27], v[50:51]
	v_mov_b32_e32 v39, v28
	v_pk_fma_f32 v[30:31], v[54:55], v[56:57], v[30:31]
	v_mov_b32_e32 v50, v160
	v_mov_b32_e32 v51, v152
	v_pk_fma_f32 v[30:31], v[38:39], v[50:51], v[30:31]
	v_mov_b32_e32 v28, v33
	v_mov_b32_e32 v52, v161
	ds_read_b128 v[158:161], v1 offset:55696
	v_mov_b32_e32 v53, v153
	ds_read_b128 v[150:153], v1 offset:55952
	v_pk_fma_f32 v[30:31], v[28:29], v[52:53], v[30:31]
	v_mov_b32_e32 v40, v162
	v_add_f32_e32 v30, v58, v30
	v_add_f32_e32 v50, v30, v31
	s_waitcnt lgkmcnt(1)
; #define LAS __attribute__((address_space(3)))
; __device__ __forceinline__ void seg_attend(SegAcc& A, const float* base, int kvh, int nk, bool valid, const LAS float* qs, LAS float* pt, int lane) {
;     ...
;     float s[4] = {0.f, 0.f, 0.f, 0.f};
; #pragma unroll
;     for (int c4 = 0; c4 < 16; ++c4)
; #pragma unroll
;         for (int gq = 0; gq < 4; ++gq) { const f32x4 qv = *(const LAS f32x4*)(qs + gq * 64 + 4 * c4); s[gq] += kv[c4][0] * qv[0] + kv[c4][1] * qv[1] + kv[c4][2] * qv[2] + kv[c4][3] * qv[3]; }
	v_mov_b32_e32 v41, v158
	v_mov_b32_e32 v30, v163
	v_mov_b32_e32 v31, v159
	v_pk_mul_f32 v[30:31], v[26:27], v[30:31]
	s_nop 0
	v_pk_fma_f32 v[30:31], v[54:55], v[40:41], v[30:31]
	v_mov_b32_e32 v40, v164
	v_mov_b32_e32 v41, v160
	v_pk_fma_f32 v[30:31], v[38:39], v[40:41], v[30:31]
	v_mov_b32_e32 v32, v165
	ds_read_b128 v[162:165], v1 offset:56208
	v_mov_b32_e32 v33, v161
	ds_read_b128 v[158:161], v1 offset:55456
	v_pk_fma_f32 v[30:31], v[28:29], v[32:33], v[30:31]
	v_mov_b32_e32 v40, v166
	v_add_f32_e32 v30, v59, v30
	v_add_f32_e32 v51, v30, v31
	v_mov_b32_e32 v46, v22
	s_waitcnt lgkmcnt(2)
	v_mov_b32_e32 v41, v150
	v_mov_b32_e32 v30, v167
	v_mov_b32_e32 v31, v151
	v_pk_mul_f32 v[30:31], v[26:27], v[30:31]
	v_mov_b32_e32 v47, v18
	v_pk_fma_f32 v[30:31], v[54:55], v[40:41], v[30:31]
	v_mov_b32_e32 v40, v168
	v_mov_b32_e32 v41, v152
	v_pk_fma_f32 v[30:31], v[38:39], v[40:41], v[30:31]
	v_mov_b32_e32 v32, v169
	ds_read_b128 v[166:169], v1 offset:55712
	v_mov_b32_e32 v33, v153
	ds_read_b128 v[150:153], v1 offset:55968
	v_pk_fma_f32 v[30:31], v[28:29], v[32:33], v[30:31]
	v_mov_b32_e32 v40, v146
	v_add_f32_e32 v30, v60, v30
	v_add_f32_e32 v52, v30, v31
	v_mov_b32_e32 v18, v23
	s_waitcnt lgkmcnt(3)
	v_mov_b32_e32 v41, v162
	v_mov_b32_e32 v30, v147
	v_mov_b32_e32 v31, v163
	v_pk_mul_f32 v[26:27], v[26:27], v[30:31]
	v_mov_b32_e32 v30, v148
	v_pk_fma_f32 v[26:27], v[54:55], v[40:41], v[26:27]
	v_mov_b32_e32 v31, v164
	v_pk_fma_f32 v[26:27], v[38:39], v[30:31], v[26:27]
	v_mov_b32_e32 v32, v149
	ds_read_b128 v[146:149], v1 offset:56224
	v_mov_b32_e32 v33, v165
	ds_read_b128 v[162:165], v1 offset:55472
	v_pk_fma_f32 v[26:27], v[28:29], v[32:33], v[26:27]
	s_nop 0
	v_add_f32_e32 v26, v61, v26
	v_add_f32_e32 v53, v26, v27
	s_waitcnt lgkmcnt(4)
	v_mov_b32_e32 v48, v158
	v_mov_b32_e32 v30, v24
	s_waitcnt lgkmcnt(0)
	v_mov_b32_e32 v49, v162
	v_mov_b32_e32 v42, v159
	v_mov_b32_e32 v43, v163
	v_pk_mul_f32 v[22:23], v[18:19], v[42:43]
	v_mov_b32_e32 v31, v20
	v_pk_fma_f32 v[22:23], v[46:47], v[48:49], v[22:23]
	v_mov_b32_e32 v42, v160
	v_mov_b32_e32 v43, v164
	v_pk_fma_f32 v[22:23], v[30:31], v[42:43], v[22:23]
	v_mov_b32_e32 v20, v25
	v_mov_b32_e32 v44, v161
	ds_read_b128 v[158:161], v1 offset:55728
	v_mov_b32_e32 v45, v165
	ds_read_b128 v[162:165], v1 offset:55984
	v_pk_fma_f32 v[22:23], v[20:21], v[44:45], v[22:23]
	v_mov_b32_e32 v32, v166
	v_add_f32_e32 v22, v50, v22
	v_add_f32_e32 v42, v22, v23
	v_mov_b32_e32 v50, s7
	s_waitcnt lgkmcnt(1)
	v_mov_b32_e32 v33, v158
	v_mov_b32_e32 v22, v167
	v_mov_b32_e32 v23, v159
	v_pk_mul_f32 v[22:23], v[18:19], v[22:23]
	s_nop 0
	v_pk_fma_f32 v[22:23], v[46:47], v[32:33], v[22:23]
	v_mov_b32_e32 v32, v168
	v_mov_b32_e32 v33, v160
	v_pk_fma_f32 v[22:23], v[30:31], v[32:33], v[22:23]
	v_mov_b32_e32 v24, v169
	ds_read_b128 v[166:169], v1 offset:56240
	v_mov_b32_e32 v25, v161
	ds_read_b128 v[158:161], v1 offset:55488
	v_pk_fma_f32 v[22:23], v[20:21], v[24:25], v[22:23]
	v_mov_b32_e32 v32, v150
	v_add_f32_e32 v22, v51, v22
	v_add_f32_e32 v43, v22, v23
	s_waitcnt lgkmcnt(2)
	v_mov_b32_e32 v33, v162
	v_mov_b32_e32 v22, v151
	v_mov_b32_e32 v23, v163
	v_pk_mul_f32 v[22:23], v[18:19], v[22:23]
	s_nop 0
	v_pk_fma_f32 v[22:23], v[46:47], v[32:33], v[22:23]
	v_mov_b32_e32 v32, v152
	v_mov_b32_e32 v33, v164
	v_pk_fma_f32 v[22:23], v[30:31], v[32:33], v[22:23]
	v_mov_b32_e32 v24, v153
	ds_read_b128 v[150:153], v1 offset:55744
	v_mov_b32_e32 v25, v165
	ds_read_b128 v[162:165], v1 offset:56000
	v_pk_fma_f32 v[22:23], v[20:21], v[24:25], v[22:23]
	v_mov_b32_e32 v32, v146
	v_add_f32_e32 v22, v52, v22
	v_add_f32_e32 v44, v22, v23
	v_mov_b32_e32 v26, v14
	s_waitcnt lgkmcnt(3)
	v_mov_b32_e32 v33, v166
	v_mov_b32_e32 v22, v147
	v_mov_b32_e32 v23, v167
	v_pk_mul_f32 v[18:19], v[18:19], v[22:23]
	v_mov_b32_e32 v22, v148
	v_pk_fma_f32 v[18:19], v[46:47], v[32:33], v[18:19]
	v_mov_b32_e32 v23, v168
	v_pk_fma_f32 v[18:19], v[30:31], v[22:23], v[18:19]
	v_mov_b32_e32 v24, v149
	ds_read_b128 v[146:149], v1 offset:56256
	v_mov_b32_e32 v25, v169
	ds_read_b128 v[166:169], v1 offset:55504
	v_pk_fma_f32 v[18:19], v[20:21], v[24:25], v[18:19]
	v_mov_b32_e32 v27, v10
	v_add_f32_e32 v18, v53, v18
	v_add_f32_e32 v45, v18, v19
	v_mov_b32_e32 v10, v15
	s_waitcnt lgkmcnt(4)
	v_mov_b32_e32 v40, v158
	s_waitcnt lgkmcnt(0)
	v_mov_b32_e32 v41, v166
	v_mov_b32_e32 v36, v159
	v_mov_b32_e32 v37, v167
	v_pk_mul_f32 v[14:15], v[10:11], v[36:37]
	v_mov_b32_e32 v36, v160
	v_pk_fma_f32 v[28:29], v[26:27], v[40:41], v[14:15]
	v_mov_b32_e32 v14, v16
	v_mov_b32_e32 v15, v12
	v_mov_b32_e32 v37, v168
	v_pk_fma_f32 v[28:29], v[14:15], v[36:37], v[28:29]
	v_mov_b32_e32 v12, v17
	v_mov_b32_e32 v38, v161
	ds_read_b128 v[158:161], v1 offset:55760
	v_mov_b32_e32 v39, v169
	ds_read_b128 v[166:169], v1 offset:56016
	v_pk_fma_f32 v[16:17], v[12:13], v[38:39], v[28:29]
	v_add_f32_e32 v16, v42, v16
	v_add_f32_e32 v40, v16, v17
	v_mov_b32_e32 v16, v150
	s_waitcnt lgkmcnt(1)
	v_mov_b32_e32 v17, v158
	v_mov_b32_e32 v28, v151
	v_mov_b32_e32 v29, v159
	v_pk_mul_f32 v[28:29], v[10:11], v[28:29]
	s_nop 0
	v_pk_fma_f32 v[16:17], v[26:27], v[16:17], v[28:29]
	v_mov_b32_e32 v28, v152
	v_mov_b32_e32 v29, v160
	v_pk_fma_f32 v[16:17], v[14:15], v[28:29], v[16:17]
	v_mov_b32_e32 v30, v153
	ds_read_b128 v[150:153], v1 offset:56272
	v_mov_b32_e32 v31, v161
	ds_read_b128 v[158:161], v1 offset:55520
	v_pk_fma_f32 v[16:17], v[12:13], v[30:31], v[16:17]
	v_add_f32_e32 v16, v43, v16
	v_add_f32_e32 v28, v16, v17
	v_mov_b32_e32 v16, v162
	s_waitcnt lgkmcnt(2)
; #define LAS __attribute__((address_space(3)))
; __device__ __forceinline__ float ex2(float x) { return __builtin_amdgcn_exp2f(x); }
; template <int CTRL> __device__ __forceinline__ float dpp_mov(float old, float x) { return __int_as_float(__builtin_amdgcn_update_dpp(__float_as_int(old), __float_as_int(x), CTRL, 0xF, 0xF, false)); }
; __device__ __forceinline__ float wave_max(float v) {
;     v = fmaxf(v, dpp_mov<0x111>(v, v)); v = fmaxf(v, dpp_mov<0x112>(v, v)); v = fmaxf(v, dpp_mov<0x114>(v, v)); v = fmaxf(v, dpp_mov<0x118>(v, v));
;     v = fmaxf(v, __int_as_float(__builtin_amdgcn_update_dpp(__float_as_int(v), __float_as_int(v), 0x142, 0xA, 0xF, false)));
;     v = fmaxf(v, __int_as_float(__builtin_amdgcn_update_dpp(__float_as_int(v), __float_as_int(v), 0x143, 0xC, 0xF, false)));
;     return __int_as_float(__builtin_amdgcn_readlane(__float_as_int(v), 63));
; }
; __device__ __forceinline__ void seg_attend(SegAcc& A, const float* base, int kvh, int nk, bool valid, const LAS float* qs, LAS float* pt, int lane) {
;     ...
;     for (int c4 = 0; c4 < 16; ++c4)
; #pragma unroll
;         for (int gq = 0; gq < 4; ++gq) { const f32x4 qv = *(const LAS f32x4*)(qs + gq * 64 + 4 * c4); s[gq] += kv[c4][0] * qv[0] + kv[c4][1] * qv[1] + kv[c4][2] * qv[2] + kv[c4][3] * qv[3]; }
;     valid = valid && lane < nk;
;     f32x4 p;
; #pragma unroll
;     for (int gq = 0; gq < 4; ++gq) { const float sv = valid ? s[gq] : NEGB; const float mx = wave_max(sv); const float mn = fmaxf(A.m[gq], mx), a = ex2(A.m[gq] - mn);
;         p[gq] = valid ? ex2(sv - mn) : 0.f; A.l[gq] = A.l[gq] * a + p[gq]; A.o[gq] *= a; A.m[gq] = mn; }
	v_mov_b32_e32 v17, v166
	v_mov_b32_e32 v30, v163
	v_mov_b32_e32 v31, v167
	v_pk_mul_f32 v[22:23], v[10:11], v[30:31]
	s_nop 0
	v_pk_fma_f32 v[16:17], v[26:27], v[16:17], v[22:23]
	v_mov_b32_e32 v22, v164
	v_mov_b32_e32 v23, v168
	v_pk_fma_f32 v[16:17], v[14:15], v[22:23], v[16:17]
	v_mov_b32_e32 v32, v165
	ds_read_b128 v[162:165], v1 offset:55776
	v_mov_b32_e32 v33, v169
	ds_read_b128 v[166:169], v1 offset:56032
	v_pk_fma_f32 v[16:17], v[12:13], v[32:33], v[16:17]
	v_add_f32_e32 v16, v44, v16
	v_add_f32_e32 v22, v16, v17
	v_mov_b32_e32 v16, v146
	v_mov_b32_e32 v18, v6
	s_waitcnt lgkmcnt(3)
	v_mov_b32_e32 v17, v150
	v_mov_b32_e32 v30, v147
	v_mov_b32_e32 v31, v151
	v_pk_mul_f32 v[10:11], v[10:11], v[30:31]
	v_mov_b32_e32 v19, v2
	v_pk_fma_f32 v[10:11], v[26:27], v[16:17], v[10:11]
	v_mov_b32_e32 v16, v148
	v_mov_b32_e32 v17, v152
	v_pk_fma_f32 v[10:11], v[14:15], v[16:17], v[10:11]
	v_mov_b32_e32 v32, v149
	ds_read_b128 v[146:149], v1 offset:56288
	v_mov_b32_e32 v33, v153
	ds_read_b128 v[150:153], v1 offset:55536
	v_pk_fma_f32 v[10:11], v[12:13], v[32:33], v[10:11]
	v_mov_b32_e32 v2, v7
	v_add_f32_e32 v10, v45, v10
	v_add_f32_e32 v20, v10, v11
	s_waitcnt lgkmcnt(4)
	v_mov_b32_e32 v38, v158
	s_waitcnt lgkmcnt(0)
	v_mov_b32_e32 v39, v150
	v_mov_b32_e32 v34, v159
	v_mov_b32_e32 v35, v151
	v_pk_mul_f32 v[6:7], v[2:3], v[34:35]
	v_mov_b32_e32 v34, v160
	v_pk_fma_f32 v[24:25], v[18:19], v[38:39], v[6:7]
	v_mov_b32_e32 v6, v8
	v_mov_b32_e32 v7, v4
	v_mov_b32_e32 v35, v152
	v_pk_fma_f32 v[24:25], v[6:7], v[34:35], v[24:25]
	v_mov_b32_e32 v4, v9
	v_mov_b32_e32 v36, v161
	ds_read_b128 v[158:161], v1 offset:55792
	v_mov_b32_e32 v37, v153
	v_pk_fma_f32 v[8:9], v[4:5], v[36:37], v[24:25]
	v_mov_b32_e32 v34, v162
	v_mov_b32_e32 v30, v164
	v_add_f32_e32 v8, v40, v8
	v_add_f32_e32 v8, v8, v9
	s_waitcnt lgkmcnt(0)
	v_mov_b32_e32 v35, v158
	v_mov_b32_e32 v24, v163
	v_mov_b32_e32 v25, v159
	v_pk_mul_f32 v[24:25], v[2:3], v[24:25]
	v_mov_b32_e32 v31, v160
	v_pk_fma_f32 v[24:25], v[18:19], v[34:35], v[24:25]
	v_mov_b32_e32 v26, v165
	v_pk_fma_f32 v[24:25], v[6:7], v[30:31], v[24:25]
	s_nop 0
	v_mov_b32_e32 v27, v161
	ds_read_b128 v[158:161], v1 offset:56048
	v_pk_fma_f32 v[24:25], v[4:5], v[26:27], v[24:25]
	s_nop 0
	v_add_f32_e32 v9, v28, v24
	v_add_f32_e32 v9, v9, v25
	v_mov_b32_e32 v28, v166
	s_waitcnt lgkmcnt(0)
	v_mov_b32_e32 v29, v158
	v_mov_b32_e32 v24, v167
	v_mov_b32_e32 v25, v159
	v_pk_mul_f32 v[14:15], v[2:3], v[24:25]
	v_mov_b32_e32 v24, v168
	v_pk_fma_f32 v[14:15], v[18:19], v[28:29], v[14:15]
	v_mov_b32_e32 v25, v160
	v_pk_fma_f32 v[14:15], v[6:7], v[24:25], v[14:15]
	v_mov_b32_e32 v26, v169
	ds_read_b128 v[166:169], v1 offset:56304
	v_mov_b32_e32 v27, v161
	v_pk_fma_f32 v[14:15], v[4:5], v[26:27], v[14:15]
	s_nop 0
	v_add_f32_e32 v14, v22, v14
	v_add_f32_e32 v21, v14, v15
	v_mov_b32_e32 v22, v146
	v_mov_b32_e32 v10, v148
	s_waitcnt lgkmcnt(0)
	v_mov_b32_e32 v23, v166
	v_mov_b32_e32 v14, v147
	v_mov_b32_e32 v15, v167
	v_pk_mul_f32 v[2:3], v[2:3], v[14:15]
	v_mov_b32_e32 v11, v168
	v_pk_fma_f32 v[2:3], v[18:19], v[22:23], v[2:3]
	v_mov_b32_e32 v16, v149
	v_pk_fma_f32 v[2:3], v[6:7], v[10:11], v[2:3]
	s_nop 0
	v_mov_b32_e32 v17, v169
	v_pk_fma_f32 v[2:3], v[4:5], v[16:17], v[2:3]
	s_nop 0
	v_add_f32_e32 v2, v20, v2
	v_add_f32_e32 v5, v2, v3
	v_cndmask_b32_e32 v2, v209, v8, vcc
	v_mov_b32_e32 v3, v2
	v_cndmask_b32_e32 v5, v209, v5, vcc
	s_nop 0
	v_mov_b32_dpp v3, v3 row_shr:1 row_mask:0xf bank_mask:0xf
	v_max_f32_e32 v3, v3, v3
	v_max_f32_e32 v3, v2, v3
	v_mov_b32_e32 v4, v3
	s_nop 1
	v_mov_b32_dpp v4, v4 row_shr:2 row_mask:0xf bank_mask:0xf
	v_max_f32_e32 v4, v4, v4
	v_max_f32_e32 v3, v3, v4
	v_mov_b32_e32 v4, v3
	s_nop 1
	v_mov_b32_dpp v4, v4 row_shr:4 row_mask:0xf bank_mask:0xf
	v_max_f32_e32 v4, v4, v4
	v_max_f32_e32 v3, v3, v4
	v_mov_b32_e32 v4, v3
	s_nop 1
	v_mov_b32_dpp v4, v4 row_shr:8 row_mask:0xf bank_mask:0xf
	v_max_f32_e32 v4, v4, v4
	v_max_f32_e32 v3, v3, v4
	v_mov_b32_e32 v4, v3
	s_nop 1
	v_mov_b32_dpp v4, v4 row_bcast:15 row_mask:0xa bank_mask:0xf
	v_max_f32_e32 v4, v4, v4
	v_max_f32_e32 v3, v3, v4
	v_mov_b32_e32 v4, v3
	s_nop 1
	v_mov_b32_dpp v4, v4 row_bcast:31 row_mask:0xc bank_mask:0xf
	v_max_f32_e32 v4, v4, v4
	v_max_f32_e32 v3, v3, v4
	v_max_f32_e32 v4, v83, v83
	v_readlane_b32 s0, v3, 63
	s_nop 1
	v_max_f32_e64 v3, s0, s0
	v_max_f32_e32 v110, v4, v3
	v_sub_f32_e32 v3, v83, v110
	v_exp_f32_e32 v6, v3
	v_cndmask_b32_e32 v3, v209, v9, vcc
	v_mov_b32_e32 v4, v3
	v_sub_f32_e32 v2, v2, v110
	v_exp_f32_e32 v2, v2
	v_mov_b32_dpp v4, v4 row_shr:1 row_mask:0xf bank_mask:0xf
	v_max_f32_e32 v4, v4, v4
	v_max_f32_e32 v4, v3, v4
	v_mov_b32_e32 v7, v4
	v_cndmask_b32_e32 v2, 0, v2, vcc
	v_fma_f32 v109, v109, v6, v2
	v_mov_b32_dpp v7, v7 row_shr:2 row_mask:0xf bank_mask:0xf
	v_max_f32_e32 v7, v7, v7
	v_max_f32_e32 v4, v4, v7
	v_mov_b32_e32 v7, v4
	s_nop 1
	v_mov_b32_dpp v7, v7 row_shr:4 row_mask:0xf bank_mask:0xf
	v_max_f32_e32 v7, v7, v7
	v_max_f32_e32 v4, v4, v7
	v_mov_b32_e32 v7, v4
	s_nop 1
	v_mov_b32_dpp v7, v7 row_shr:8 row_mask:0xf bank_mask:0xf
	v_max_f32_e32 v7, v7, v7
	v_max_f32_e32 v4, v4, v7
	v_mov_b32_e32 v7, v4
	s_nop 1
	v_mov_b32_dpp v7, v7 row_bcast:15 row_mask:0xa bank_mask:0xf
	v_max_f32_e32 v7, v7, v7
	v_max_f32_e32 v4, v4, v7
	v_mov_b32_e32 v7, v4
	s_nop 1
	v_mov_b32_dpp v7, v7 row_bcast:31 row_mask:0xc bank_mask:0xf
	v_max_f32_e32 v7, v7, v7
	v_max_f32_e32 v4, v4, v7
	v_max_f32_e32 v7, v81, v81
	v_readlane_b32 s0, v4, 63
	s_nop 1
	v_max_f32_e64 v4, s0, s0
	v_max_f32_e32 v108, v7, v4
	v_sub_f32_e32 v4, v81, v108
	v_exp_f32_e32 v7, v4
	v_cndmask_b32_e32 v4, v209, v21, vcc
	v_mov_b32_e32 v8, v4
	v_sub_f32_e32 v3, v3, v108
; #define LAS __attribute__((address_space(3)))
; __device__ __forceinline__ float ex2(float x) { return __builtin_amdgcn_exp2f(x); }
; template <int CTRL> __device__ __forceinline__ float dpp_mov(float old, float x) { return __int_as_float(__builtin_amdgcn_update_dpp(__float_as_int(old), __float_as_int(x), CTRL, 0xF, 0xF, false)); }
; #define LDS_WAIT() asm volatile("s_waitcnt lgkmcnt(0)" ::: "memory")
; __device__ __forceinline__ float wave_max(float v) {
;     v = fmaxf(v, dpp_mov<0x111>(v, v)); v = fmaxf(v, dpp_mov<0x112>(v, v)); v = fmaxf(v, dpp_mov<0x114>(v, v)); v = fmaxf(v, dpp_mov<0x118>(v, v));
;     v = fmaxf(v, __int_as_float(__builtin_amdgcn_update_dpp(__float_as_int(v), __float_as_int(v), 0x142, 0xA, 0xF, false)));
;     v = fmaxf(v, __int_as_float(__builtin_amdgcn_update_dpp(__float_as_int(v), __float_as_int(v), 0x143, 0xC, 0xF, false)));
;     return __int_as_float(__builtin_amdgcn_readlane(__float_as_int(v), 63));
; }
; __device__ __forceinline__ void seg_attend(SegAcc& A, const float* base, int kvh, int nk, bool valid, const LAS float* qs, LAS float* pt, int lane) {
;     ...
;     f32x4 p;
; #pragma unroll
;     for (int gq = 0; gq < 4; ++gq) { const float sv = valid ? s[gq] : NEGB; const float mx = wave_max(sv); const float mn = fmaxf(A.m[gq], mx), a = ex2(A.m[gq] - mn);
;         p[gq] = valid ? ex2(sv - mn) : 0.f; A.l[gq] = A.l[gq] * a + p[gq]; A.o[gq] *= a; A.m[gq] = mn; }
;     *(LAS f32x4*)(pt + 4 * lane) = p;
;     LDS_WAIT();
; #pragma unroll
;     for (int k = 0; k < 64; ++k) { const f32x4 pk = *(const LAS f32x4*)(pt + 4 * k);
; #pragma unroll
;         for (int gq = 0; gq < 4; ++gq) A.o[gq] += pk[gq] * vv[k]; }
	v_exp_f32_e32 v3, v3
	v_mov_b32_dpp v8, v8 row_shr:1 row_mask:0xf bank_mask:0xf
	v_max_f32_e32 v8, v8, v8
	v_max_f32_e32 v8, v4, v8
	v_mov_b32_e32 v9, v8
	v_cndmask_b32_e32 v3, 0, v3, vcc
	v_fma_f32 v107, v107, v7, v3
	v_mov_b32_dpp v9, v9 row_shr:2 row_mask:0xf bank_mask:0xf
	v_max_f32_e32 v9, v9, v9
	v_max_f32_e32 v8, v8, v9
	v_mov_b32_e32 v9, v8
	s_nop 1
	v_mov_b32_dpp v9, v9 row_shr:4 row_mask:0xf bank_mask:0xf
	v_max_f32_e32 v9, v9, v9
	v_max_f32_e32 v8, v8, v9
	v_mov_b32_e32 v9, v8
	s_nop 1
	v_mov_b32_dpp v9, v9 row_shr:8 row_mask:0xf bank_mask:0xf
	v_max_f32_e32 v9, v9, v9
	v_max_f32_e32 v8, v8, v9
	v_mov_b32_e32 v9, v8
	s_nop 1
	v_mov_b32_dpp v9, v9 row_bcast:15 row_mask:0xa bank_mask:0xf
	v_max_f32_e32 v9, v9, v9
	v_max_f32_e32 v8, v8, v9
	v_mov_b32_e32 v9, v8
	s_nop 1
	v_mov_b32_dpp v9, v9 row_bcast:31 row_mask:0xc bank_mask:0xf
	v_max_f32_e32 v9, v9, v9
	v_max_f32_e32 v8, v8, v9
	v_max_f32_e32 v9, v79, v79
	v_readlane_b32 s0, v8, 63
	s_nop 1
	v_max_f32_e64 v8, s0, s0
	v_max_f32_e32 v106, v9, v8
	v_mov_b32_e32 v9, v5
	v_sub_f32_e32 v4, v4, v106
	v_exp_f32_e32 v4, v4
	v_mov_b32_dpp v9, v9 row_shr:1 row_mask:0xf bank_mask:0xf
	v_max_f32_e32 v9, v9, v9
	v_max_f32_e32 v9, v5, v9
	v_mov_b32_e32 v10, v9
	v_sub_f32_e32 v8, v79, v106
	v_exp_f32_e32 v8, v8
	v_mov_b32_dpp v10, v10 row_shr:2 row_mask:0xf bank_mask:0xf
	v_max_f32_e32 v10, v10, v10
	v_max_f32_e32 v9, v9, v10
	v_mov_b32_e32 v10, v9
	v_cndmask_b32_e32 v4, 0, v4, vcc
	v_fma_f32 v105, v105, v8, v4
	v_mov_b32_dpp v10, v10 row_shr:4 row_mask:0xf bank_mask:0xf
	v_max_f32_e32 v10, v10, v10
	v_max_f32_e32 v9, v9, v10
	v_mov_b32_e32 v10, v9
	s_nop 1
	v_mov_b32_dpp v10, v10 row_shr:8 row_mask:0xf bank_mask:0xf
	v_max_f32_e32 v10, v10, v10
	v_max_f32_e32 v9, v9, v10
	v_mov_b32_e32 v10, v9
	s_nop 1
	v_mov_b32_dpp v10, v10 row_bcast:15 row_mask:0xa bank_mask:0xf
	v_max_f32_e32 v10, v10, v10
	v_max_f32_e32 v9, v9, v10
	v_mov_b32_e32 v10, v9
	s_nop 1
	v_mov_b32_dpp v10, v10 row_bcast:31 row_mask:0xc bank_mask:0xf
	v_max_f32_e32 v10, v10, v10
	v_max_f32_e32 v9, v9, v10
	v_max_f32_e32 v10, v77, v77
	v_readlane_b32 s0, v9, 63
	s_nop 1
	v_max_f32_e64 v9, s0, s0
	v_max_f32_e32 v104, v10, v9
	v_sub_f32_e32 v5, v5, v104
	v_exp_f32_e32 v5, v5
	v_add_u32_e32 v10, s7, v71
	v_sub_f32_e32 v9, v77, v104
	v_exp_f32_e32 v9, v9
	v_cndmask_b32_e32 v5, 0, v5, vcc
	ds_write_b128 v10, v[2:5] offset:18432
	s_waitcnt lgkmcnt(0)
	v_mov_b32_e32 v119, v5
	ds_read_b128 v[2:5], v50 offset:18432
	ds_read_b128 v[10:13], v50 offset:18448
	ds_read_b128 v[14:17], v50 offset:18464
	ds_read_b128 v[18:21], v50 offset:18480
	ds_read_b128 v[22:25], v50 offset:18496
	ds_read_b128 v[26:29], v50 offset:18512
	ds_read_b128 v[30:33], v50 offset:18528
	ds_read_b128 v[34:37], v50 offset:18544
	ds_read_b128 v[38:41], v50 offset:18560
	s_waitcnt lgkmcnt(8)
	v_pk_mul_f32 v[2:3], v[138:139], v[2:3] op_sel_hi:[0,1]
	v_pk_fma_f32 v[2:3], v[102:103], v[6:7], v[2:3]
	v_fmac_f32_e32 v119, v75, v9
	s_waitcnt lgkmcnt(7)
	v_pk_fma_f32 v[2:3], v[132:133], v[10:11], v[2:3] op_sel_hi:[0,1,1]
	s_waitcnt lgkmcnt(6)
	v_pk_fma_f32 v[2:3], v[134:135], v[14:15], v[2:3] op_sel_hi:[0,1,1]
	s_waitcnt lgkmcnt(5)
	v_pk_fma_f32 v[2:3], v[136:137], v[18:19], v[2:3] op_sel_hi:[0,1,1]
	s_waitcnt lgkmcnt(4)
	v_pk_fma_f32 v[2:3], v[174:175], v[22:23], v[2:3] op_sel_hi:[0,1,1]
	s_waitcnt lgkmcnt(3)
	v_pk_fma_f32 v[2:3], v[186:187], v[26:27], v[2:3] op_sel_hi:[0,1,1]
	s_waitcnt lgkmcnt(2)
	v_pk_fma_f32 v[2:3], v[198:199], v[30:31], v[2:3] op_sel_hi:[0,1,1]
	s_waitcnt lgkmcnt(1)
	v_pk_fma_f32 v[2:3], v[210:211], v[34:35], v[2:3] op_sel_hi:[0,1,1]
	s_waitcnt lgkmcnt(0)
	v_pk_fma_f32 v[46:47], v[222:223], v[38:39], v[2:3] op_sel_hi:[0,1,1]
	v_pk_mul_f32 v[2:3], v[138:139], v[4:5] op_sel_hi:[0,1]
	v_pk_fma_f32 v[2:3], v[100:101], v[8:9], v[2:3]
	s_nop 0
	v_pk_fma_f32 v[2:3], v[132:133], v[12:13], v[2:3] op_sel_hi:[0,1,1]
	v_pk_fma_f32 v[2:3], v[134:135], v[16:17], v[2:3] op_sel_hi:[0,1,1]
	v_pk_fma_f32 v[2:3], v[136:137], v[20:21], v[2:3] op_sel_hi:[0,1,1]
	v_pk_fma_f32 v[2:3], v[174:175], v[24:25], v[2:3] op_sel_hi:[0,1,1]
	v_pk_fma_f32 v[2:3], v[186:187], v[28:29], v[2:3] op_sel_hi:[0,1,1]
	v_pk_fma_f32 v[2:3], v[198:199], v[32:33], v[2:3] op_sel_hi:[0,1,1]
	v_pk_fma_f32 v[2:3], v[210:211], v[36:37], v[2:3] op_sel_hi:[0,1,1]
	v_pk_fma_f32 v[48:49], v[222:223], v[40:41], v[2:3] op_sel_hi:[0,1,1]
	ds_read_b128 v[2:5], v50 offset:18576
	ds_read_b128 v[6:9], v50 offset:18592
	ds_read_b128 v[10:13], v50 offset:18608
	ds_read_b128 v[14:17], v50 offset:18624
	ds_read_b128 v[18:21], v50 offset:18640
	ds_read_b128 v[22:25], v50 offset:18656
	ds_read_b128 v[26:29], v50 offset:18672
	ds_read_b128 v[30:33], v50 offset:18688
	ds_read_b128 v[34:37], v50 offset:18704
	ds_read_b128 v[38:41], v50 offset:18720
	ds_read_b128 v[42:45], v50 offset:18736
	s_waitcnt lgkmcnt(10)
	v_pk_fma_f32 v[2:3], v[0:1], v[2:3], v[46:47] op_sel_hi:[0,1,1]
	s_waitcnt lgkmcnt(9)
	v_pk_fma_f32 v[2:3], v[78:79], v[6:7], v[2:3] op_sel_hi:[0,1,1]
	s_waitcnt lgkmcnt(8)
	v_pk_fma_f32 v[2:3], v[88:89], v[10:11], v[2:3] op_sel_hi:[0,1,1]
	s_waitcnt lgkmcnt(7)
	v_pk_fma_f32 v[2:3], v[112:113], v[14:15], v[2:3] op_sel_hi:[0,1,1]
	s_waitcnt lgkmcnt(6)
	v_pk_fma_f32 v[2:3], v[122:123], v[18:19], v[2:3] op_sel_hi:[0,1,1]
	s_waitcnt lgkmcnt(5)
	v_pk_fma_f32 v[2:3], v[140:141], v[22:23], v[2:3] op_sel_hi:[0,1,1]
	s_waitcnt lgkmcnt(4)
	v_pk_fma_f32 v[2:3], v[176:177], v[26:27], v[2:3] op_sel_hi:[0,1,1]
	s_waitcnt lgkmcnt(3)
	v_pk_fma_f32 v[2:3], v[188:189], v[30:31], v[2:3] op_sel_hi:[0,1,1]
	s_waitcnt lgkmcnt(2)
	v_pk_fma_f32 v[2:3], v[200:201], v[34:35], v[2:3] op_sel_hi:[0,1,1]
	s_waitcnt lgkmcnt(1)
; #define LAS __attribute__((address_space(3)))
; __device__ __forceinline__ void seg_attend(SegAcc& A, const float* base, int kvh, int nk, bool valid, const LAS float* qs, LAS float* pt, int lane) {
;     ...
; #pragma unroll
;     for (int k = 0; k < 64; ++k) { const f32x4 pk = *(const LAS f32x4*)(pt + 4 * k);
; #pragma unroll
;         for (int gq = 0; gq < 4; ++gq) A.o[gq] += pk[gq] * vv[k]; }
	v_pk_fma_f32 v[2:3], v[212:213], v[38:39], v[2:3] op_sel_hi:[0,1,1]
	s_waitcnt lgkmcnt(0)
	v_pk_fma_f32 v[46:47], v[224:225], v[42:43], v[2:3] op_sel_hi:[0,1,1]
	v_pk_fma_f32 v[2:3], v[0:1], v[4:5], v[48:49] op_sel_hi:[0,1,1]
	v_pk_fma_f32 v[2:3], v[78:79], v[8:9], v[2:3] op_sel_hi:[0,1,1]
	v_pk_fma_f32 v[2:3], v[88:89], v[12:13], v[2:3] op_sel_hi:[0,1,1]
	v_pk_fma_f32 v[2:3], v[112:113], v[16:17], v[2:3] op_sel_hi:[0,1,1]
	v_pk_fma_f32 v[2:3], v[122:123], v[20:21], v[2:3] op_sel_hi:[0,1,1]
	v_pk_fma_f32 v[2:3], v[140:141], v[24:25], v[2:3] op_sel_hi:[0,1,1]
	v_pk_fma_f32 v[2:3], v[176:177], v[28:29], v[2:3] op_sel_hi:[0,1,1]
	v_pk_fma_f32 v[2:3], v[188:189], v[32:33], v[2:3] op_sel_hi:[0,1,1]
	v_pk_fma_f32 v[2:3], v[200:201], v[36:37], v[2:3] op_sel_hi:[0,1,1]
	v_pk_fma_f32 v[2:3], v[212:213], v[40:41], v[2:3] op_sel_hi:[0,1,1]
	v_pk_fma_f32 v[48:49], v[224:225], v[44:45], v[2:3] op_sel_hi:[0,1,1]
	ds_read_b128 v[2:5], v50 offset:18752
	ds_read_b128 v[6:9], v50 offset:18768
	ds_read_b128 v[10:13], v50 offset:18784
	ds_read_b128 v[14:17], v50 offset:18800
	ds_read_b128 v[18:21], v50 offset:18816
	ds_read_b128 v[22:25], v50 offset:18832
	ds_read_b128 v[26:29], v50 offset:18848
	ds_read_b128 v[30:33], v50 offset:18864
	ds_read_b128 v[34:37], v50 offset:18880
	ds_read_b128 v[38:41], v50 offset:18896
	ds_read_b128 v[42:45], v50 offset:18912
	s_waitcnt lgkmcnt(10)
	v_pk_fma_f32 v[2:3], v[70:71], v[2:3], v[46:47] op_sel_hi:[0,1,1]
	s_waitcnt lgkmcnt(9)
	v_pk_fma_f32 v[2:3], v[80:81], v[6:7], v[2:3] op_sel_hi:[0,1,1]
	s_waitcnt lgkmcnt(8)
	v_pk_fma_f32 v[2:3], v[90:91], v[10:11], v[2:3] op_sel_hi:[0,1,1]
	s_waitcnt lgkmcnt(7)
	v_pk_fma_f32 v[2:3], v[114:115], v[14:15], v[2:3] op_sel_hi:[0,1,1]
	s_waitcnt lgkmcnt(6)
	v_pk_fma_f32 v[2:3], v[124:125], v[18:19], v[2:3] op_sel_hi:[0,1,1]
	s_waitcnt lgkmcnt(5)
	v_pk_fma_f32 v[2:3], v[142:143], v[22:23], v[2:3] op_sel_hi:[0,1,1]
	s_waitcnt lgkmcnt(4)
	v_pk_fma_f32 v[2:3], v[178:179], v[26:27], v[2:3] op_sel_hi:[0,1,1]
	s_waitcnt lgkmcnt(3)
	v_pk_fma_f32 v[2:3], v[190:191], v[30:31], v[2:3] op_sel_hi:[0,1,1]
	s_waitcnt lgkmcnt(2)
	v_pk_fma_f32 v[2:3], v[202:203], v[34:35], v[2:3] op_sel_hi:[0,1,1]
	s_waitcnt lgkmcnt(1)
	v_pk_fma_f32 v[2:3], v[214:215], v[38:39], v[2:3] op_sel_hi:[0,1,1]
	s_waitcnt lgkmcnt(0)
	v_pk_fma_f32 v[46:47], v[226:227], v[42:43], v[2:3] op_sel_hi:[0,1,1]
	v_pk_fma_f32 v[2:3], v[70:71], v[4:5], v[48:49] op_sel_hi:[0,1,1]
	v_pk_fma_f32 v[2:3], v[80:81], v[8:9], v[2:3] op_sel_hi:[0,1,1]
	v_pk_fma_f32 v[2:3], v[90:91], v[12:13], v[2:3] op_sel_hi:[0,1,1]
	v_pk_fma_f32 v[2:3], v[114:115], v[16:17], v[2:3] op_sel_hi:[0,1,1]
	v_pk_fma_f32 v[2:3], v[124:125], v[20:21], v[2:3] op_sel_hi:[0,1,1]
	v_pk_fma_f32 v[2:3], v[142:143], v[24:25], v[2:3] op_sel_hi:[0,1,1]
	v_pk_fma_f32 v[2:3], v[178:179], v[28:29], v[2:3] op_sel_hi:[0,1,1]
	v_pk_fma_f32 v[2:3], v[190:191], v[32:33], v[2:3] op_sel_hi:[0,1,1]
	v_pk_fma_f32 v[2:3], v[202:203], v[36:37], v[2:3] op_sel_hi:[0,1,1]
	v_pk_fma_f32 v[2:3], v[214:215], v[40:41], v[2:3] op_sel_hi:[0,1,1]
	v_pk_fma_f32 v[48:49], v[226:227], v[44:45], v[2:3] op_sel_hi:[0,1,1]
	ds_read_b128 v[2:5], v50 offset:18928
	ds_read_b128 v[6:9], v50 offset:18944
	ds_read_b128 v[10:13], v50 offset:18960
	ds_read_b128 v[14:17], v50 offset:18976
	ds_read_b128 v[18:21], v50 offset:18992
	ds_read_b128 v[22:25], v50 offset:19008
	ds_read_b128 v[26:29], v50 offset:19024
	ds_read_b128 v[30:33], v50 offset:19040
	ds_read_b128 v[34:37], v50 offset:19056
	ds_read_b128 v[38:41], v50 offset:19072
	ds_read_b128 v[42:45], v50 offset:19088
	s_waitcnt lgkmcnt(10)
	v_pk_fma_f32 v[2:3], v[72:73], v[2:3], v[46:47] op_sel_hi:[0,1,1]
	s_waitcnt lgkmcnt(9)
	v_pk_fma_f32 v[2:3], v[82:83], v[6:7], v[2:3] op_sel_hi:[0,1,1]
	s_waitcnt lgkmcnt(8)
	v_pk_fma_f32 v[2:3], v[92:93], v[10:11], v[2:3] op_sel_hi:[0,1,1]
	s_waitcnt lgkmcnt(7)
	v_pk_fma_f32 v[2:3], v[116:117], v[14:15], v[2:3] op_sel_hi:[0,1,1]
	s_waitcnt lgkmcnt(6)
	v_pk_fma_f32 v[2:3], v[126:127], v[18:19], v[2:3] op_sel_hi:[0,1,1]
	s_waitcnt lgkmcnt(5)
	v_pk_fma_f32 v[2:3], v[144:145], v[22:23], v[2:3] op_sel_hi:[0,1,1]
	s_waitcnt lgkmcnt(4)
	v_pk_fma_f32 v[2:3], v[180:181], v[26:27], v[2:3] op_sel_hi:[0,1,1]
	s_waitcnt lgkmcnt(3)
	v_pk_fma_f32 v[2:3], v[192:193], v[30:31], v[2:3] op_sel_hi:[0,1,1]
	s_waitcnt lgkmcnt(2)
	v_pk_fma_f32 v[2:3], v[204:205], v[34:35], v[2:3] op_sel_hi:[0,1,1]
	s_waitcnt lgkmcnt(1)
	v_pk_fma_f32 v[2:3], v[216:217], v[38:39], v[2:3] op_sel_hi:[0,1,1]
	s_waitcnt lgkmcnt(0)
	v_pk_fma_f32 v[46:47], v[228:229], v[42:43], v[2:3] op_sel_hi:[0,1,1]
	v_pk_fma_f32 v[2:3], v[72:73], v[4:5], v[48:49] op_sel_hi:[0,1,1]
	v_pk_fma_f32 v[2:3], v[82:83], v[8:9], v[2:3] op_sel_hi:[0,1,1]
	v_pk_fma_f32 v[2:3], v[92:93], v[12:13], v[2:3] op_sel_hi:[0,1,1]
	v_pk_fma_f32 v[2:3], v[116:117], v[16:17], v[2:3] op_sel_hi:[0,1,1]
	v_pk_fma_f32 v[2:3], v[126:127], v[20:21], v[2:3] op_sel_hi:[0,1,1]
	v_pk_fma_f32 v[2:3], v[144:145], v[24:25], v[2:3] op_sel_hi:[0,1,1]
	v_pk_fma_f32 v[2:3], v[180:181], v[28:29], v[2:3] op_sel_hi:[0,1,1]
	v_pk_fma_f32 v[2:3], v[192:193], v[32:33], v[2:3] op_sel_hi:[0,1,1]
	v_pk_fma_f32 v[2:3], v[204:205], v[36:37], v[2:3] op_sel_hi:[0,1,1]
	v_pk_fma_f32 v[2:3], v[216:217], v[40:41], v[2:3] op_sel_hi:[0,1,1]
	v_pk_fma_f32 v[48:49], v[228:229], v[44:45], v[2:3] op_sel_hi:[0,1,1]
	ds_read_b128 v[2:5], v50 offset:19104
	ds_read_b128 v[6:9], v50 offset:19120
	ds_read_b128 v[10:13], v50 offset:19136
	ds_read_b128 v[14:17], v50 offset:19152
	ds_read_b128 v[18:21], v50 offset:19168
	ds_read_b128 v[22:25], v50 offset:19184
	ds_read_b128 v[26:29], v50 offset:19200
	ds_read_b128 v[30:33], v50 offset:19216
	ds_read_b128 v[34:37], v50 offset:19232
	ds_read_b128 v[38:41], v50 offset:19248
	ds_read_b128 v[42:45], v50 offset:19264
	s_waitcnt lgkmcnt(10)
; #define LAS __attribute__((address_space(3)))
; __device__ __forceinline__ void seg_attend(SegAcc& A, const float* base, int kvh, int nk, bool valid, const LAS float* qs, LAS float* pt, int lane) {
;     ...
; #pragma unroll
;     for (int k = 0; k < 64; ++k) { const f32x4 pk = *(const LAS f32x4*)(pt + 4 * k);
; #pragma unroll
;         for (int gq = 0; gq < 4; ++gq) A.o[gq] += pk[gq] * vv[k]; }
; __device__ __forceinline__ void sample_task_part2(const Prm& P, Ctx& C, int b, int kvh, int ts) {
;     ...
;     for (int si = C.wave; si < 16; si += NWAVES) { const bool last = blist[si] >= 256; seg_attend(As, (const float*)(uintptr_t)segb[si], kvh, last ? 4 : 64, last ? lane <= ts : true, qs, ptab, lane); }
;     seg_attend(Aw, (const float*)(uintptr_t)segb[16 + C.wave], kvh, 64, (64 * C.wave + lane) >= 1 + ts, qs, ptab, lane);
	v_pk_fma_f32 v[2:3], v[74:75], v[2:3], v[46:47] op_sel_hi:[0,1,1]
	s_waitcnt lgkmcnt(9)
	v_pk_fma_f32 v[2:3], v[84:85], v[6:7], v[2:3] op_sel_hi:[0,1,1]
	s_waitcnt lgkmcnt(8)
	v_pk_fma_f32 v[2:3], v[94:95], v[10:11], v[2:3] op_sel_hi:[0,1,1]
	s_waitcnt lgkmcnt(7)
	v_pk_fma_f32 v[2:3], v[118:119], v[14:15], v[2:3] op_sel_hi:[0,1,1]
	s_waitcnt lgkmcnt(6)
	v_pk_fma_f32 v[2:3], v[128:129], v[18:19], v[2:3] op_sel_hi:[0,1,1]
	s_waitcnt lgkmcnt(5)
	v_pk_fma_f32 v[2:3], v[170:171], v[22:23], v[2:3] op_sel_hi:[0,1,1]
	s_waitcnt lgkmcnt(4)
	v_pk_fma_f32 v[2:3], v[182:183], v[26:27], v[2:3] op_sel_hi:[0,1,1]
	s_waitcnt lgkmcnt(3)
	v_pk_fma_f32 v[2:3], v[194:195], v[30:31], v[2:3] op_sel_hi:[0,1,1]
	s_waitcnt lgkmcnt(2)
	v_pk_fma_f32 v[2:3], v[206:207], v[34:35], v[2:3] op_sel_hi:[0,1,1]
	s_waitcnt lgkmcnt(1)
	v_pk_fma_f32 v[2:3], v[218:219], v[38:39], v[2:3] op_sel_hi:[0,1,1]
	s_waitcnt lgkmcnt(0)
	v_pk_fma_f32 v[46:47], v[230:231], v[42:43], v[2:3] op_sel_hi:[0,1,1]
	v_pk_fma_f32 v[2:3], v[74:75], v[4:5], v[48:49] op_sel_hi:[0,1,1]
	v_pk_fma_f32 v[2:3], v[84:85], v[8:9], v[2:3] op_sel_hi:[0,1,1]
	v_pk_fma_f32 v[2:3], v[94:95], v[12:13], v[2:3] op_sel_hi:[0,1,1]
	v_pk_fma_f32 v[2:3], v[118:119], v[16:17], v[2:3] op_sel_hi:[0,1,1]
	v_pk_fma_f32 v[2:3], v[128:129], v[20:21], v[2:3] op_sel_hi:[0,1,1]
	v_pk_fma_f32 v[2:3], v[170:171], v[24:25], v[2:3] op_sel_hi:[0,1,1]
	v_pk_fma_f32 v[2:3], v[182:183], v[28:29], v[2:3] op_sel_hi:[0,1,1]
	v_pk_fma_f32 v[2:3], v[194:195], v[32:33], v[2:3] op_sel_hi:[0,1,1]
	v_pk_fma_f32 v[2:3], v[206:207], v[36:37], v[2:3] op_sel_hi:[0,1,1]
	v_pk_fma_f32 v[2:3], v[218:219], v[40:41], v[2:3] op_sel_hi:[0,1,1]
	v_pk_fma_f32 v[48:49], v[230:231], v[44:45], v[2:3] op_sel_hi:[0,1,1]
	ds_read_b128 v[2:5], v50 offset:19280
	ds_read_b128 v[6:9], v50 offset:19296
	ds_read_b128 v[10:13], v50 offset:19312
	ds_read_b128 v[14:17], v50 offset:19328
	ds_read_b128 v[18:21], v50 offset:19344
	ds_read_b128 v[22:25], v50 offset:19360
	ds_read_b128 v[26:29], v50 offset:19376
	ds_read_b128 v[30:33], v50 offset:19392
	ds_read_b128 v[34:37], v50 offset:19408
	ds_read_b128 v[38:41], v50 offset:19424
	ds_read_b128 v[42:45], v50 offset:19440
	s_waitcnt lgkmcnt(10)
	v_pk_fma_f32 v[2:3], v[76:77], v[2:3], v[46:47] op_sel_hi:[0,1,1]
	s_waitcnt lgkmcnt(9)
	v_pk_fma_f32 v[2:3], v[86:87], v[6:7], v[2:3] op_sel_hi:[0,1,1]
	s_waitcnt lgkmcnt(8)
	v_pk_fma_f32 v[2:3], v[96:97], v[10:11], v[2:3] op_sel_hi:[0,1,1]
	s_waitcnt lgkmcnt(7)
	v_pk_fma_f32 v[2:3], v[120:121], v[14:15], v[2:3] op_sel_hi:[0,1,1]
	s_waitcnt lgkmcnt(6)
	v_pk_fma_f32 v[2:3], v[130:131], v[18:19], v[2:3] op_sel_hi:[0,1,1]
	s_waitcnt lgkmcnt(5)
	v_pk_fma_f32 v[2:3], v[172:173], v[22:23], v[2:3] op_sel_hi:[0,1,1]
	s_waitcnt lgkmcnt(4)
	v_pk_fma_f32 v[2:3], v[184:185], v[26:27], v[2:3] op_sel_hi:[0,1,1]
	s_waitcnt lgkmcnt(3)
	v_pk_fma_f32 v[2:3], v[196:197], v[30:31], v[2:3] op_sel_hi:[0,1,1]
	s_waitcnt lgkmcnt(2)
	v_pk_fma_f32 v[2:3], v[208:209], v[34:35], v[2:3] op_sel_hi:[0,1,1]
	s_waitcnt lgkmcnt(1)
	v_pk_fma_f32 v[2:3], v[220:221], v[38:39], v[2:3] op_sel_hi:[0,1,1]
	s_waitcnt lgkmcnt(0)
	v_pk_fma_f32 v[102:103], v[232:233], v[42:43], v[2:3] op_sel_hi:[0,1,1]
	v_pk_fma_f32 v[2:3], v[76:77], v[4:5], v[48:49] op_sel_hi:[0,1,1]
	v_pk_fma_f32 v[2:3], v[86:87], v[8:9], v[2:3] op_sel_hi:[0,1,1]
	v_pk_fma_f32 v[2:3], v[96:97], v[12:13], v[2:3] op_sel_hi:[0,1,1]
	v_pk_fma_f32 v[2:3], v[120:121], v[16:17], v[2:3] op_sel_hi:[0,1,1]
	v_pk_fma_f32 v[2:3], v[130:131], v[20:21], v[2:3] op_sel_hi:[0,1,1]
	v_pk_fma_f32 v[2:3], v[172:173], v[24:25], v[2:3] op_sel_hi:[0,1,1]
	v_pk_fma_f32 v[2:3], v[184:185], v[28:29], v[2:3] op_sel_hi:[0,1,1]
	v_pk_fma_f32 v[2:3], v[196:197], v[32:33], v[2:3] op_sel_hi:[0,1,1]
	v_pk_fma_f32 v[2:3], v[208:209], v[36:37], v[2:3] op_sel_hi:[0,1,1]
	s_waitcnt lgkmcnt(0)
	v_pk_fma_f32 v[2:3], v[220:221], v[40:41], v[2:3] op_sel_hi:[0,1,1]
	v_add_co_u32_e32 v73, vcc, 8, v73
	v_pk_fma_f32 v[100:101], v[232:233], v[44:45], v[2:3] op_sel_hi:[0,1,1]
	s_andn2_b64 vcc, exec, vcc
	s_cbranch_vccz .LBB0_1573
.LBB0_1574:
	v_readlane_b32 s0, v251, 29
	v_cmp_gt_i32_e64 s[46:47], 64, v98
	s_lshl_b32 s78, s33, 2
	v_mov_b32_e32 v0, s0
	ds_read_b64 v[66:67], v0 offset:128
	v_cndmask_b32_e64 v2, 0, v98, s[46:47]
	v_ashrrev_i32_e32 v3, 31, v2
	v_lshlrev_b64 v[2:3], 10, v[2:3]
	s_movk_i32 s0, 0x1000
	s_waitcnt lgkmcnt(0)
; #define LAS __attribute__((address_space(3)))
; __device__ __forceinline__ void seg_attend(SegAcc& A, const float* base, int kvh, int nk, bool valid, const LAS float* qs, LAS float* pt, int lane) {
;     f32x4 kv[16]; float vv[64];
;     const f32x4* kp = (const f32x4*)(base + (size_t)(lane < nk ? lane : 0) * 256 + kvh * 64);
; #pragma unroll
;     for (int c4 = 0; c4 < 16; ++c4) kv[c4] = kp[c4];
;     const float* vb = base + 128 + kvh * 64 + lane;
; #pragma unroll
;     for (int k = 0; k < 64; ++k) vv[k] = vb[(size_t)(k < nk ? k : 0) * 256];
; __device__ __forceinline__ void sample_task_part2(const Prm& P, Ctx& C, int b, int kvh, int ts) {
;     ...
;     seg_attend(Aw, (const float*)(uintptr_t)segb[16 + C.wave], kvh, 64, (64 * C.wave + lane) >= 1 + ts, qs, ptab, lane);
	v_lshl_add_u64 v[2:3], v[66:67], 0, v[2:3]
	v_lshl_add_u64 v[2:3], v[2:3], 0, s[78:79]
	flat_load_dwordx4 v[62:65], v[2:3]
	flat_load_dwordx4 v[58:61], v[2:3] offset:16
	flat_load_dwordx4 v[54:57], v[2:3] offset:32
	flat_load_dwordx4 v[50:53], v[2:3] offset:48
	flat_load_dwordx4 v[46:49], v[2:3] offset:64
	flat_load_dwordx4 v[42:45], v[2:3] offset:80
	flat_load_dwordx4 v[38:41], v[2:3] offset:96
	flat_load_dwordx4 v[34:37], v[2:3] offset:112
	flat_load_dwordx4 v[30:33], v[2:3] offset:128
	flat_load_dwordx4 v[26:29], v[2:3] offset:144
	flat_load_dwordx4 v[22:25], v[2:3] offset:160
	flat_load_dwordx4 v[18:21], v[2:3] offset:176
	flat_load_dwordx4 v[10:13], v[2:3] offset:192
	flat_load_dwordx4 v[6:9], v[2:3] offset:208
	flat_load_dwordx4 v[14:17], v[2:3] offset:224
	s_nop 0
	flat_load_dwordx4 v[2:5], v[2:3] offset:240
	v_lshl_add_u64 v[66:67], v[66:67], 0, s[78:79]
	v_lshl_add_u64 v[66:67], v[98:99], 2, v[66:67]
	v_add_co_u32_e64 v68, s[0:1], s0, v66
	flat_load_dword v216, v[66:67] offset:512
	flat_load_dword v218, v[66:67] offset:1536
	flat_load_dword v220, v[66:67] offset:2560
	flat_load_dword v222, v[66:67] offset:3584
	v_addc_co_u32_e64 v69, s[0:1], 0, v67, s[0:1]
	s_movk_i32 s0, 0x2000
	flat_load_dword v224, v[68:69] offset:512
	flat_load_dword v226, v[68:69] offset:1536
	flat_load_dword v228, v[68:69] offset:2560
	flat_load_dword v230, v[68:69] offset:3584
	v_add_co_u32_e64 v68, s[0:1], s0, v66
	v_cmp_lt_i32_e32 vcc, s25, v117
	s_nop 0
	v_addc_co_u32_e64 v69, s[0:1], 0, v67, s[0:1]
	s_movk_i32 s0, 0x3000
	flat_load_dword v232, v[68:69] offset:512
	flat_load_dword v214, v[68:69] offset:1536
	flat_load_dword v212, v[68:69] offset:2560
	flat_load_dword v208, v[68:69] offset:3584
	v_add_co_u32_e64 v68, s[0:1], s0, v66
	s_and_b64 vcc, s[46:47], vcc
	s_nop 0
	v_addc_co_u32_e64 v69, s[0:1], 0, v67, s[0:1]
	s_movk_i32 s0, 0x4000
	flat_load_dword v210, v[68:69] offset:512
	flat_load_dword v206, v[68:69] offset:1536
	flat_load_dword v204, v[68:69] offset:2560
	flat_load_dword v200, v[68:69] offset:3584
	v_add_co_u32_e64 v68, s[0:1], s0, v66
	v_readlane_b32 s2, v250, 62
	s_nop 0
	v_addc_co_u32_e64 v69, s[0:1], 0, v67, s[0:1]
	s_movk_i32 s0, 0x5000
	flat_load_dword v202, v[68:69] offset:512
	flat_load_dword v198, v[68:69] offset:1536
	flat_load_dword v196, v[68:69] offset:2560
	flat_load_dword v194, v[68:69] offset:3584
	v_add_co_u32_e64 v68, s[0:1], s0, v66
	v_readlane_b32 s3, v250, 63
	s_nop 0
	v_addc_co_u32_e64 v69, s[0:1], 0, v67, s[0:1]
	s_movk_i32 s0, 0x6000
	flat_load_dword v172, v[68:69] offset:512
	flat_load_dword v174, v[68:69] offset:1536
	flat_load_dword v176, v[68:69] offset:2560
	flat_load_dword v178, v[68:69] offset:3584
	v_add_co_u32_e64 v68, s[0:1], s0, v66
	s_nop 1
	v_addc_co_u32_e64 v69, s[0:1], 0, v67, s[0:1]
	s_movk_i32 s0, 0x7000
	flat_load_dword v180, v[68:69] offset:512
	flat_load_dword v182, v[68:69] offset:1536
	flat_load_dword v184, v[68:69] offset:2560
	flat_load_dword v186, v[68:69] offset:3584
	v_add_co_u32_e64 v68, s[0:1], s0, v66
	s_nop 1
	v_addc_co_u32_e64 v69, s[0:1], 0, v67, s[0:1]
	s_mov_b32 s0, 0x8000
	flat_load_dword v188, v[68:69] offset:512
	flat_load_dword v190, v[68:69] offset:1536
	flat_load_dword v192, v[68:69] offset:2560
	flat_load_dword v144, v[68:69] offset:3584
	v_add_co_u32_e64 v68, s[0:1], s0, v66
	s_nop 1
	v_addc_co_u32_e64 v69, s[0:1], 0, v67, s[0:1]
	s_mov_b32 s0, 0x9000
	flat_load_dword v170, v[68:69] offset:512
	flat_load_dword v142, v[68:69] offset:1536
	flat_load_dword v140, v[68:69] offset:2560
	flat_load_dword v136, v[68:69] offset:3584
	v_add_co_u32_e64 v68, s[0:1], s0, v66
	s_nop 1
	v_addc_co_u32_e64 v69, s[0:1], 0, v67, s[0:1]
	s_mov_b32 s0, 0xa000
	flat_load_dword v138, v[68:69] offset:512
	flat_load_dword v134, v[68:69] offset:1536
	flat_load_dword v132, v[68:69] offset:2560
	flat_load_dword v128, v[68:69] offset:3584
	v_add_co_u32_e64 v68, s[0:1], s0, v66
	s_nop 1
	v_addc_co_u32_e64 v69, s[0:1], 0, v67, s[0:1]
	s_mov_b32 s0, 0xb000
	flat_load_dword v130, v[68:69] offset:512
	flat_load_dword v126, v[68:69] offset:1536
	flat_load_dword v90, v[68:69] offset:2560
	flat_load_dword v92, v[68:69] offset:3584
	v_add_co_u32_e64 v68, s[0:1], s0, v66
	s_nop 1
	v_addc_co_u32_e64 v69, s[0:1], 0, v67, s[0:1]
	s_mov_b32 s0, 0xc000
	flat_load_dword v94, v[68:69] offset:512
	flat_load_dword v96, v[68:69] offset:1536
	flat_load_dword v112, v[68:69] offset:2560
	flat_load_dword v114, v[68:69] offset:3584
	v_add_co_u32_e64 v68, s[0:1], s0, v66
	s_nop 1
	v_addc_co_u32_e64 v69, s[0:1], 0, v67, s[0:1]
	s_mov_b32 s0, 0xd000
	flat_load_dword v116, v[68:69] offset:512
	flat_load_dword v118, v[68:69] offset:1536
	flat_load_dword v120, v[68:69] offset:2560
	flat_load_dword v122, v[68:69] offset:3584
	v_add_co_u32_e64 v68, s[0:1], s0, v66
	s_nop 1
	v_addc_co_u32_e64 v69, s[0:1], 0, v67, s[0:1]
	s_mov_b32 s0, 0xe000
	flat_load_dword v124, v[68:69] offset:512
	flat_load_dword v88, v[68:69] offset:1536
	flat_load_dword v86, v[68:69] offset:2560
	flat_load_dword v82, v[68:69] offset:3584
	v_add_co_u32_e64 v68, s[0:1], s0, v66
	s_nop 1
	v_addc_co_u32_e64 v69, s[0:1], 0, v67, s[0:1]
	s_mov_b32 s0, 0xf000
	s_nop 0
	v_add_co_u32_e64 v66, s[0:1], s0, v66
	flat_load_dword v84, v[68:69] offset:512
	flat_load_dword v80, v[68:69] offset:1536
	flat_load_dword v78, v[68:69] offset:2560
	flat_load_dword v74, v[68:69] offset:3584
	v_addc_co_u32_e64 v67, s[0:1], 0, v67, s[0:1]
	flat_load_dword v76, v[66:67] offset:512
	flat_load_dword v72, v[66:67] offset:1536
	flat_load_dword v70, v[66:67] offset:2560
	flat_load_dword v0, v[66:67] offset:3584
	ds_read_b128 v[66:69], v1 offset:55296
	ds_read_b128 v[234:237], v1 offset:55312
	ds_read_b128 v[238:241], v1 offset:55328
	ds_read_b128 v[242:245], v1 offset:55344
	s_waitcnt vmcnt(0) lgkmcnt(0)
; #define LAS __attribute__((address_space(3)))
; __device__ __forceinline__ void seg_attend(SegAcc& A, const float* base, int kvh, int nk, bool valid, const LAS float* qs, LAS float* pt, int lane) {
;     ...
;     float s[4] = {0.f, 0.f, 0.f, 0.f};
; #pragma unroll
;     for (int c4 = 0; c4 < 16; ++c4)
; #pragma unroll
;         for (int gq = 0; gq < 4; ++gq) { const f32x4 qv = *(const LAS f32x4*)(qs + gq * 64 + 4 * c4); s[gq] += kv[c4][0] * qv[0] + kv[c4][1] * qv[1] + kv[c4][2] * qv[2] + kv[c4][3] * qv[3]; }
	ds_read_b128 v[146:149], v1 offset:55552
	ds_read_b128 v[150:153], v1 offset:55808
	ds_read_b128 v[154:157], v1 offset:56064
	ds_read_b128 v[158:161], v1 offset:55568
	ds_read_b128 v[162:165], v1 offset:55824
	s_waitcnt lgkmcnt(4)
	ds_read_b128 v[166:169], v1 offset:56080
	v_mul_f32_e32 v67, v63, v67
	v_fmac_f32_e32 v67, v62, v66
	v_fmac_f32_e32 v67, v64, v68
	v_fmac_f32_e32 v67, v65, v69
	v_add_f32_e32 v73, 0, v67
	v_mul_f32_e32 v67, v63, v147
	v_fmac_f32_e32 v67, v62, v146
	v_fmac_f32_e32 v67, v64, v148
	v_fmac_f32_e32 v67, v65, v149
	s_waitcnt lgkmcnt(4)
	ds_read_b128 v[146:149], v1 offset:55584
	v_add_f32_e32 v75, 0, v67
	v_mul_f32_e32 v67, v63, v151
	v_fmac_f32_e32 v67, v62, v150
	v_fmac_f32_e32 v67, v64, v152
	v_fmac_f32_e32 v67, v65, v153
	s_waitcnt lgkmcnt(4)
	ds_read_b128 v[150:153], v1 offset:55840
	v_add_f32_e32 v77, 0, v67
	v_mul_f32_e32 v63, v63, v155
	v_fmac_f32_e32 v63, v62, v154
	v_mul_f32_e32 v62, v59, v235
	v_fmac_f32_e32 v62, v58, v234
	v_fmac_f32_e32 v63, v64, v156
	v_fmac_f32_e32 v62, v60, v236
	v_fmac_f32_e32 v63, v65, v157
	s_waitcnt lgkmcnt(4)
	ds_read_b128 v[154:157], v1 offset:56096
	v_fmac_f32_e32 v62, v61, v237
	v_add_f32_e32 v66, 0, v63
	v_add_f32_e32 v67, v73, v62
	v_mul_f32_e32 v63, v59, v159
	v_fmac_f32_e32 v63, v58, v158
	v_fmac_f32_e32 v63, v60, v160
	v_fmac_f32_e32 v63, v61, v161
	s_waitcnt lgkmcnt(4)
	ds_read_b128 v[158:161], v1 offset:55600
	v_add_f32_e32 v68, v75, v63
	v_mul_f32_e32 v63, v59, v163
	v_fmac_f32_e32 v63, v58, v162
	v_fmac_f32_e32 v63, v60, v164
	v_fmac_f32_e32 v63, v61, v165
	s_waitcnt lgkmcnt(4)
	ds_read_b128 v[162:165], v1 offset:55856
	v_add_f32_e32 v69, v77, v63
	v_mul_f32_e32 v59, v59, v167
	v_fmac_f32_e32 v59, v58, v166
	v_mul_f32_e32 v58, v55, v239
	v_fmac_f32_e32 v58, v54, v238
	v_fmac_f32_e32 v59, v60, v168
	v_fmac_f32_e32 v58, v56, v240
	v_fmac_f32_e32 v59, v61, v169
	s_waitcnt lgkmcnt(4)
	ds_read_b128 v[166:169], v1 offset:56112
	v_fmac_f32_e32 v58, v57, v241
	v_add_f32_e32 v62, v66, v59
	v_add_f32_e32 v63, v67, v58
	v_mul_f32_e32 v59, v55, v147
	v_fmac_f32_e32 v59, v54, v146
	v_fmac_f32_e32 v59, v56, v148
	v_fmac_f32_e32 v59, v57, v149
	s_waitcnt lgkmcnt(4)
	ds_read_b128 v[146:149], v1 offset:55360
	v_add_f32_e32 v64, v68, v59
	v_mul_f32_e32 v59, v55, v151
	v_fmac_f32_e32 v59, v54, v150
	v_fmac_f32_e32 v59, v56, v152
	v_fmac_f32_e32 v59, v57, v153
	s_waitcnt lgkmcnt(4)
	ds_read_b128 v[150:153], v1 offset:55616
	v_add_f32_e32 v65, v69, v59
	v_mul_f32_e32 v55, v55, v155
	v_fmac_f32_e32 v55, v54, v154
	v_mul_f32_e32 v54, v51, v243
	v_fmac_f32_e32 v54, v50, v242
	v_fmac_f32_e32 v55, v56, v156
	v_fmac_f32_e32 v54, v52, v244
	v_fmac_f32_e32 v55, v57, v157
	s_waitcnt lgkmcnt(4)
	ds_read_b128 v[154:157], v1 offset:55872
	v_fmac_f32_e32 v54, v53, v245
	v_add_f32_e32 v58, v62, v55
	v_add_f32_e32 v59, v63, v54
	v_mul_f32_e32 v55, v51, v159
	v_fmac_f32_e32 v55, v50, v158
	v_fmac_f32_e32 v55, v52, v160
	v_fmac_f32_e32 v55, v53, v161
	s_waitcnt lgkmcnt(4)
	ds_read_b128 v[158:161], v1 offset:56128
	v_add_f32_e32 v60, v64, v55
	v_mul_f32_e32 v55, v51, v163
	v_fmac_f32_e32 v55, v50, v162
	v_fmac_f32_e32 v55, v52, v164
	v_fmac_f32_e32 v55, v53, v165
	s_waitcnt lgkmcnt(4)
	ds_read_b128 v[162:165], v1 offset:55376
	v_add_f32_e32 v61, v65, v55
	v_mul_f32_e32 v51, v51, v167
	v_fmac_f32_e32 v51, v50, v166
	v_fmac_f32_e32 v51, v52, v168
	v_fmac_f32_e32 v51, v53, v169
	s_waitcnt lgkmcnt(4)
	ds_read_b128 v[166:169], v1 offset:55632
	v_add_f32_e32 v54, v58, v51
	v_mul_f32_e32 v51, v47, v147
	v_fmac_f32_e32 v51, v46, v146
	v_fmac_f32_e32 v51, v48, v148
	v_fmac_f32_e32 v51, v49, v149
	s_waitcnt lgkmcnt(4)
	ds_read_b128 v[146:149], v1 offset:55888
	v_add_f32_e32 v55, v59, v51
	v_mul_f32_e32 v51, v47, v151
	v_fmac_f32_e32 v51, v46, v150
	v_fmac_f32_e32 v51, v48, v152
	v_fmac_f32_e32 v51, v49, v153
	s_waitcnt lgkmcnt(4)
	ds_read_b128 v[150:153], v1 offset:56144
	v_add_f32_e32 v56, v60, v51
	v_mul_f32_e32 v51, v47, v155
	v_fmac_f32_e32 v51, v46, v154
	v_fmac_f32_e32 v51, v48, v156
	v_fmac_f32_e32 v51, v49, v157
	s_waitcnt lgkmcnt(4)
	ds_read_b128 v[154:157], v1 offset:55392
	v_add_f32_e32 v57, v61, v51
	v_mul_f32_e32 v47, v47, v159
	v_fmac_f32_e32 v47, v46, v158
	v_fmac_f32_e32 v47, v48, v160
	v_fmac_f32_e32 v47, v49, v161
	s_waitcnt lgkmcnt(4)
	ds_read_b128 v[158:161], v1 offset:55648
	v_add_f32_e32 v50, v54, v47
	v_mov_b32_e32 v54, v30
	v_mul_f32_e32 v47, v43, v163
	v_fmac_f32_e32 v47, v42, v162
	v_fmac_f32_e32 v47, v44, v164
	v_fmac_f32_e32 v47, v45, v165
	s_waitcnt lgkmcnt(4)
	ds_read_b128 v[162:165], v1 offset:55904
	v_add_f32_e32 v51, v55, v47
	v_mov_b32_e32 v55, v26
	v_mov_b32_e32 v26, v31
	v_mul_f32_e32 v47, v43, v167
	v_fmac_f32_e32 v47, v42, v166
	v_fmac_f32_e32 v47, v44, v168
	v_fmac_f32_e32 v47, v45, v169
	s_waitcnt lgkmcnt(4)
	ds_read_b128 v[166:169], v1 offset:56160
	v_add_f32_e32 v52, v56, v47
	v_mul_f32_e32 v47, v43, v147
	v_fmac_f32_e32 v47, v42, v146
	v_fmac_f32_e32 v47, v44, v148
	v_fmac_f32_e32 v47, v45, v149
	s_waitcnt lgkmcnt(4)
	ds_read_b128 v[146:149], v1 offset:55408
	v_add_f32_e32 v53, v57, v47
	v_mul_f32_e32 v43, v43, v151
	v_fmac_f32_e32 v43, v42, v150
	v_fmac_f32_e32 v43, v44, v152
	v_fmac_f32_e32 v43, v45, v153
	s_waitcnt lgkmcnt(4)
	ds_read_b128 v[150:153], v1 offset:55664
	v_add_f32_e32 v46, v50, v43
	v_mul_f32_e32 v43, v39, v155
	v_fmac_f32_e32 v43, v38, v154
	v_fmac_f32_e32 v43, v40, v156
	v_fmac_f32_e32 v43, v41, v157
	s_waitcnt lgkmcnt(4)
	ds_read_b128 v[154:157], v1 offset:55920
	v_add_f32_e32 v47, v51, v43
	v_mul_f32_e32 v43, v39, v159
	v_fmac_f32_e32 v43, v38, v158
	v_fmac_f32_e32 v43, v40, v160
	v_fmac_f32_e32 v43, v41, v161
	s_waitcnt lgkmcnt(4)
; #define LAS __attribute__((address_space(3)))
; __device__ __forceinline__ void seg_attend(SegAcc& A, const float* base, int kvh, int nk, bool valid, const LAS float* qs, LAS float* pt, int lane) {
;     ...
;     float s[4] = {0.f, 0.f, 0.f, 0.f};
; #pragma unroll
;     for (int c4 = 0; c4 < 16; ++c4)
; #pragma unroll
;         for (int gq = 0; gq < 4; ++gq) { const f32x4 qv = *(const LAS f32x4*)(qs + gq * 64 + 4 * c4); s[gq] += kv[c4][0] * qv[0] + kv[c4][1] * qv[1] + kv[c4][2] * qv[2] + kv[c4][3] * qv[3]; }
	ds_read_b128 v[158:161], v1 offset:56176
	v_add_f32_e32 v48, v52, v43
	v_mul_f32_e32 v43, v39, v163
	v_fmac_f32_e32 v43, v38, v162
	v_fmac_f32_e32 v43, v40, v164
	v_fmac_f32_e32 v43, v41, v165
	s_waitcnt lgkmcnt(4)
	ds_read_b128 v[162:165], v1 offset:55424
	v_add_f32_e32 v49, v53, v43
	v_mul_f32_e32 v39, v39, v167
	v_fmac_f32_e32 v39, v38, v166
	v_fmac_f32_e32 v39, v40, v168
	v_fmac_f32_e32 v39, v41, v169
	s_waitcnt lgkmcnt(4)
	ds_read_b128 v[166:169], v1 offset:55680
	v_add_f32_e32 v42, v46, v39
	v_mul_f32_e32 v39, v35, v147
	v_fmac_f32_e32 v39, v34, v146
	v_fmac_f32_e32 v39, v36, v148
	v_fmac_f32_e32 v39, v37, v149
	s_waitcnt lgkmcnt(4)
	ds_read_b128 v[146:149], v1 offset:55936
	v_add_f32_e32 v58, v47, v39
	v_mul_f32_e32 v39, v35, v151
	v_fmac_f32_e32 v39, v34, v150
	v_fmac_f32_e32 v39, v36, v152
	v_fmac_f32_e32 v39, v37, v153
	s_waitcnt lgkmcnt(4)
	ds_read_b128 v[150:153], v1 offset:56192
	v_add_f32_e32 v59, v48, v39
	v_mul_f32_e32 v39, v35, v155
	v_fmac_f32_e32 v39, v34, v154
	v_fmac_f32_e32 v39, v36, v156
	v_fmac_f32_e32 v39, v37, v157
	s_waitcnt lgkmcnt(4)
	ds_read_b128 v[154:157], v1 offset:55440
	v_add_f32_e32 v60, v49, v39
	v_mul_f32_e32 v35, v35, v159
	v_fmac_f32_e32 v35, v34, v158
	v_fmac_f32_e32 v35, v36, v160
	v_fmac_f32_e32 v35, v37, v161
	s_waitcnt lgkmcnt(4)
	ds_read_b128 v[158:161], v1 offset:55696
	v_add_f32_e32 v61, v42, v35
	v_mov_b32_e32 v56, v162
	v_mov_b32_e32 v34, v32
	s_waitcnt lgkmcnt(1)
	v_mov_b32_e32 v57, v154
	v_mov_b32_e32 v50, v163
	v_mov_b32_e32 v51, v155
	v_pk_mul_f32 v[30:31], v[26:27], v[50:51]
	v_mov_b32_e32 v35, v28
	v_pk_fma_f32 v[30:31], v[54:55], v[56:57], v[30:31]
	v_mov_b32_e32 v50, v164
	v_mov_b32_e32 v51, v156
	v_pk_fma_f32 v[30:31], v[34:35], v[50:51], v[30:31]
	v_mov_b32_e32 v28, v33
	v_mov_b32_e32 v52, v165
	ds_read_b128 v[162:165], v1 offset:55952
	v_mov_b32_e32 v53, v157
	ds_read_b128 v[154:157], v1 offset:56208
	v_pk_fma_f32 v[30:31], v[28:29], v[52:53], v[30:31]
	v_mov_b32_e32 v36, v166
	v_add_f32_e32 v30, v58, v30
	v_add_f32_e32 v50, v30, v31
	s_waitcnt lgkmcnt(2)
	v_mov_b32_e32 v37, v158
	v_mov_b32_e32 v30, v167
	v_mov_b32_e32 v31, v159
	v_pk_mul_f32 v[30:31], v[26:27], v[30:31]
	s_nop 0
	v_pk_fma_f32 v[30:31], v[54:55], v[36:37], v[30:31]
	v_mov_b32_e32 v36, v168
	v_mov_b32_e32 v37, v160
	v_pk_fma_f32 v[30:31], v[34:35], v[36:37], v[30:31]
	v_mov_b32_e32 v32, v169
	ds_read_b128 v[166:169], v1 offset:55456
	v_mov_b32_e32 v33, v161
	ds_read_b128 v[158:161], v1 offset:55712
	v_pk_fma_f32 v[30:31], v[28:29], v[32:33], v[30:31]
	v_mov_b32_e32 v36, v146
	v_add_f32_e32 v30, v59, v30
	v_add_f32_e32 v51, v30, v31
	s_waitcnt lgkmcnt(3)
	v_mov_b32_e32 v37, v162
	v_mov_b32_e32 v30, v147
	v_mov_b32_e32 v31, v163
	v_pk_mul_f32 v[30:31], v[26:27], v[30:31]
	s_nop 0
	v_pk_fma_f32 v[30:31], v[54:55], v[36:37], v[30:31]
	v_mov_b32_e32 v36, v148
	v_mov_b32_e32 v37, v164
	v_pk_fma_f32 v[30:31], v[34:35], v[36:37], v[30:31]
	v_mov_b32_e32 v32, v149
	ds_read_b128 v[146:149], v1 offset:55968
	v_mov_b32_e32 v33, v165
	ds_read_b128 v[162:165], v1 offset:56224
	v_pk_fma_f32 v[30:31], v[28:29], v[32:33], v[30:31]
	v_mov_b32_e32 v36, v150
	v_add_f32_e32 v30, v60, v30
	v_add_f32_e32 v52, v30, v31
	v_mov_b32_e32 v46, v22
	s_waitcnt lgkmcnt(4)
	v_mov_b32_e32 v37, v154
	v_mov_b32_e32 v30, v151
	v_mov_b32_e32 v31, v155
	v_pk_mul_f32 v[26:27], v[26:27], v[30:31]
	v_mov_b32_e32 v30, v152
	v_pk_fma_f32 v[26:27], v[54:55], v[36:37], v[26:27]
	v_mov_b32_e32 v31, v156
	v_pk_fma_f32 v[26:27], v[34:35], v[30:31], v[26:27]
	v_mov_b32_e32 v32, v153
	ds_read_b128 v[150:153], v1 offset:55472
	v_mov_b32_e32 v33, v157
	s_waitcnt lgkmcnt(4)
	ds_read_b128 v[154:157], v1 offset:55728
	v_pk_fma_f32 v[26:27], v[28:29], v[32:33], v[26:27]
	v_mov_b32_e32 v47, v18
	v_add_f32_e32 v26, v61, v26
	v_add_f32_e32 v53, v26, v27
	v_mov_b32_e32 v18, v23
	v_mov_b32_e32 v48, v166
	v_mov_b32_e32 v26, v24
	s_waitcnt lgkmcnt(1)
	v_mov_b32_e32 v49, v150
	v_mov_b32_e32 v42, v167
	v_mov_b32_e32 v43, v151
	v_pk_mul_f32 v[22:23], v[18:19], v[42:43]
	v_mov_b32_e32 v27, v20
	v_pk_fma_f32 v[22:23], v[46:47], v[48:49], v[22:23]
	v_mov_b32_e32 v42, v168
	v_mov_b32_e32 v43, v152
	v_pk_fma_f32 v[22:23], v[26:27], v[42:43], v[22:23]
	v_mov_b32_e32 v20, v25
	v_mov_b32_e32 v44, v169
	ds_read_b128 v[166:169], v1 offset:55984
	v_mov_b32_e32 v45, v153
	ds_read_b128 v[150:153], v1 offset:56240
	v_pk_fma_f32 v[22:23], v[20:21], v[44:45], v[22:23]
	v_mov_b32_e32 v28, v158
	v_add_f32_e32 v22, v50, v22
	v_add_f32_e32 v42, v22, v23
	s_waitcnt lgkmcnt(2)
	v_mov_b32_e32 v29, v154
	v_mov_b32_e32 v22, v159
	v_mov_b32_e32 v23, v155
	v_pk_mul_f32 v[22:23], v[18:19], v[22:23]
	s_nop 0
	v_pk_fma_f32 v[22:23], v[46:47], v[28:29], v[22:23]
	v_mov_b32_e32 v28, v160
	v_mov_b32_e32 v29, v156
	v_pk_fma_f32 v[22:23], v[26:27], v[28:29], v[22:23]
	v_mov_b32_e32 v24, v161
	ds_read_b128 v[158:161], v1 offset:55488
	v_mov_b32_e32 v25, v157
	ds_read_b128 v[154:157], v1 offset:55744
	v_pk_fma_f32 v[22:23], v[20:21], v[24:25], v[22:23]
	v_mov_b32_e32 v28, v146
	v_add_f32_e32 v22, v51, v22
	v_add_f32_e32 v43, v22, v23
	s_waitcnt lgkmcnt(3)
	v_mov_b32_e32 v29, v166
	v_mov_b32_e32 v22, v147
	v_mov_b32_e32 v23, v167
	v_pk_mul_f32 v[22:23], v[18:19], v[22:23]
	s_nop 0
	v_pk_fma_f32 v[22:23], v[46:47], v[28:29], v[22:23]
	v_mov_b32_e32 v28, v148
	v_mov_b32_e32 v29, v168
	v_pk_fma_f32 v[22:23], v[26:27], v[28:29], v[22:23]
	v_mov_b32_e32 v24, v149
	ds_read_b128 v[146:149], v1 offset:56000
	v_mov_b32_e32 v25, v169
	ds_read_b128 v[166:169], v1 offset:56256
	v_pk_fma_f32 v[22:23], v[20:21], v[24:25], v[22:23]
	v_mov_b32_e32 v28, v162
	v_add_f32_e32 v22, v52, v22
	v_add_f32_e32 v44, v22, v23
	s_waitcnt lgkmcnt(4)
; #define LAS __attribute__((address_space(3)))
; __device__ __forceinline__ void seg_attend(SegAcc& A, const float* base, int kvh, int nk, bool valid, const LAS float* qs, LAS float* pt, int lane) {
;     ...
;     float s[4] = {0.f, 0.f, 0.f, 0.f};
; #pragma unroll
;     for (int c4 = 0; c4 < 16; ++c4)
; #pragma unroll
;         for (int gq = 0; gq < 4; ++gq) { const f32x4 qv = *(const LAS f32x4*)(qs + gq * 64 + 4 * c4); s[gq] += kv[c4][0] * qv[0] + kv[c4][1] * qv[1] + kv[c4][2] * qv[2] + kv[c4][3] * qv[3]; }
	v_mov_b32_e32 v29, v150
	v_mov_b32_e32 v22, v163
	v_mov_b32_e32 v23, v151
	v_pk_mul_f32 v[18:19], v[18:19], v[22:23]
	v_mov_b32_e32 v22, v164
	v_pk_fma_f32 v[18:19], v[46:47], v[28:29], v[18:19]
	v_mov_b32_e32 v23, v152
	v_pk_fma_f32 v[18:19], v[26:27], v[22:23], v[18:19]
	v_mov_b32_e32 v24, v165
	ds_read_b128 v[162:165], v1 offset:55504
	v_mov_b32_e32 v25, v153
	s_waitcnt lgkmcnt(4)
	ds_read_b128 v[150:153], v1 offset:55760
	v_pk_fma_f32 v[18:19], v[20:21], v[24:25], v[18:19]
	v_mov_b32_e32 v41, v6
	v_add_f32_e32 v18, v53, v18
	v_add_f32_e32 v45, v18, v19
	v_mov_b32_e32 v6, v11
	v_mov_b32_e32 v40, v10
	v_mov_b32_e32 v30, v158
	v_mov_b32_e32 v18, v12
	s_waitcnt lgkmcnt(1)
	v_mov_b32_e32 v31, v162
	v_mov_b32_e32 v36, v159
	v_mov_b32_e32 v37, v163
	v_pk_mul_f32 v[10:11], v[6:7], v[36:37]
	v_mov_b32_e32 v19, v8
	v_pk_fma_f32 v[10:11], v[40:41], v[30:31], v[10:11]
	v_mov_b32_e32 v30, v160
	v_mov_b32_e32 v31, v164
	v_pk_fma_f32 v[10:11], v[18:19], v[30:31], v[10:11]
	v_mov_b32_e32 v8, v13
	v_mov_b32_e32 v38, v161
	ds_read_b128 v[158:161], v1 offset:56016
	v_mov_b32_e32 v39, v165
	v_pk_fma_f32 v[10:11], v[8:9], v[38:39], v[10:11]
	v_mov_b32_e32 v20, v154
	v_add_f32_e32 v10, v42, v10
	v_add_f32_e32 v31, v10, v11
	s_waitcnt lgkmcnt(1)
	v_mov_b32_e32 v21, v150
	v_mov_b32_e32 v10, v155
	v_mov_b32_e32 v11, v151
	v_pk_mul_f32 v[10:11], v[6:7], v[10:11]
	s_nop 0
	v_pk_fma_f32 v[10:11], v[40:41], v[20:21], v[10:11]
	v_mov_b32_e32 v20, v156
	v_mov_b32_e32 v21, v152
	v_pk_fma_f32 v[10:11], v[18:19], v[20:21], v[10:11]
	v_mov_b32_e32 v12, v157
	ds_read_b128 v[154:157], v1 offset:56272
	v_mov_b32_e32 v13, v153
	ds_read_b128 v[150:153], v1 offset:55520
	v_pk_fma_f32 v[10:11], v[8:9], v[12:13], v[10:11]
	v_mov_b32_e32 v20, v146
	v_add_f32_e32 v10, v43, v10
	v_add_f32_e32 v30, v10, v11
	v_mov_b32_e32 v26, v14
	s_waitcnt lgkmcnt(2)
	v_mov_b32_e32 v21, v158
	v_mov_b32_e32 v10, v147
	v_mov_b32_e32 v11, v159
	v_pk_mul_f32 v[10:11], v[6:7], v[10:11]
	v_mov_b32_e32 v27, v2
	v_pk_fma_f32 v[10:11], v[40:41], v[20:21], v[10:11]
	v_mov_b32_e32 v20, v148
	v_mov_b32_e32 v21, v160
	v_pk_fma_f32 v[10:11], v[18:19], v[20:21], v[10:11]
	v_mov_b32_e32 v12, v149
	ds_read_b128 v[146:149], v1 offset:55776
	v_mov_b32_e32 v13, v161
	ds_read_b128 v[158:161], v1 offset:56032
	v_pk_fma_f32 v[10:11], v[8:9], v[12:13], v[10:11]
	v_mov_b32_e32 v20, v166
	v_add_f32_e32 v10, v44, v10
	v_add_f32_e32 v29, v10, v11
	v_mov_b32_e32 v2, v15
	s_waitcnt lgkmcnt(3)
	v_mov_b32_e32 v21, v154
	v_mov_b32_e32 v10, v167
	v_mov_b32_e32 v11, v155
	v_pk_mul_f32 v[6:7], v[6:7], v[10:11]
	v_mov_b32_e32 v10, v168
	v_pk_fma_f32 v[6:7], v[40:41], v[20:21], v[6:7]
	v_mov_b32_e32 v11, v156
	v_pk_fma_f32 v[6:7], v[18:19], v[10:11], v[6:7]
	v_mov_b32_e32 v12, v169
	ds_read_b128 v[166:169], v1 offset:56288
	v_mov_b32_e32 v13, v157
	ds_read_b128 v[154:157], v1 offset:55536
	v_pk_fma_f32 v[6:7], v[8:9], v[12:13], v[6:7]
	s_nop 0
	v_add_f32_e32 v6, v45, v6
	v_add_f32_e32 v28, v6, v7
	s_waitcnt lgkmcnt(4)
	v_mov_b32_e32 v36, v150
	v_mov_b32_e32 v22, v16
	s_waitcnt lgkmcnt(0)
	v_mov_b32_e32 v37, v154
	v_mov_b32_e32 v32, v151
	v_mov_b32_e32 v33, v155
	v_pk_mul_f32 v[14:15], v[2:3], v[32:33]
	v_mov_b32_e32 v23, v4
	v_pk_fma_f32 v[14:15], v[26:27], v[36:37], v[14:15]
	v_mov_b32_e32 v32, v152
	v_mov_b32_e32 v33, v156
	v_pk_fma_f32 v[14:15], v[22:23], v[32:33], v[14:15]
	v_mov_b32_e32 v4, v17
	v_mov_b32_e32 v34, v153
	v_mov_b32_e32 v35, v157
	v_pk_fma_f32 v[14:15], v[4:5], v[34:35], v[14:15]
	v_mov_b32_e32 v32, v146
	v_add_f32_e32 v14, v31, v14
	v_add_f32_e32 v24, v14, v15
	ds_read_b128 v[14:17], v1 offset:55792
	v_mov_b32_e32 v18, v148
	v_mov_b32_e32 v20, v158
	s_waitcnt lgkmcnt(0)
	v_mov_b32_e32 v33, v14
	v_mov_b32_e32 v14, v147
	v_pk_mul_f32 v[14:15], v[2:3], v[14:15]
	v_mov_b32_e32 v19, v16
	v_pk_fma_f32 v[14:15], v[26:27], v[32:33], v[14:15]
	v_mov_b32_e32 v16, v149
	ds_read_b128 v[146:149], v1 offset:56048
	v_pk_fma_f32 v[14:15], v[22:23], v[18:19], v[14:15]
	s_nop 0
	v_pk_fma_f32 v[14:15], v[4:5], v[16:17], v[14:15]
	s_nop 0
	v_add_f32_e32 v14, v30, v14
	v_add_f32_e32 v18, v14, v15
	s_waitcnt lgkmcnt(0)
	v_mov_b32_e32 v21, v146
	v_mov_b32_e32 v14, v159
	v_mov_b32_e32 v15, v147
	v_pk_mul_f32 v[10:11], v[2:3], v[14:15]
	v_mov_b32_e32 v14, v160
	v_pk_fma_f32 v[10:11], v[26:27], v[20:21], v[10:11]
	v_mov_b32_e32 v15, v148
	v_pk_fma_f32 v[10:11], v[22:23], v[14:15], v[10:11]
	v_mov_b32_e32 v16, v161
	ds_read_b128 v[158:161], v1 offset:56304
	v_mov_b32_e32 v17, v149
	v_pk_fma_f32 v[10:11], v[4:5], v[16:17], v[10:11]
	v_mov_b32_e32 v14, v166
	v_add_f32_e32 v10, v29, v10
	v_add_f32_e32 v16, v10, v11
	v_mov_b32_e32 v6, v168
	s_waitcnt lgkmcnt(0)
; #define LAS __attribute__((address_space(3)))
; __device__ __forceinline__ float ex2(float x) { return __builtin_amdgcn_exp2f(x); }
; template <int CTRL> __device__ __forceinline__ float dpp_mov(float old, float x) { return __int_as_float(__builtin_amdgcn_update_dpp(__float_as_int(old), __float_as_int(x), CTRL, 0xF, 0xF, false)); }
; #define LDS_WAIT() asm volatile("s_waitcnt lgkmcnt(0)" ::: "memory")
; __device__ __forceinline__ float wave_max(float v) {
;     v = fmaxf(v, dpp_mov<0x111>(v, v)); v = fmaxf(v, dpp_mov<0x112>(v, v)); v = fmaxf(v, dpp_mov<0x114>(v, v)); v = fmaxf(v, dpp_mov<0x118>(v, v));
;     v = fmaxf(v, __int_as_float(__builtin_amdgcn_update_dpp(__float_as_int(v), __float_as_int(v), 0x142, 0xA, 0xF, false)));
;     v = fmaxf(v, __int_as_float(__builtin_amdgcn_update_dpp(__float_as_int(v), __float_as_int(v), 0x143, 0xC, 0xF, false)));
;     return __int_as_float(__builtin_amdgcn_readlane(__float_as_int(v), 63));
; __device__ __forceinline__ void seg_attend(SegAcc& A, const float* base, int kvh, int nk, bool valid, const LAS float* qs, LAS float* pt, int lane) {
;     ...
;     valid = valid && lane < nk;
;     f32x4 p;
; #pragma unroll
;     for (int gq = 0; gq < 4; ++gq) { const float sv = valid ? s[gq] : NEGB; const float mx = wave_max(sv); const float mn = fmaxf(A.m[gq], mx), a = ex2(A.m[gq] - mn);
;         p[gq] = valid ? ex2(sv - mn) : 0.f; A.l[gq] = A.l[gq] * a + p[gq]; A.o[gq] *= a; A.m[gq] = mn; }
;     *(LAS f32x4*)(pt + 4 * lane) = p;
;     LDS_WAIT();
; #pragma unroll
;     for (int k = 0; k < 64; ++k) { const f32x4 pk = *(const LAS f32x4*)(pt + 4 * k);
	v_mov_b32_e32 v15, v158
	v_mov_b32_e32 v10, v167
	v_mov_b32_e32 v11, v159
	v_pk_mul_f32 v[2:3], v[2:3], v[10:11]
	v_mov_b32_e32 v7, v160
	v_pk_fma_f32 v[2:3], v[26:27], v[14:15], v[2:3]
	v_mov_b32_e32 v12, v169
	v_pk_fma_f32 v[2:3], v[22:23], v[6:7], v[2:3]
	s_nop 0
	v_mov_b32_e32 v13, v161
	v_pk_fma_f32 v[2:3], v[4:5], v[12:13], v[2:3]
	s_nop 0
	v_add_f32_e32 v2, v28, v2
	v_add_f32_e32 v2, v2, v3
	v_cndmask_b32_e32 v3, v209, v24, vcc
	v_mov_b32_e32 v4, v3
	v_cndmask_b32_e32 v2, v209, v2, vcc
	s_nop 0
	v_mov_b32_dpp v4, v4 row_shr:1 row_mask:0xf bank_mask:0xf
	v_max_f32_e32 v4, v4, v4
	v_max_f32_e32 v4, v3, v4
	v_mov_b32_e32 v5, v4
	s_nop 1
	v_mov_b32_dpp v5, v5 row_shr:2 row_mask:0xf bank_mask:0xf
	v_max_f32_e32 v5, v5, v5
	v_max_f32_e32 v4, v4, v5
	v_mov_b32_e32 v5, v4
	s_nop 1
	v_mov_b32_dpp v5, v5 row_shr:4 row_mask:0xf bank_mask:0xf
	v_max_f32_e32 v5, v5, v5
	v_max_f32_e32 v4, v4, v5
	v_mov_b32_e32 v5, v4
	s_nop 1
	v_mov_b32_dpp v5, v5 row_shr:8 row_mask:0xf bank_mask:0xf
	v_max_f32_e32 v5, v5, v5
	v_max_f32_e32 v4, v4, v5
	v_mov_b32_e32 v5, v4
	s_nop 1
	v_mov_b32_dpp v5, v5 row_bcast:15 row_mask:0xa bank_mask:0xf
	v_max_f32_e32 v5, v5, v5
	v_max_f32_e32 v4, v4, v5
	v_mov_b32_e32 v5, v4
	s_nop 1
	v_mov_b32_dpp v5, v5 row_bcast:31 row_mask:0xc bank_mask:0xf
	v_max_f32_e32 v5, v5, v5
	v_max_f32_e32 v4, v4, v5
	s_nop 0
	v_readlane_b32 s0, v4, 63
	s_nop 1
	v_max_f32_e64 v4, s0, s0
	v_max_f32_e32 v240, 0xf149f2ca, v4
	v_sub_f32_e32 v3, v3, v240
	v_exp_f32_e32 v3, v3
	v_sub_f32_e32 v4, 0xf149f2ca, v240
	v_exp_f32_e32 v44, v4
	v_cndmask_b32_e32 v4, 0, v3, vcc
	v_cndmask_b32_e32 v3, v209, v18, vcc
	v_mov_b32_e32 v5, v3
	s_nop 1
	v_mov_b32_dpp v5, v5 row_shr:1 row_mask:0xf bank_mask:0xf
	v_max_f32_e32 v5, v5, v5
	v_max_f32_e32 v5, v3, v5
	v_mov_b32_e32 v6, v5
	s_nop 1
	v_mov_b32_dpp v6, v6 row_shr:2 row_mask:0xf bank_mask:0xf
	v_max_f32_e32 v6, v6, v6
	v_max_f32_e32 v5, v5, v6
	v_mov_b32_e32 v6, v5
	s_nop 1
	v_mov_b32_dpp v6, v6 row_shr:4 row_mask:0xf bank_mask:0xf
	v_max_f32_e32 v6, v6, v6
	v_max_f32_e32 v5, v5, v6
	v_mov_b32_e32 v6, v5
	s_nop 1
	v_mov_b32_dpp v6, v6 row_shr:8 row_mask:0xf bank_mask:0xf
	v_max_f32_e32 v6, v6, v6
	v_max_f32_e32 v5, v5, v6
	v_mov_b32_e32 v6, v5
	s_nop 1
	v_mov_b32_dpp v6, v6 row_bcast:15 row_mask:0xa bank_mask:0xf
	v_max_f32_e32 v6, v6, v6
	v_max_f32_e32 v5, v5, v6
	v_mov_b32_e32 v6, v5
	s_nop 1
	v_mov_b32_dpp v6, v6 row_bcast:31 row_mask:0xc bank_mask:0xf
	v_max_f32_e32 v6, v6, v6
	v_max_f32_e32 v5, v5, v6
	s_nop 0
	v_readlane_b32 s0, v5, 63
	s_nop 1
	v_max_f32_e64 v5, s0, s0
	v_max_f32_e32 v238, 0xf149f2ca, v5
	v_sub_f32_e32 v3, v3, v238
	v_exp_f32_e32 v3, v3
	v_sub_f32_e32 v5, 0xf149f2ca, v238
	v_exp_f32_e32 v45, v5
	v_cndmask_b32_e32 v5, 0, v3, vcc
	v_cndmask_b32_e32 v3, v209, v16, vcc
	v_mov_b32_e32 v6, v3
	v_pk_mul_f32 v[44:45], v[44:45], 0 op_sel_hi:[1,0]
	s_nop 0
	v_mov_b32_dpp v6, v6 row_shr:1 row_mask:0xf bank_mask:0xf
	v_max_f32_e32 v6, v6, v6
	v_max_f32_e32 v6, v3, v6
	v_mov_b32_e32 v7, v6
	v_add_f32_e32 v111, v44, v4
	v_add_f32_e32 v123, v45, v5
	v_mov_b32_dpp v7, v7 row_shr:2 row_mask:0xf bank_mask:0xf
	v_max_f32_e32 v7, v7, v7
	v_max_f32_e32 v6, v6, v7
	v_mov_b32_e32 v7, v6
	s_nop 1
	v_mov_b32_dpp v7, v7 row_shr:4 row_mask:0xf bank_mask:0xf
	v_max_f32_e32 v7, v7, v7
	v_max_f32_e32 v6, v6, v7
	v_mov_b32_e32 v7, v6
	s_nop 1
	v_mov_b32_dpp v7, v7 row_shr:8 row_mask:0xf bank_mask:0xf
	v_max_f32_e32 v7, v7, v7
	v_max_f32_e32 v6, v6, v7
	v_mov_b32_e32 v7, v6
	s_nop 1
	v_mov_b32_dpp v7, v7 row_bcast:15 row_mask:0xa bank_mask:0xf
	v_max_f32_e32 v7, v7, v7
	v_max_f32_e32 v6, v6, v7
	v_mov_b32_e32 v7, v6
	s_nop 1
	v_mov_b32_dpp v7, v7 row_bcast:31 row_mask:0xc bank_mask:0xf
	v_max_f32_e32 v7, v7, v7
	v_max_f32_e32 v6, v6, v7
	s_nop 0
	v_readlane_b32 s0, v6, 63
	s_nop 1
	v_max_f32_e64 v6, s0, s0
	v_max_f32_e32 v236, 0xf149f2ca, v6
	v_sub_f32_e32 v3, v3, v236
	v_exp_f32_e32 v3, v3
	v_sub_f32_e32 v6, 0xf149f2ca, v236
	v_exp_f32_e32 v46, v6
	v_cndmask_b32_e32 v6, 0, v3, vcc
	v_mov_b32_e32 v3, v2
	s_nop 1
	v_mov_b32_dpp v3, v3 row_shr:1 row_mask:0xf bank_mask:0xf
	v_max_f32_e32 v3, v3, v3
	v_max_f32_e32 v3, v2, v3
	v_mov_b32_e32 v7, v3
	s_nop 1
	v_mov_b32_dpp v7, v7 row_shr:2 row_mask:0xf bank_mask:0xf
	v_max_f32_e32 v7, v7, v7
	v_max_f32_e32 v3, v3, v7
	v_mov_b32_e32 v7, v3
	s_nop 1
	v_mov_b32_dpp v7, v7 row_shr:4 row_mask:0xf bank_mask:0xf
	v_max_f32_e32 v7, v7, v7
	v_max_f32_e32 v3, v3, v7
	v_mov_b32_e32 v7, v3
	s_nop 1
	v_mov_b32_dpp v7, v7 row_shr:8 row_mask:0xf bank_mask:0xf
	v_max_f32_e32 v7, v7, v7
	v_max_f32_e32 v3, v3, v7
	v_mov_b32_e32 v7, v3
	s_nop 1
	v_mov_b32_dpp v7, v7 row_bcast:15 row_mask:0xa bank_mask:0xf
	v_max_f32_e32 v7, v7, v7
	v_max_f32_e32 v3, v3, v7
	v_mov_b32_e32 v7, v3
	s_nop 1
	v_mov_b32_dpp v7, v7 row_bcast:31 row_mask:0xc bank_mask:0xf
	v_max_f32_e32 v7, v7, v7
	v_max_f32_e32 v3, v3, v7
	s_nop 0
	v_readlane_b32 s0, v3, 63
	s_nop 1
	v_max_f32_e64 v3, s0, s0
	v_max_f32_e32 v234, 0xf149f2ca, v3
	v_sub_f32_e32 v2, v2, v234
	v_exp_f32_e32 v2, v2
	v_readlane_b32 s0, v251, 15
	v_sub_f32_e32 v3, 0xf149f2ca, v234
	v_exp_f32_e32 v47, v3
	v_cndmask_b32_e32 v7, 0, v2, vcc
	v_add_u32_e32 v127, s0, v71
	ds_write_b128 v127, v[4:7] offset:18432
	s_waitcnt lgkmcnt(0)
	v_mov_b32_e32 v2, s0
	ds_read_b128 v[8:11], v2 offset:18432
	ds_read_b128 v[12:15], v2 offset:18448
	ds_read_b128 v[16:19], v2 offset:18464
	ds_read_b128 v[20:23], v2 offset:18480
	ds_read_b128 v[24:27], v2 offset:18496
	ds_read_b128 v[28:31], v2 offset:18512
	ds_read_b128 v[32:35], v2 offset:18528
	ds_read_b128 v[36:39], v2 offset:18544
	ds_read_b128 v[40:43], v2 offset:18560
	s_waitcnt lgkmcnt(8)
; #define LAS __attribute__((address_space(3)))
; #define LDS_WAIT() asm volatile("s_waitcnt lgkmcnt(0)" ::: "memory")
; __device__ __forceinline__ void seg_attend(SegAcc& A, const float* base, int kvh, int nk, bool valid, const LAS float* qs, LAS float* pt, int lane) {
;     ...
; #pragma unroll
;     for (int k = 0; k < 64; ++k) { const f32x4 pk = *(const LAS f32x4*)(pt + 4 * k);
; #pragma unroll
;         for (int gq = 0; gq < 4; ++gq) A.o[gq] += pk[gq] * vv[k]; }
;     LDS_WAIT();
	v_pk_fma_f32 v[4:5], v[216:217], v[8:9], v[44:45] op_sel_hi:[0,1,1]
	s_waitcnt lgkmcnt(7)
	v_pk_fma_f32 v[4:5], v[218:219], v[12:13], v[4:5] op_sel_hi:[0,1,1]
	s_waitcnt lgkmcnt(6)
	v_pk_fma_f32 v[4:5], v[220:221], v[16:17], v[4:5] op_sel_hi:[0,1,1]
	s_waitcnt lgkmcnt(5)
	v_pk_fma_f32 v[4:5], v[222:223], v[20:21], v[4:5] op_sel_hi:[0,1,1]
	s_waitcnt lgkmcnt(4)
	v_pk_fma_f32 v[4:5], v[224:225], v[24:25], v[4:5] op_sel_hi:[0,1,1]
	s_waitcnt lgkmcnt(3)
	v_pk_fma_f32 v[4:5], v[226:227], v[28:29], v[4:5] op_sel_hi:[0,1,1]
	s_waitcnt lgkmcnt(2)
	v_pk_fma_f32 v[4:5], v[228:229], v[32:33], v[4:5] op_sel_hi:[0,1,1]
	s_waitcnt lgkmcnt(1)
	v_pk_fma_f32 v[4:5], v[230:231], v[36:37], v[4:5] op_sel_hi:[0,1,1]
	s_waitcnt lgkmcnt(0)
	v_pk_fma_f32 v[48:49], v[232:233], v[40:41], v[4:5] op_sel_hi:[0,1,1]
	v_pk_mul_f32 v[4:5], v[46:47], 0 op_sel_hi:[1,0]
	s_and_b64 vcc, exec, s[2:3]
	v_add_f32_e32 v121, v4, v6
	v_add_f32_e32 v125, v5, v7
	v_pk_fma_f32 v[4:5], v[216:217], v[10:11], v[4:5] op_sel_hi:[0,1,1]
	v_pk_fma_f32 v[4:5], v[218:219], v[14:15], v[4:5] op_sel_hi:[0,1,1]
	v_pk_fma_f32 v[4:5], v[220:221], v[18:19], v[4:5] op_sel_hi:[0,1,1]
	v_pk_fma_f32 v[4:5], v[222:223], v[22:23], v[4:5] op_sel_hi:[0,1,1]
	v_pk_fma_f32 v[4:5], v[224:225], v[26:27], v[4:5] op_sel_hi:[0,1,1]
	v_pk_fma_f32 v[4:5], v[226:227], v[30:31], v[4:5] op_sel_hi:[0,1,1]
	v_pk_fma_f32 v[4:5], v[228:229], v[34:35], v[4:5] op_sel_hi:[0,1,1]
	v_pk_fma_f32 v[4:5], v[230:231], v[38:39], v[4:5] op_sel_hi:[0,1,1]
	v_pk_fma_f32 v[50:51], v[232:233], v[42:43], v[4:5] op_sel_hi:[0,1,1]
	ds_read_b128 v[4:7], v2 offset:18576
	ds_read_b128 v[8:11], v2 offset:18592
	ds_read_b128 v[12:15], v2 offset:18608
	ds_read_b128 v[16:19], v2 offset:18624
	ds_read_b128 v[20:23], v2 offset:18640
	ds_read_b128 v[24:27], v2 offset:18656
	ds_read_b128 v[28:31], v2 offset:18672
	ds_read_b128 v[32:35], v2 offset:18688
	ds_read_b128 v[36:39], v2 offset:18704
	ds_read_b128 v[40:43], v2 offset:18720
	ds_read_b128 v[44:47], v2 offset:18736
	s_waitcnt lgkmcnt(10)
	v_pk_fma_f32 v[4:5], v[214:215], v[4:5], v[48:49] op_sel_hi:[0,1,1]
	s_waitcnt lgkmcnt(9)
	v_pk_fma_f32 v[4:5], v[212:213], v[8:9], v[4:5] op_sel_hi:[0,1,1]
	s_waitcnt lgkmcnt(8)
	v_pk_fma_f32 v[4:5], v[208:209], v[12:13], v[4:5] op_sel_hi:[0,1,1]
	s_waitcnt lgkmcnt(7)
	v_pk_fma_f32 v[4:5], v[210:211], v[16:17], v[4:5] op_sel_hi:[0,1,1]
	s_waitcnt lgkmcnt(6)
	v_pk_fma_f32 v[4:5], v[206:207], v[20:21], v[4:5] op_sel_hi:[0,1,1]
	s_waitcnt lgkmcnt(5)
	v_pk_fma_f32 v[4:5], v[204:205], v[24:25], v[4:5] op_sel_hi:[0,1,1]
	s_waitcnt lgkmcnt(4)
	v_pk_fma_f32 v[4:5], v[200:201], v[28:29], v[4:5] op_sel_hi:[0,1,1]
	s_waitcnt lgkmcnt(3)
	v_pk_fma_f32 v[4:5], v[202:203], v[32:33], v[4:5] op_sel_hi:[0,1,1]
	s_waitcnt lgkmcnt(2)
	v_pk_fma_f32 v[4:5], v[198:199], v[36:37], v[4:5] op_sel_hi:[0,1,1]
	s_waitcnt lgkmcnt(1)
	v_pk_fma_f32 v[4:5], v[196:197], v[40:41], v[4:5] op_sel_hi:[0,1,1]
	s_waitcnt lgkmcnt(0)
	v_pk_fma_f32 v[48:49], v[194:195], v[44:45], v[4:5] op_sel_hi:[0,1,1]
	v_pk_fma_f32 v[4:5], v[214:215], v[6:7], v[50:51] op_sel_hi:[0,1,1]
	v_pk_fma_f32 v[4:5], v[212:213], v[10:11], v[4:5] op_sel_hi:[0,1,1]
	v_pk_fma_f32 v[4:5], v[208:209], v[14:15], v[4:5] op_sel_hi:[0,1,1]
	v_pk_fma_f32 v[4:5], v[210:211], v[18:19], v[4:5] op_sel_hi:[0,1,1]
	v_pk_fma_f32 v[4:5], v[206:207], v[22:23], v[4:5] op_sel_hi:[0,1,1]
	v_pk_fma_f32 v[4:5], v[204:205], v[26:27], v[4:5] op_sel_hi:[0,1,1]
	v_pk_fma_f32 v[4:5], v[200:201], v[30:31], v[4:5] op_sel_hi:[0,1,1]
	v_pk_fma_f32 v[4:5], v[202:203], v[34:35], v[4:5] op_sel_hi:[0,1,1]
	v_pk_fma_f32 v[4:5], v[198:199], v[38:39], v[4:5] op_sel_hi:[0,1,1]
	v_pk_fma_f32 v[4:5], v[196:197], v[42:43], v[4:5] op_sel_hi:[0,1,1]
	v_pk_fma_f32 v[50:51], v[194:195], v[46:47], v[4:5] op_sel_hi:[0,1,1]
	ds_read_b128 v[4:7], v2 offset:18752
	ds_read_b128 v[8:11], v2 offset:18768
	ds_read_b128 v[12:15], v2 offset:18784
	ds_read_b128 v[16:19], v2 offset:18800
	ds_read_b128 v[20:23], v2 offset:18816
	ds_read_b128 v[24:27], v2 offset:18832
	ds_read_b128 v[28:31], v2 offset:18848
	ds_read_b128 v[32:35], v2 offset:18864
	ds_read_b128 v[36:39], v2 offset:18880
	ds_read_b128 v[40:43], v2 offset:18896
	ds_read_b128 v[44:47], v2 offset:18912
	s_waitcnt lgkmcnt(10)
	v_pk_fma_f32 v[4:5], v[172:173], v[4:5], v[48:49] op_sel_hi:[0,1,1]
	s_waitcnt lgkmcnt(9)
	v_pk_fma_f32 v[4:5], v[174:175], v[8:9], v[4:5] op_sel_hi:[0,1,1]
	s_waitcnt lgkmcnt(8)
	v_pk_fma_f32 v[4:5], v[176:177], v[12:13], v[4:5] op_sel_hi:[0,1,1]
	s_waitcnt lgkmcnt(7)
	v_pk_fma_f32 v[4:5], v[178:179], v[16:17], v[4:5] op_sel_hi:[0,1,1]
	s_waitcnt lgkmcnt(6)
	v_pk_fma_f32 v[4:5], v[180:181], v[20:21], v[4:5] op_sel_hi:[0,1,1]
	s_waitcnt lgkmcnt(5)
	v_pk_fma_f32 v[4:5], v[182:183], v[24:25], v[4:5] op_sel_hi:[0,1,1]
	s_waitcnt lgkmcnt(4)
	v_pk_fma_f32 v[4:5], v[184:185], v[28:29], v[4:5] op_sel_hi:[0,1,1]
	s_waitcnt lgkmcnt(3)
	v_pk_fma_f32 v[4:5], v[186:187], v[32:33], v[4:5] op_sel_hi:[0,1,1]
	s_waitcnt lgkmcnt(2)
	v_pk_fma_f32 v[4:5], v[188:189], v[36:37], v[4:5] op_sel_hi:[0,1,1]
	s_waitcnt lgkmcnt(1)
	v_pk_fma_f32 v[4:5], v[190:191], v[40:41], v[4:5] op_sel_hi:[0,1,1]
	s_waitcnt lgkmcnt(0)
; #define LAS __attribute__((address_space(3)))
; #define LDS_WAIT() asm volatile("s_waitcnt lgkmcnt(0)" ::: "memory")
; __device__ __forceinline__ void seg_attend(SegAcc& A, const float* base, int kvh, int nk, bool valid, const LAS float* qs, LAS float* pt, int lane) {
;     ...
; #pragma unroll
;     for (int k = 0; k < 64; ++k) { const f32x4 pk = *(const LAS f32x4*)(pt + 4 * k);
; #pragma unroll
;         for (int gq = 0; gq < 4; ++gq) A.o[gq] += pk[gq] * vv[k]; }
;     LDS_WAIT();
	v_pk_fma_f32 v[48:49], v[192:193], v[44:45], v[4:5] op_sel_hi:[0,1,1]
	v_pk_fma_f32 v[4:5], v[172:173], v[6:7], v[50:51] op_sel_hi:[0,1,1]
	v_pk_fma_f32 v[4:5], v[174:175], v[10:11], v[4:5] op_sel_hi:[0,1,1]
	v_pk_fma_f32 v[4:5], v[176:177], v[14:15], v[4:5] op_sel_hi:[0,1,1]
	v_pk_fma_f32 v[4:5], v[178:179], v[18:19], v[4:5] op_sel_hi:[0,1,1]
	v_pk_fma_f32 v[4:5], v[180:181], v[22:23], v[4:5] op_sel_hi:[0,1,1]
	v_pk_fma_f32 v[4:5], v[182:183], v[26:27], v[4:5] op_sel_hi:[0,1,1]
	v_pk_fma_f32 v[4:5], v[184:185], v[30:31], v[4:5] op_sel_hi:[0,1,1]
	v_pk_fma_f32 v[4:5], v[186:187], v[34:35], v[4:5] op_sel_hi:[0,1,1]
	v_pk_fma_f32 v[4:5], v[188:189], v[38:39], v[4:5] op_sel_hi:[0,1,1]
	v_pk_fma_f32 v[4:5], v[190:191], v[42:43], v[4:5] op_sel_hi:[0,1,1]
	v_pk_fma_f32 v[50:51], v[192:193], v[46:47], v[4:5] op_sel_hi:[0,1,1]
	ds_read_b128 v[4:7], v2 offset:18928
	ds_read_b128 v[8:11], v2 offset:18944
	ds_read_b128 v[12:15], v2 offset:18960
	ds_read_b128 v[16:19], v2 offset:18976
	ds_read_b128 v[20:23], v2 offset:18992
	ds_read_b128 v[24:27], v2 offset:19008
	ds_read_b128 v[28:31], v2 offset:19024
	ds_read_b128 v[32:35], v2 offset:19040
	ds_read_b128 v[36:39], v2 offset:19056
	ds_read_b128 v[40:43], v2 offset:19072
	ds_read_b128 v[44:47], v2 offset:19088
	s_waitcnt lgkmcnt(10)
	v_pk_fma_f32 v[4:5], v[144:145], v[4:5], v[48:49] op_sel_hi:[0,1,1]
	s_waitcnt lgkmcnt(9)
	v_pk_fma_f32 v[4:5], v[170:171], v[8:9], v[4:5] op_sel_hi:[0,1,1]
	s_waitcnt lgkmcnt(8)
	v_pk_fma_f32 v[4:5], v[142:143], v[12:13], v[4:5] op_sel_hi:[0,1,1]
	s_waitcnt lgkmcnt(7)
	v_pk_fma_f32 v[4:5], v[140:141], v[16:17], v[4:5] op_sel_hi:[0,1,1]
	s_waitcnt lgkmcnt(6)
	v_pk_fma_f32 v[4:5], v[136:137], v[20:21], v[4:5] op_sel_hi:[0,1,1]
	s_waitcnt lgkmcnt(5)
	v_pk_fma_f32 v[4:5], v[138:139], v[24:25], v[4:5] op_sel_hi:[0,1,1]
	s_waitcnt lgkmcnt(4)
	v_pk_fma_f32 v[4:5], v[134:135], v[28:29], v[4:5] op_sel_hi:[0,1,1]
	s_waitcnt lgkmcnt(3)
	v_pk_fma_f32 v[4:5], v[132:133], v[32:33], v[4:5] op_sel_hi:[0,1,1]
	s_waitcnt lgkmcnt(2)
	v_pk_fma_f32 v[4:5], v[128:129], v[36:37], v[4:5] op_sel_hi:[0,1,1]
	s_waitcnt lgkmcnt(1)
	v_pk_fma_f32 v[4:5], v[130:131], v[40:41], v[4:5] op_sel_hi:[0,1,1]
	s_waitcnt lgkmcnt(0)
	v_pk_fma_f32 v[48:49], v[126:127], v[44:45], v[4:5] op_sel_hi:[0,1,1]
	v_pk_fma_f32 v[4:5], v[144:145], v[6:7], v[50:51] op_sel_hi:[0,1,1]
	v_pk_fma_f32 v[4:5], v[170:171], v[10:11], v[4:5] op_sel_hi:[0,1,1]
	v_pk_fma_f32 v[4:5], v[142:143], v[14:15], v[4:5] op_sel_hi:[0,1,1]
	v_pk_fma_f32 v[4:5], v[140:141], v[18:19], v[4:5] op_sel_hi:[0,1,1]
	v_pk_fma_f32 v[4:5], v[136:137], v[22:23], v[4:5] op_sel_hi:[0,1,1]
	v_pk_fma_f32 v[4:5], v[138:139], v[26:27], v[4:5] op_sel_hi:[0,1,1]
	v_pk_fma_f32 v[4:5], v[134:135], v[30:31], v[4:5] op_sel_hi:[0,1,1]
	v_pk_fma_f32 v[4:5], v[132:133], v[34:35], v[4:5] op_sel_hi:[0,1,1]
	v_pk_fma_f32 v[4:5], v[128:129], v[38:39], v[4:5] op_sel_hi:[0,1,1]
	v_pk_fma_f32 v[4:5], v[130:131], v[42:43], v[4:5] op_sel_hi:[0,1,1]
	v_pk_fma_f32 v[50:51], v[126:127], v[46:47], v[4:5] op_sel_hi:[0,1,1]
	ds_read_b128 v[4:7], v2 offset:19104
	ds_read_b128 v[8:11], v2 offset:19120
	ds_read_b128 v[12:15], v2 offset:19136
	ds_read_b128 v[16:19], v2 offset:19152
	ds_read_b128 v[20:23], v2 offset:19168
	ds_read_b128 v[24:27], v2 offset:19184
	ds_read_b128 v[28:31], v2 offset:19200
	ds_read_b128 v[32:35], v2 offset:19216
	ds_read_b128 v[36:39], v2 offset:19232
	ds_read_b128 v[40:43], v2 offset:19248
	ds_read_b128 v[44:47], v2 offset:19264
	s_waitcnt lgkmcnt(10)
	v_pk_fma_f32 v[4:5], v[90:91], v[4:5], v[48:49] op_sel_hi:[0,1,1]
	s_waitcnt lgkmcnt(9)
	v_pk_fma_f32 v[4:5], v[92:93], v[8:9], v[4:5] op_sel_hi:[0,1,1]
	s_waitcnt lgkmcnt(8)
	v_pk_fma_f32 v[4:5], v[94:95], v[12:13], v[4:5] op_sel_hi:[0,1,1]
	s_waitcnt lgkmcnt(7)
	v_pk_fma_f32 v[4:5], v[96:97], v[16:17], v[4:5] op_sel_hi:[0,1,1]
	s_waitcnt lgkmcnt(6)
	v_pk_fma_f32 v[4:5], v[112:113], v[20:21], v[4:5] op_sel_hi:[0,1,1]
	s_waitcnt lgkmcnt(5)
	v_pk_fma_f32 v[4:5], v[114:115], v[24:25], v[4:5] op_sel_hi:[0,1,1]
	s_waitcnt lgkmcnt(4)
	v_pk_fma_f32 v[4:5], v[116:117], v[28:29], v[4:5] op_sel_hi:[0,1,1]
	s_waitcnt lgkmcnt(3)
	v_pk_fma_f32 v[4:5], v[118:119], v[32:33], v[4:5] op_sel_hi:[0,1,1]
	s_waitcnt lgkmcnt(2)
	v_pk_fma_f32 v[4:5], v[120:121], v[36:37], v[4:5] op_sel_hi:[0,1,1]
	s_waitcnt lgkmcnt(1)
	v_pk_fma_f32 v[4:5], v[122:123], v[40:41], v[4:5] op_sel_hi:[0,1,1]
	s_waitcnt lgkmcnt(0)
	v_pk_fma_f32 v[48:49], v[124:125], v[44:45], v[4:5] op_sel_hi:[0,1,1]
	v_pk_fma_f32 v[4:5], v[90:91], v[6:7], v[50:51] op_sel_hi:[0,1,1]
	v_pk_fma_f32 v[4:5], v[92:93], v[10:11], v[4:5] op_sel_hi:[0,1,1]
	v_pk_fma_f32 v[4:5], v[94:95], v[14:15], v[4:5] op_sel_hi:[0,1,1]
	v_pk_fma_f32 v[4:5], v[96:97], v[18:19], v[4:5] op_sel_hi:[0,1,1]
	v_pk_fma_f32 v[4:5], v[112:113], v[22:23], v[4:5] op_sel_hi:[0,1,1]
	v_pk_fma_f32 v[4:5], v[114:115], v[26:27], v[4:5] op_sel_hi:[0,1,1]
	v_pk_fma_f32 v[4:5], v[116:117], v[30:31], v[4:5] op_sel_hi:[0,1,1]
	v_pk_fma_f32 v[4:5], v[118:119], v[34:35], v[4:5] op_sel_hi:[0,1,1]
	v_pk_fma_f32 v[4:5], v[120:121], v[38:39], v[4:5] op_sel_hi:[0,1,1]
	v_pk_fma_f32 v[4:5], v[122:123], v[42:43], v[4:5] op_sel_hi:[0,1,1]
	v_pk_fma_f32 v[50:51], v[124:125], v[46:47], v[4:5] op_sel_hi:[0,1,1]
	ds_read_b128 v[4:7], v2 offset:19280
	ds_read_b128 v[8:11], v2 offset:19296
	ds_read_b128 v[12:15], v2 offset:19312
	ds_read_b128 v[16:19], v2 offset:19328
	ds_read_b128 v[20:23], v2 offset:19344
	ds_read_b128 v[24:27], v2 offset:19360
	ds_read_b128 v[28:31], v2 offset:19376
	ds_read_b128 v[32:35], v2 offset:19392
	ds_read_b128 v[36:39], v2 offset:19408
	ds_read_b128 v[40:43], v2 offset:19424
	ds_read_b128 v[44:47], v2 offset:19440
	s_waitcnt lgkmcnt(10)
; #define LAS __attribute__((address_space(3)))
; __device__ __forceinline__ void seg_attend(SegAcc& A, const float* base, int kvh, int nk, bool valid, const LAS float* qs, LAS float* pt, int lane) {
;     ...
;     const f32x4* kp = (const f32x4*)(base + (size_t)(lane < nk ? lane : 0) * 256 + kvh * 64);
; #pragma unroll
;     for (int c4 = 0; c4 < 16; ++c4) kv[c4] = kp[c4];
;     const float* vb = base + 128 + kvh * 64 + lane;
; #pragma unroll
;     for (int k = 0; k < 64; ++k) vv[k] = vb[(size_t)(k < nk ? k : 0) * 256];
;     float s[4] = {0.f, 0.f, 0.f, 0.f};
; #pragma unroll
;     for (int c4 = 0; c4 < 16; ++c4)
; #pragma unroll
;         for (int gq = 0; gq < 4; ++gq) { const f32x4 qv = *(const LAS f32x4*)(qs + gq * 64 + 4 * c4); s[gq] += kv[c4][0] * qv[0] + kv[c4][1] * qv[1] + kv[c4][2] * qv[2] + kv[c4][3] * qv[3]; }
	v_pk_fma_f32 v[2:3], v[88:89], v[4:5], v[48:49] op_sel_hi:[0,1,1]
	s_waitcnt lgkmcnt(9)
	v_pk_fma_f32 v[2:3], v[86:87], v[8:9], v[2:3] op_sel_hi:[0,1,1]
	s_waitcnt lgkmcnt(8)
	v_pk_fma_f32 v[2:3], v[82:83], v[12:13], v[2:3] op_sel_hi:[0,1,1]
	s_waitcnt lgkmcnt(7)
	v_pk_fma_f32 v[2:3], v[84:85], v[16:17], v[2:3] op_sel_hi:[0,1,1]
	s_waitcnt lgkmcnt(6)
	v_pk_fma_f32 v[2:3], v[80:81], v[20:21], v[2:3] op_sel_hi:[0,1,1]
	s_waitcnt lgkmcnt(5)
	v_pk_fma_f32 v[2:3], v[78:79], v[24:25], v[2:3] op_sel_hi:[0,1,1]
	s_waitcnt lgkmcnt(4)
	v_pk_fma_f32 v[2:3], v[74:75], v[28:29], v[2:3] op_sel_hi:[0,1,1]
	s_waitcnt lgkmcnt(3)
	v_pk_fma_f32 v[2:3], v[76:77], v[32:33], v[2:3] op_sel_hi:[0,1,1]
	s_waitcnt lgkmcnt(2)
	v_pk_fma_f32 v[2:3], v[72:73], v[36:37], v[2:3] op_sel_hi:[0,1,1]
	s_waitcnt lgkmcnt(1)
	v_pk_fma_f32 v[2:3], v[70:71], v[40:41], v[2:3] op_sel_hi:[0,1,1]
	s_waitcnt lgkmcnt(0)
	v_pk_fma_f32 v[114:115], v[0:1], v[44:45], v[2:3] op_sel_hi:[0,1,1]
	v_pk_fma_f32 v[2:3], v[88:89], v[6:7], v[50:51] op_sel_hi:[0,1,1]
	v_pk_fma_f32 v[2:3], v[86:87], v[10:11], v[2:3] op_sel_hi:[0,1,1]
	v_pk_fma_f32 v[2:3], v[82:83], v[14:15], v[2:3] op_sel_hi:[0,1,1]
	v_pk_fma_f32 v[2:3], v[84:85], v[18:19], v[2:3] op_sel_hi:[0,1,1]
	v_pk_fma_f32 v[2:3], v[80:81], v[22:23], v[2:3] op_sel_hi:[0,1,1]
	v_pk_fma_f32 v[2:3], v[78:79], v[26:27], v[2:3] op_sel_hi:[0,1,1]
	v_pk_fma_f32 v[2:3], v[74:75], v[30:31], v[2:3] op_sel_hi:[0,1,1]
	v_pk_fma_f32 v[2:3], v[76:77], v[34:35], v[2:3] op_sel_hi:[0,1,1]
	v_pk_fma_f32 v[2:3], v[72:73], v[38:39], v[2:3] op_sel_hi:[0,1,1]
	s_waitcnt lgkmcnt(0)
	v_pk_fma_f32 v[2:3], v[70:71], v[42:43], v[2:3] op_sel_hi:[0,1,1]
	v_pk_fma_f32 v[112:113], v[0:1], v[46:47], v[2:3] op_sel_hi:[0,1,1]
	s_cbranch_vccz .LBB0_1576
	v_readlane_b32 s1, v251, 61
	v_cmp_gt_i32_e32 vcc, 4, v98
	ds_read_b128 v[6:9], v1 offset:55296
	v_mov_b32_e32 v0, s1
	ds_read_b64 v[62:63], v0
	v_cndmask_b32_e32 v2, 0, v98, vcc
	v_ashrrev_i32_e32 v3, 31, v2
	v_lshlrev_b64 v[2:3], 10, v[2:3]
	v_cmp_lt_i32_e32 vcc, s25, v98
	s_waitcnt lgkmcnt(0)
	v_lshl_add_u64 v[2:3], v[62:63], 0, v[2:3]
	v_lshl_add_u64 v[64:65], v[2:3], 0, s[78:79]
	flat_load_dwordx4 v[18:21], v[64:65]
	flat_load_dwordx4 v[14:17], v[64:65] offset:16
	flat_load_dwordx4 v[10:13], v[64:65] offset:32
	ds_read_b128 v[26:29], v1 offset:55312
	ds_read_b128 v[22:25], v1 offset:55328
	ds_read_b128 v[2:5], v1 offset:55344
	ds_read_b128 v[30:33], v1 offset:55568
	ds_read_b128 v[38:41], v1 offset:55584
	ds_read_b128 v[46:49], v1 offset:55824
	ds_read_b128 v[34:37], v1 offset:55840
	ds_read_b128 v[50:53], v1 offset:56080
	ds_read_b128 v[42:45], v1 offset:56096
	ds_read_b128 v[54:57], v1 offset:55552
	ds_read_b128 v[58:61], v1 offset:55536
	ds_read_b128 v[128:131], v1 offset:55808
	ds_read_b128 v[70:73], v1 offset:55792
	ds_read_b128 v[132:135], v1 offset:56064
	ds_read_b128 v[66:69], v1 offset:56048
	flat_load_dwordx4 v[136:139], v[64:65] offset:48
	v_lshl_add_u64 v[62:63], v[62:63], 0, s[78:79]
	v_lshl_add_u64 v[144:145], v[98:99], 2, v[62:63]
	flat_load_dwordx4 v[140:143], v[64:65] offset:64
	flat_load_dwordx4 v[242:245], v[64:65] offset:80
	flat_load_dwordx4 v[228:231], v[64:65] offset:96
	flat_load_dwordx4 v[220:223], v[64:65] offset:112
	flat_load_dwordx4 v[224:227], v[64:65] offset:128
	flat_load_dwordx4 v[94:97], v[64:65] offset:144
	flat_load_dwordx4 v[90:93], v[64:65] offset:160
	flat_load_dwordx4 v[86:89], v[64:65] offset:176
	flat_load_dwordx4 v[82:85], v[64:65] offset:192
	flat_load_dwordx4 v[78:81], v[64:65] offset:208
	flat_load_dwordx4 v[74:77], v[64:65] offset:224
	s_nop 0
	flat_load_dwordx4 v[62:65], v[64:65] offset:240
	s_nop 0
	flat_load_dword v0, v[144:145] offset:512
	flat_load_dword v116, v[144:145] offset:1536
	flat_load_dword v118, v[144:145] offset:2560
	flat_load_dword v120, v[144:145] offset:3584
	s_mov_b32 s1, s0
	s_waitcnt vmcnt(0) lgkmcnt(0)
	ds_read_b128 v[146:149], v1 offset:55600
	ds_read_b128 v[150:153], v1 offset:55616
	v_mul_f32_e32 v7, v19, v7
	v_mul_f32_e32 v27, v15, v27
	v_fmac_f32_e32 v7, v18, v6
	v_mul_f32_e32 v23, v11, v23
	v_fmac_f32_e32 v27, v14, v26
	ds_read_b128 v[154:157], v1 offset:55856
	v_fmac_f32_e32 v7, v20, v8
	v_fmac_f32_e32 v23, v10, v22
	v_fmac_f32_e32 v27, v16, v28
	v_fmac_f32_e32 v7, v21, v9
	ds_read_b128 v[158:161], v1 offset:55872
	ds_read_b128 v[162:165], v1 offset:56112
	v_mul_f32_e32 v99, v19, v129
	v_fmac_f32_e32 v23, v12, v24
	v_fmac_f32_e32 v27, v17, v29
	v_add_f32_e32 v6, 0, v7
	v_mul_f32_e32 v31, v15, v31
	v_mul_f32_e32 v47, v15, v47
	v_mul_f32_e32 v15, v15, v51
	v_fmac_f32_e32 v99, v18, v128
	v_fmac_f32_e32 v23, v13, v25
	s_waitcnt lgkmcnt(4)
	ds_read_b128 v[166:169], v1 offset:56128
	v_add_f32_e32 v6, v6, v27
	v_fmac_f32_e32 v31, v14, v30
	v_fmac_f32_e32 v47, v14, v46
	v_fmac_f32_e32 v15, v14, v50
	v_fmac_f32_e32 v99, v20, v130
	v_add_f32_e32 v14, v6, v23
	v_mul_f32_e32 v6, v11, v35
	v_fmac_f32_e32 v47, v16, v48
	v_fmac_f32_e32 v99, v21, v131
	v_fmac_f32_e32 v6, v10, v34
	v_fmac_f32_e32 v47, v17, v49
	v_add_f32_e32 v8, 0, v99
	v_fmac_f32_e32 v6, v12, v36
	v_add_f32_e32 v8, v8, v47
	v_fmac_f32_e32 v6, v13, v37
	v_mul_f32_e32 v39, v11, v39
	v_add_f32_e32 v22, v8, v6
	v_mul_f32_e32 v6, v11, v43
	v_fmac_f32_e32 v39, v10, v38
	v_fmac_f32_e32 v6, v10, v42
	v_fmac_f32_e32 v39, v12, v40
	v_fmac_f32_e32 v6, v12, v44
	v_fmac_f32_e32 v39, v13, v41
	v_fmac_f32_e32 v6, v13, v45
	v_mul_f32_e32 v3, v137, v3
	v_mul_f32_e32 v55, v19, v55
	v_mul_f32_e32 v19, v19, v133
	v_fmac_f32_e32 v3, v136, v2
	v_fmac_f32_e32 v55, v18, v54
	v_fmac_f32_e32 v19, v18, v132
	v_fmac_f32_e32 v3, v138, v4
	v_fmac_f32_e32 v55, v20, v56
	v_fmac_f32_e32 v19, v20, v134
	v_fmac_f32_e32 v3, v139, v5
	v_fmac_f32_e32 v31, v16, v32
	v_fmac_f32_e32 v15, v16, v52
	v_fmac_f32_e32 v55, v21, v57
	v_fmac_f32_e32 v19, v21, v135
	v_add_f32_e32 v24, v14, v3
	v_mul_f32_e32 v11, v137, v147
	v_fmac_f32_e32 v31, v17, v33
	v_fmac_f32_e32 v15, v17, v53
	v_add_f32_e32 v7, 0, v55
	v_add_f32_e32 v9, 0, v19
	v_fmac_f32_e32 v11, v136, v146
	v_add_f32_e32 v7, v7, v31
	v_add_f32_e32 v9, v9, v15
	v_fmac_f32_e32 v11, v138, v148
	v_add_f32_e32 v18, v7, v39
	v_fmac_f32_e32 v11, v139, v149
	s_waitcnt lgkmcnt(4)
; #define LAS __attribute__((address_space(3)))
; __device__ __forceinline__ void seg_attend(SegAcc& A, const float* base, int kvh, int nk, bool valid, const LAS float* qs, LAS float* pt, int lane) {
;     ...
; #pragma unroll
;     for (int c4 = 0; c4 < 16; ++c4)
; #pragma unroll
;         for (int gq = 0; gq < 4; ++gq) { const f32x4 qv = *(const LAS f32x4*)(qs + gq * 64 + 4 * c4); s[gq] += kv[c4][0] * qv[0] + kv[c4][1] * qv[1] + kv[c4][2] * qv[2] + kv[c4][3] * qv[3]; }
	ds_read_b128 v[146:149], v1 offset:55360
	v_add_f32_e32 v25, v18, v11
	s_waitcnt lgkmcnt(4)
	v_mul_f32_e32 v15, v137, v155
	v_fmac_f32_e32 v15, v136, v154
	v_mul_f32_e32 v3, v141, v151
	v_fmac_f32_e32 v15, v138, v156
	v_fmac_f32_e32 v3, v140, v150
	s_waitcnt lgkmcnt(3)
	v_mul_f32_e32 v2, v141, v159
	v_fmac_f32_e32 v15, v139, v157
	ds_read_b128 v[154:157], v1 offset:55376
	v_fmac_f32_e32 v2, v140, v158
	v_add_f32_e32 v22, v22, v15
	s_waitcnt lgkmcnt(3)
	v_mul_f32_e32 v19, v137, v163
	v_fmac_f32_e32 v3, v142, v152
	v_fmac_f32_e32 v2, v142, v160
	v_add_f32_e32 v23, v9, v6
	v_fmac_f32_e32 v19, v136, v162
	v_fmac_f32_e32 v3, v143, v153
	ds_read_b128 v[150:153], v1 offset:55632
	v_fmac_f32_e32 v2, v143, v161
	ds_read_b128 v[158:161], v1 offset:55648
	v_fmac_f32_e32 v19, v138, v164
	v_add_f32_e32 v20, v25, v3
	v_add_f32_e32 v22, v22, v2
	s_waitcnt lgkmcnt(3)
	v_mul_f32_e32 v7, v141, v147
	v_fmac_f32_e32 v7, v140, v146
	v_fmac_f32_e32 v7, v142, v148
	s_waitcnt lgkmcnt(2)
	v_mul_f32_e32 v3, v243, v155
	v_fmac_f32_e32 v3, v242, v154
	v_fmac_f32_e32 v19, v139, v165
	ds_read_b128 v[162:165], v1 offset:55888
	v_fmac_f32_e32 v7, v143, v149
	ds_read_b128 v[146:149], v1 offset:55904
	v_fmac_f32_e32 v3, v244, v156
	v_add_f32_e32 v18, v23, v19
	v_add_f32_e32 v19, v24, v7
	v_mul_f32_e32 v6, v141, v167
	v_fmac_f32_e32 v3, v245, v157
	ds_read_b128 v[154:157], v1 offset:56144
	v_fmac_f32_e32 v6, v140, v166
	v_add_f32_e32 v24, v19, v3
	s_waitcnt lgkmcnt(4)
	v_mul_f32_e32 v11, v243, v151
	v_fmac_f32_e32 v6, v142, v168
	v_fmac_f32_e32 v11, v242, v150
	v_fmac_f32_e32 v6, v143, v169
	ds_read_b128 v[166:169], v1 offset:56160
	v_fmac_f32_e32 v11, v244, v152
	v_fmac_f32_e32 v11, v245, v153
	s_waitcnt lgkmcnt(4)
	ds_read_b128 v[150:153], v1 offset:55392
	v_add_f32_e32 v25, v20, v11
	v_add_f32_e32 v23, v18, v6
	s_waitcnt lgkmcnt(4)
	v_mul_f32_e32 v15, v243, v163
	v_fmac_f32_e32 v15, v242, v162
	v_mul_f32_e32 v3, v229, v159
	v_fmac_f32_e32 v15, v244, v164
	v_fmac_f32_e32 v3, v228, v158
	s_waitcnt lgkmcnt(3)
	v_mul_f32_e32 v2, v229, v147
	v_fmac_f32_e32 v15, v245, v165
	ds_read_b128 v[162:165], v1 offset:55408
	v_fmac_f32_e32 v2, v228, v146
	v_add_f32_e32 v22, v22, v15
	s_waitcnt lgkmcnt(3)
	v_mul_f32_e32 v19, v243, v155
	v_fmac_f32_e32 v3, v230, v160
	v_fmac_f32_e32 v2, v230, v148
	v_fmac_f32_e32 v19, v242, v154
	v_fmac_f32_e32 v3, v231, v161
	ds_read_b128 v[158:161], v1 offset:55664
	v_fmac_f32_e32 v2, v231, v149
	ds_read_b128 v[146:149], v1 offset:55680
	v_fmac_f32_e32 v19, v244, v156
	v_add_f32_e32 v20, v25, v3
	v_add_f32_e32 v22, v22, v2
	s_waitcnt lgkmcnt(3)
	v_mul_f32_e32 v7, v229, v151
	v_fmac_f32_e32 v7, v228, v150
	v_fmac_f32_e32 v7, v230, v152
	s_waitcnt lgkmcnt(2)
	v_mul_f32_e32 v3, v221, v163
	v_fmac_f32_e32 v3, v220, v162
	v_fmac_f32_e32 v19, v245, v157
	ds_read_b128 v[154:157], v1 offset:56176
	v_fmac_f32_e32 v7, v231, v153
	ds_read_b128 v[150:153], v1 offset:55424
	v_fmac_f32_e32 v3, v222, v164
	v_add_f32_e32 v18, v23, v19
	v_add_f32_e32 v19, v24, v7
	v_fmac_f32_e32 v3, v223, v165
	ds_read_b128 v[162:165], v1 offset:55440
	v_mul_f32_e32 v6, v229, v167
	v_add_f32_e32 v30, v19, v3
	s_waitcnt lgkmcnt(4)
	v_mul_f32_e32 v11, v221, v159
	v_fmac_f32_e32 v6, v228, v166
	v_fmac_f32_e32 v11, v220, v158
	v_fmac_f32_e32 v6, v230, v168
	v_fmac_f32_e32 v11, v222, v160
	v_fmac_f32_e32 v6, v231, v169
	ds_read_b128 v[166:169], v1 offset:55920
	v_fmac_f32_e32 v11, v223, v161
	s_waitcnt lgkmcnt(4)
	ds_read_b128 v[158:161], v1 offset:55936
	v_add_f32_e32 v23, v18, v6
	v_add_f32_e32 v32, v20, v11
	v_mov_b32_e32 v27, v94
	v_mov_b32_e32 v94, v225
	v_mov_b32_e32 v26, v224
	s_waitcnt lgkmcnt(4)
	v_mul_f32_e32 v19, v221, v155
	v_fmac_f32_e32 v19, v220, v154
	v_fmac_f32_e32 v19, v222, v156
	v_fmac_f32_e32 v19, v223, v157
	ds_read_b128 v[154:157], v1 offset:55696
	v_add_f32_e32 v34, v23, v19
	s_waitcnt lgkmcnt(4)
	v_mov_b32_e32 v28, v150
	v_mov_b32_e32 v57, s1
	s_waitcnt lgkmcnt(3)
	v_mov_b32_e32 v29, v162
	v_mov_b32_e32 v18, v151
	v_mov_b32_e32 v19, v163
	v_pk_mul_f32 v[6:7], v[94:95], v[18:19]
	v_mov_b32_e32 v18, v152
	v_pk_fma_f32 v[6:7], v[26:27], v[28:29], v[6:7]
	v_mov_b32_e32 v28, v226
	v_mov_b32_e32 v29, v96
	v_mov_b32_e32 v19, v164
	v_pk_fma_f32 v[6:7], v[28:29], v[18:19], v[6:7]
	v_mov_b32_e32 v96, v227
	v_mov_b32_e32 v20, v153
	ds_read_b128 v[150:153], v1 offset:55712
	v_mov_b32_e32 v21, v165
	ds_read_b128 v[162:165], v1 offset:56192
	v_pk_fma_f32 v[18:19], v[96:97], v[20:21], v[6:7]
	v_add_f32_e32 v18, v30, v18
	s_waitcnt lgkmcnt(4)
	v_mul_f32_e32 v15, v221, v167
	v_add_f32_e32 v35, v18, v19
	s_waitcnt lgkmcnt(2)
	v_mov_b32_e32 v31, v154
	v_mov_b32_e32 v6, v147
	v_fmac_f32_e32 v15, v220, v166
	v_mov_b32_e32 v30, v146
	v_mov_b32_e32 v7, v155
	v_pk_mul_f32 v[2:3], v[94:95], v[6:7]
	v_fmac_f32_e32 v15, v222, v168
	v_pk_fma_f32 v[2:3], v[26:27], v[30:31], v[2:3]
	v_mov_b32_e32 v6, v148
	v_mov_b32_e32 v7, v156
	v_fmac_f32_e32 v15, v223, v169
	ds_read_b128 v[166:169], v1 offset:55952
	v_pk_fma_f32 v[2:3], v[28:29], v[6:7], v[2:3]
	v_mov_b32_e32 v8, v149
	ds_read_b128 v[146:149], v1 offset:55456
	v_add_f32_e32 v33, v22, v15
	v_mov_b32_e32 v9, v157
	ds_read_b128 v[154:157], v1 offset:56208
	v_pk_fma_f32 v[6:7], v[96:97], v[8:9], v[2:3]
	v_mov_b32_e32 v30, v158
	v_mov_b32_e32 v10, v160
	v_add_f32_e32 v6, v32, v6
	s_waitcnt lgkmcnt(2)
	v_mov_b32_e32 v31, v166
	v_mov_b32_e32 v2, v159
	v_mov_b32_e32 v3, v167
	v_pk_mul_f32 v[2:3], v[94:95], v[2:3]
	v_mov_b32_e32 v11, v168
	v_pk_fma_f32 v[2:3], v[26:27], v[30:31], v[2:3]
	v_mov_b32_e32 v4, v161
	ds_read_b128 v[158:161], v1 offset:56224
	v_pk_fma_f32 v[2:3], v[28:29], v[10:11], v[2:3]
	v_mov_b32_e32 v30, v162
	v_mov_b32_e32 v5, v169
	ds_read_b128 v[166:169], v1 offset:55472
	v_pk_fma_f32 v[10:11], v[96:97], v[4:5], v[2:3]
	v_add_f32_e32 v10, v33, v10
	v_add_f32_e32 v33, v10, v11
	v_mov_b32_e32 v14, v164
	s_waitcnt lgkmcnt(2)
; #define LAS __attribute__((address_space(3)))
; __device__ __forceinline__ void seg_attend(SegAcc& A, const float* base, int kvh, int nk, bool valid, const LAS float* qs, LAS float* pt, int lane) {
;     ...
; #pragma unroll
;     for (int c4 = 0; c4 < 16; ++c4)
; #pragma unroll
;         for (int gq = 0; gq < 4; ++gq) { const f32x4 qv = *(const LAS f32x4*)(qs + gq * 64 + 4 * c4); s[gq] += kv[c4][0] * qv[0] + kv[c4][1] * qv[1] + kv[c4][2] * qv[2] + kv[c4][3] * qv[3]; }
	v_mov_b32_e32 v31, v154
	v_mov_b32_e32 v2, v163
	v_mov_b32_e32 v3, v155
	v_pk_mul_f32 v[2:3], v[94:95], v[2:3]
	v_mov_b32_e32 v15, v156
	v_pk_fma_f32 v[2:3], v[26:27], v[30:31], v[2:3]
	v_mov_b32_e32 v4, v165
	ds_read_b128 v[162:165], v1 offset:55968
	v_pk_fma_f32 v[2:3], v[28:29], v[14:15], v[2:3]
	v_mov_b32_e32 v27, v86
	v_mov_b32_e32 v5, v157
	ds_read_b128 v[154:157], v1 offset:55728
	v_pk_fma_f32 v[2:3], v[96:97], v[4:5], v[2:3]
	v_mov_b32_e32 v86, v91
	v_add_f32_e32 v2, v34, v2
	v_add_f32_e32 v34, v2, v3
	v_mov_b32_e32 v26, v90
	v_mov_b32_e32 v28, v146
	v_mov_b32_e32 v22, v148
	v_add_f32_e32 v32, v6, v7
	s_waitcnt lgkmcnt(2)
	v_mov_b32_e32 v29, v166
	v_mov_b32_e32 v2, v147
	v_mov_b32_e32 v3, v167
	v_pk_mul_f32 v[2:3], v[86:87], v[2:3]
	v_mov_b32_e32 v23, v168
	v_pk_fma_f32 v[2:3], v[26:27], v[28:29], v[2:3]
	v_mov_b32_e32 v28, v92
	v_mov_b32_e32 v29, v88
	v_pk_fma_f32 v[2:3], v[28:29], v[22:23], v[2:3]
	v_mov_b32_e32 v88, v93
	v_mov_b32_e32 v4, v149
	ds_read_b128 v[146:149], v1 offset:55488
	v_mov_b32_e32 v5, v169
	ds_read_b128 v[166:169], v1 offset:55984
	v_pk_fma_f32 v[22:23], v[88:89], v[4:5], v[2:3]
	v_mov_b32_e32 v30, v150
	v_mov_b32_e32 v18, v152
	v_add_f32_e32 v22, v35, v22
	s_waitcnt lgkmcnt(2)
	v_mov_b32_e32 v31, v154
	v_mov_b32_e32 v2, v151
	v_mov_b32_e32 v3, v155
	v_pk_mul_f32 v[2:3], v[86:87], v[2:3]
	v_mov_b32_e32 v19, v156
	v_pk_fma_f32 v[2:3], v[26:27], v[30:31], v[2:3]
	v_mov_b32_e32 v4, v153
	ds_read_b128 v[150:153], v1 offset:56000
	v_pk_fma_f32 v[2:3], v[28:29], v[18:19], v[2:3]
	v_mov_b32_e32 v30, v162
	v_mov_b32_e32 v5, v157
	ds_read_b128 v[154:157], v1 offset:56240
	v_pk_fma_f32 v[18:19], v[88:89], v[4:5], v[2:3]
	v_add_f32_e32 v18, v32, v18
	v_add_f32_e32 v32, v18, v19
	v_mov_b32_e32 v6, v164
	s_waitcnt lgkmcnt(2)
	v_mov_b32_e32 v31, v166
	v_mov_b32_e32 v2, v163
	v_mov_b32_e32 v3, v167
	v_pk_mul_f32 v[2:3], v[86:87], v[2:3]
	v_mov_b32_e32 v7, v168
	v_pk_fma_f32 v[2:3], v[26:27], v[30:31], v[2:3]
	v_mov_b32_e32 v4, v165
	ds_read_b128 v[162:165], v1 offset:56256
	v_pk_fma_f32 v[2:3], v[28:29], v[6:7], v[2:3]
	v_mov_b32_e32 v30, v158
	v_mov_b32_e32 v5, v169
	ds_read_b128 v[166:169], v1 offset:55504
	v_pk_fma_f32 v[6:7], v[88:89], v[4:5], v[2:3]
	v_add_f32_e32 v6, v33, v6
	v_add_f32_e32 v33, v6, v7
	v_mov_b32_e32 v10, v160
	s_waitcnt lgkmcnt(2)
	v_mov_b32_e32 v31, v154
	v_mov_b32_e32 v2, v159
	v_mov_b32_e32 v3, v155
	v_pk_mul_f32 v[2:3], v[86:87], v[2:3]
	v_mov_b32_e32 v11, v156
	v_pk_fma_f32 v[2:3], v[26:27], v[30:31], v[2:3]
	v_mov_b32_e32 v4, v161
	ds_read_b128 v[158:161], v1 offset:55744
	v_pk_fma_f32 v[2:3], v[28:29], v[10:11], v[2:3]
	v_mov_b32_e32 v27, v78
	v_mov_b32_e32 v5, v157
	ds_read_b128 v[154:157], v1 offset:55520
	v_pk_fma_f32 v[2:3], v[88:89], v[4:5], v[2:3]
	v_mov_b32_e32 v78, v83
	v_add_f32_e32 v2, v34, v2
	v_add_f32_e32 v34, v2, v3
	v_mov_b32_e32 v26, v82
	v_mov_b32_e32 v28, v146
	v_mov_b32_e32 v14, v148
	v_add_f32_e32 v35, v22, v23
	s_waitcnt lgkmcnt(2)
	v_mov_b32_e32 v29, v166
	v_mov_b32_e32 v2, v147
	v_mov_b32_e32 v3, v167
	v_pk_mul_f32 v[2:3], v[78:79], v[2:3]
	v_mov_b32_e32 v15, v168
	v_pk_fma_f32 v[2:3], v[26:27], v[28:29], v[2:3]
	v_mov_b32_e32 v28, v84
	v_mov_b32_e32 v29, v80
	v_pk_fma_f32 v[2:3], v[28:29], v[14:15], v[2:3]
	v_mov_b32_e32 v80, v85
	v_mov_b32_e32 v4, v149
	ds_read_b128 v[146:149], v1 offset:55760
	v_mov_b32_e32 v5, v169
	ds_read_b128 v[166:169], v1 offset:55776
	v_pk_fma_f32 v[14:15], v[80:81], v[4:5], v[2:3]
	v_add_f32_e32 v14, v35, v14
	v_add_f32_e32 v35, v14, v15
	s_waitcnt lgkmcnt(3)
	v_mov_b32_e32 v30, v158
	s_waitcnt lgkmcnt(1)
	v_mov_b32_e32 v31, v146
	v_mov_b32_e32 v2, v159
	v_mov_b32_e32 v3, v147
	v_pk_mul_f32 v[2:3], v[78:79], v[2:3]
	v_mov_b32_e32 v22, v160
	v_pk_fma_f32 v[2:3], v[26:27], v[30:31], v[2:3]
	v_mov_b32_e32 v23, v148
	v_pk_fma_f32 v[2:3], v[28:29], v[22:23], v[2:3]
	v_mov_b32_e32 v4, v161
	ds_read_b128 v[158:161], v1 offset:56016
	v_mov_b32_e32 v5, v149
	ds_read_b128 v[146:149], v1 offset:56032
	v_pk_fma_f32 v[22:23], v[80:81], v[4:5], v[2:3]
	v_add_f32_e32 v22, v32, v22
	v_add_f32_e32 v32, v22, v23
	v_mov_b32_e32 v30, v150
	s_waitcnt lgkmcnt(1)
	v_mov_b32_e32 v31, v158
	v_mov_b32_e32 v2, v151
	v_mov_b32_e32 v3, v159
	v_pk_mul_f32 v[2:3], v[78:79], v[2:3]
	v_mov_b32_e32 v18, v152
	v_pk_fma_f32 v[2:3], v[26:27], v[30:31], v[2:3]
	v_mov_b32_e32 v19, v160
	v_pk_fma_f32 v[2:3], v[28:29], v[18:19], v[2:3]
	v_mov_b32_e32 v4, v153
	ds_read_b128 v[150:153], v1 offset:56272
	v_mov_b32_e32 v5, v161
	ds_read_b128 v[158:161], v1 offset:56288
	v_pk_fma_f32 v[18:19], v[80:81], v[4:5], v[2:3]
	v_add_f32_e32 v18, v33, v18
	v_add_f32_e32 v33, v18, v19
	v_mov_b32_e32 v30, v162
	s_waitcnt lgkmcnt(1)
	v_mov_b32_e32 v31, v150
	v_mov_b32_e32 v2, v163
	v_mov_b32_e32 v3, v151
	v_pk_mul_f32 v[2:3], v[78:79], v[2:3]
	v_mov_b32_e32 v6, v164
	v_pk_fma_f32 v[2:3], v[26:27], v[30:31], v[2:3]
	v_mov_b32_e32 v7, v152
	v_pk_fma_f32 v[2:3], v[28:29], v[6:7], v[2:3]
	v_mov_b32_e32 v4, v165
	ds_read_b128 v[162:165], v1 offset:56304
	v_mov_b32_e32 v5, v153
	v_pk_fma_f32 v[2:3], v[80:81], v[4:5], v[2:3]
	v_mov_b32_e32 v7, v62
	v_add_f32_e32 v2, v34, v2
	v_add_f32_e32 v26, v2, v3
	v_mov_b32_e32 v3, v58
	v_mov_b32_e32 v62, v75
	v_mov_b32_e32 v58, v155
	v_mov_b32_e32 v6, v74
	v_mov_b32_e32 v2, v154
	v_pk_mul_f32 v[4:5], v[62:63], v[58:59]
	v_mov_b32_e32 v8, v76
	v_pk_fma_f32 v[2:3], v[6:7], v[2:3], v[4:5]
	v_mov_b32_e32 v9, v64
	v_mov_b32_e32 v4, v156
	v_mov_b32_e32 v5, v60
	v_pk_fma_f32 v[2:3], v[8:9], v[4:5], v[2:3]
	v_mov_b32_e32 v64, v77
	v_mov_b32_e32 v60, v157
	v_pk_fma_f32 v[2:3], v[64:65], v[60:61], v[2:3]
	s_nop 0
	v_add_f32_e32 v2, v35, v2
	v_add_f32_e32 v12, v2, v3
	v_mov_b32_e32 v3, v70
	v_mov_b32_e32 v70, v167
	v_mov_b32_e32 v2, v166
	v_pk_mul_f32 v[4:5], v[62:63], v[70:71]
	s_nop 0
	v_pk_fma_f32 v[2:3], v[6:7], v[2:3], v[4:5]
	v_mov_b32_e32 v4, v168
	v_mov_b32_e32 v5, v72
	v_pk_fma_f32 v[2:3], v[8:9], v[4:5], v[2:3]
	v_mov_b32_e32 v72, v169
	v_pk_fma_f32 v[2:3], v[64:65], v[72:73], v[2:3]
	s_nop 0
	v_add_f32_e32 v2, v32, v2
	v_add_f32_e32 v13, v2, v3
	v_mov_b32_e32 v3, v66
	v_mov_b32_e32 v66, v147
	v_mov_b32_e32 v2, v146
	v_pk_mul_f32 v[4:5], v[62:63], v[66:67]
	s_nop 0
	v_pk_fma_f32 v[2:3], v[6:7], v[2:3], v[4:5]
	v_mov_b32_e32 v4, v148
	v_mov_b32_e32 v5, v68
	v_pk_fma_f32 v[10:11], v[8:9], v[4:5], v[2:3]
	v_mov_b32_e32 v68, v149
	v_pk_fma_f32 v[10:11], v[64:65], v[68:69], v[10:11]
	s_nop 0
	v_add_f32_e32 v10, v33, v10
	v_add_f32_e32 v14, v10, v11
	s_waitcnt lgkmcnt(0)
; #define LAS __attribute__((address_space(3)))
; __device__ __forceinline__ float ex2(float x) { return __builtin_amdgcn_exp2f(x); }
; template <int CTRL> __device__ __forceinline__ float dpp_mov(float old, float x) { return __int_as_float(__builtin_amdgcn_update_dpp(__float_as_int(old), __float_as_int(x), CTRL, 0xF, 0xF, false)); }
; #define LDS_WAIT() asm volatile("s_waitcnt lgkmcnt(0)" ::: "memory")
; __device__ __forceinline__ float wave_max(float v) {
;     v = fmaxf(v, dpp_mov<0x111>(v, v)); v = fmaxf(v, dpp_mov<0x112>(v, v)); v = fmaxf(v, dpp_mov<0x114>(v, v)); v = fmaxf(v, dpp_mov<0x118>(v, v));
;     v = fmaxf(v, __int_as_float(__builtin_amdgcn_update_dpp(__float_as_int(v), __float_as_int(v), 0x142, 0xA, 0xF, false)));
;     v = fmaxf(v, __int_as_float(__builtin_amdgcn_update_dpp(__float_as_int(v), __float_as_int(v), 0x143, 0xC, 0xF, false)));
;     return __int_as_float(__builtin_amdgcn_readlane(__float_as_int(v), 63));
; __device__ __forceinline__ void seg_attend(SegAcc& A, const float* base, int kvh, int nk, bool valid, const LAS float* qs, LAS float* pt, int lane) {
;     ...
;         for (int gq = 0; gq < 4; ++gq) { const f32x4 qv = *(const LAS f32x4*)(qs + gq * 64 + 4 * c4); s[gq] += kv[c4][0] * qv[0] + kv[c4][1] * qv[1] + kv[c4][2] * qv[2] + kv[c4][3] * qv[3]; }
;     valid = valid && lane < nk;
;     f32x4 p;
; #pragma unroll
;     for (int gq = 0; gq < 4; ++gq) { const float sv = valid ? s[gq] : NEGB; const float mx = wave_max(sv); const float mn = fmaxf(A.m[gq], mx), a = ex2(A.m[gq] - mn);
;         p[gq] = valid ? ex2(sv - mn) : 0.f; A.l[gq] = A.l[gq] * a + p[gq]; A.o[gq] *= a; A.m[gq] = mn; }
;     *(LAS f32x4*)(pt + 4 * lane) = p;
;     LDS_WAIT();
; #pragma unroll
;     for (int k = 0; k < 64; ++k) { const f32x4 pk = *(const LAS f32x4*)(pt + 4 * k);
	v_mov_b32_e32 v11, v162
	v_mov_b32_e32 v2, v159
	v_mov_b32_e32 v10, v158
	v_mov_b32_e32 v3, v163
	v_pk_mul_f32 v[2:3], v[62:63], v[2:3]
	s_nop 0
	v_pk_fma_f32 v[2:3], v[6:7], v[10:11], v[2:3]
	v_mov_b32_e32 v6, v160
	v_mov_b32_e32 v7, v164
	v_pk_fma_f32 v[2:3], v[8:9], v[6:7], v[2:3]
	v_mov_b32_e32 v4, v161
	v_mov_b32_e32 v5, v165
	v_pk_fma_f32 v[2:3], v[64:65], v[4:5], v[2:3]
	v_cndmask_b32_e32 v5, v12, v209, vcc
	v_add_f32_e32 v4, v26, v2
	v_mov_b32_e32 v2, v5
	v_add_f32_e32 v3, v4, v3
	v_cndmask_b32_e32 v3, v3, v209, vcc
	v_mov_b32_dpp v2, v2 row_shr:1 row_mask:0xf bank_mask:0xf
	v_max_f32_e32 v2, v2, v2
	v_max_f32_e32 v2, v5, v2
	v_mov_b32_e32 v6, v2
	s_nop 1
	v_mov_b32_dpp v6, v6 row_shr:2 row_mask:0xf bank_mask:0xf
	v_max_f32_e32 v6, v6, v6
	v_max_f32_e32 v2, v2, v6
	v_mov_b32_e32 v6, v2
	s_nop 1
	v_mov_b32_dpp v6, v6 row_shr:4 row_mask:0xf bank_mask:0xf
	v_max_f32_e32 v6, v6, v6
	v_max_f32_e32 v2, v2, v6
	v_mov_b32_e32 v6, v2
	s_nop 1
	v_mov_b32_dpp v6, v6 row_shr:8 row_mask:0xf bank_mask:0xf
	v_max_f32_e32 v6, v6, v6
	v_max_f32_e32 v2, v2, v6
	v_mov_b32_e32 v6, v2
	s_nop 1
	v_mov_b32_dpp v6, v6 row_bcast:15 row_mask:0xa bank_mask:0xf
	v_max_f32_e32 v6, v6, v6
	v_max_f32_e32 v2, v2, v6
	v_mov_b32_e32 v6, v2
	s_nop 1
	v_mov_b32_dpp v6, v6 row_bcast:31 row_mask:0xc bank_mask:0xf
	v_max_f32_e32 v6, v6, v6
	v_max_f32_e32 v2, v2, v6
	v_max_f32_e32 v6, v240, v240
	v_readlane_b32 s0, v2, 63
	s_nop 1
	v_max_f32_e64 v2, s0, s0
	v_max_f32_e32 v2, v6, v2
	v_sub_f32_e32 v5, v5, v2
	v_exp_f32_e32 v5, v5
	v_sub_f32_e32 v4, v240, v2
	v_exp_f32_e32 v40, v4
	v_mov_b32_e32 v240, v2
	v_cndmask_b32_e64 v4, v5, 0, vcc
	v_cndmask_b32_e32 v5, v13, v209, vcc
	v_mov_b32_e32 v6, v5
	v_fma_f32 v111, v111, v40, v4
	s_nop 0
	v_mov_b32_dpp v6, v6 row_shr:1 row_mask:0xf bank_mask:0xf
	v_max_f32_e32 v6, v6, v6
	v_max_f32_e32 v6, v5, v6
	v_mov_b32_e32 v7, v6
	s_nop 1
	v_mov_b32_dpp v7, v7 row_shr:2 row_mask:0xf bank_mask:0xf
	v_max_f32_e32 v7, v7, v7
	v_max_f32_e32 v6, v6, v7
	v_mov_b32_e32 v7, v6
	s_nop 1
	v_mov_b32_dpp v7, v7 row_shr:4 row_mask:0xf bank_mask:0xf
	v_max_f32_e32 v7, v7, v7
	v_max_f32_e32 v6, v6, v7
	v_mov_b32_e32 v7, v6
	s_nop 1
	v_mov_b32_dpp v7, v7 row_shr:8 row_mask:0xf bank_mask:0xf
	v_max_f32_e32 v7, v7, v7
	v_max_f32_e32 v6, v6, v7
	v_mov_b32_e32 v7, v6
	s_nop 1
	v_mov_b32_dpp v7, v7 row_bcast:15 row_mask:0xa bank_mask:0xf
	v_max_f32_e32 v7, v7, v7
	v_max_f32_e32 v6, v6, v7
	v_mov_b32_e32 v7, v6
	s_nop 1
	v_mov_b32_dpp v7, v7 row_bcast:31 row_mask:0xc bank_mask:0xf
	v_max_f32_e32 v7, v7, v7
	v_max_f32_e32 v6, v6, v7
	v_max_f32_e32 v7, v238, v238
	v_readlane_b32 s0, v6, 63
	s_nop 1
	v_max_f32_e64 v6, s0, s0
	v_max_f32_e32 v54, v7, v6
	v_sub_f32_e32 v6, v238, v54
	v_exp_f32_e32 v41, v6
	v_cndmask_b32_e32 v6, v14, v209, vcc
	v_mov_b32_e32 v7, v6
	v_sub_f32_e32 v5, v5, v54
	v_exp_f32_e32 v5, v5
	v_mov_b32_dpp v7, v7 row_shr:1 row_mask:0xf bank_mask:0xf
	v_max_f32_e32 v7, v7, v7
	v_max_f32_e32 v7, v6, v7
	v_mov_b32_e32 v8, v7
	v_cndmask_b32_e64 v5, v5, 0, vcc
	v_fma_f32 v123, v123, v41, v5
	v_mov_b32_dpp v8, v8 row_shr:2 row_mask:0xf bank_mask:0xf
	v_max_f32_e32 v8, v8, v8
	v_max_f32_e32 v7, v7, v8
	v_mov_b32_e32 v8, v7
	v_mov_b32_e32 v238, v54
	s_nop 0
	v_mov_b32_dpp v8, v8 row_shr:4 row_mask:0xf bank_mask:0xf
	v_max_f32_e32 v8, v8, v8
	v_max_f32_e32 v7, v7, v8
	v_mov_b32_e32 v8, v7
	s_nop 1
	v_mov_b32_dpp v8, v8 row_shr:8 row_mask:0xf bank_mask:0xf
	v_max_f32_e32 v8, v8, v8
	v_max_f32_e32 v7, v7, v8
	v_mov_b32_e32 v8, v7
	s_nop 1
	v_mov_b32_dpp v8, v8 row_bcast:15 row_mask:0xa bank_mask:0xf
	v_max_f32_e32 v8, v8, v8
	v_max_f32_e32 v7, v7, v8
	v_mov_b32_e32 v8, v7
	s_nop 1
	v_mov_b32_dpp v8, v8 row_bcast:31 row_mask:0xc bank_mask:0xf
	v_max_f32_e32 v8, v8, v8
	v_max_f32_e32 v7, v7, v8
	v_max_f32_e32 v8, v236, v236
	v_readlane_b32 s0, v7, 63
	s_nop 1
	v_max_f32_e64 v7, s0, s0
	v_max_f32_e32 v55, v8, v7
	v_sub_f32_e32 v7, v236, v55
	v_exp_f32_e32 v44, v7
	v_mov_b32_e32 v7, v3
	v_sub_f32_e32 v6, v6, v55
	v_exp_f32_e32 v6, v6
	v_mov_b32_dpp v7, v7 row_shr:1 row_mask:0xf bank_mask:0xf
	v_max_f32_e32 v7, v7, v7
	v_max_f32_e32 v7, v3, v7
	v_mov_b32_e32 v8, v7
	v_cndmask_b32_e64 v6, v6, 0, vcc
	v_fma_f32 v121, v121, v44, v6
	v_mov_b32_dpp v8, v8 row_shr:2 row_mask:0xf bank_mask:0xf
	v_max_f32_e32 v8, v8, v8
	v_max_f32_e32 v7, v7, v8
	v_mov_b32_e32 v8, v7
	v_mov_b32_e32 v236, v55
	s_nop 0
	v_mov_b32_dpp v8, v8 row_shr:4 row_mask:0xf bank_mask:0xf
	v_max_f32_e32 v8, v8, v8
	v_max_f32_e32 v7, v7, v8
	v_mov_b32_e32 v8, v7
	s_nop 1
	v_mov_b32_dpp v8, v8 row_shr:8 row_mask:0xf bank_mask:0xf
	v_max_f32_e32 v8, v8, v8
	v_max_f32_e32 v7, v7, v8
	v_mov_b32_e32 v8, v7
	s_nop 1
	v_mov_b32_dpp v8, v8 row_bcast:15 row_mask:0xa bank_mask:0xf
	v_max_f32_e32 v8, v8, v8
	v_max_f32_e32 v7, v7, v8
	v_mov_b32_e32 v8, v7
	s_nop 1
	v_mov_b32_dpp v8, v8 row_bcast:31 row_mask:0xc bank_mask:0xf
	v_max_f32_e32 v8, v8, v8
	v_max_f32_e32 v7, v7, v8
	v_max_f32_e32 v8, v234, v234
	v_readlane_b32 s0, v7, 63
	s_nop 1
	v_max_f32_e64 v7, s0, s0
	v_max_f32_e32 v56, v8, v7
	v_sub_f32_e32 v3, v3, v56
	v_exp_f32_e32 v3, v3
	v_sub_f32_e32 v7, v234, v56
	v_exp_f32_e32 v45, v7
	v_mov_b32_e32 v234, v56
	v_cndmask_b32_e64 v7, v3, 0, vcc
	ds_write_b128 v127, v[4:7] offset:18432
	s_waitcnt lgkmcnt(0)
	v_mov_b32_e32 v3, v7
	ds_read_b128 v[4:7], v57 offset:18432
	ds_read_b128 v[8:11], v57 offset:18448
	ds_read_b128 v[12:15], v57 offset:18464
	ds_read_b128 v[16:19], v57 offset:18480
	ds_read_b128 v[20:23], v57 offset:18496
	ds_read_b128 v[24:27], v57 offset:18512
	ds_read_b128 v[28:31], v57 offset:18528
	ds_read_b128 v[32:35], v57 offset:18544
	ds_read_b128 v[36:39], v57 offset:18560
	s_waitcnt lgkmcnt(8)
; #define LAS __attribute__((address_space(3)))
; __device__ __forceinline__ void seg_attend(SegAcc& A, const float* base, int kvh, int nk, bool valid, const LAS float* qs, LAS float* pt, int lane) {
;     ...
; #pragma unroll
;     for (int k = 0; k < 64; ++k) { const f32x4 pk = *(const LAS f32x4*)(pt + 4 * k);
; #pragma unroll
;         for (int gq = 0; gq < 4; ++gq) A.o[gq] += pk[gq] * vv[k]; }
	v_pk_mul_f32 v[4:5], v[0:1], v[4:5] op_sel_hi:[0,1]
	v_pk_fma_f32 v[4:5], v[114:115], v[40:41], v[4:5]
	ds_read_b128 v[40:43], v57 offset:18576
	s_waitcnt lgkmcnt(8)
	v_pk_fma_f32 v[4:5], v[116:117], v[8:9], v[4:5] op_sel_hi:[0,1,1]
	s_waitcnt lgkmcnt(7)
	v_pk_fma_f32 v[4:5], v[118:119], v[12:13], v[4:5] op_sel_hi:[0,1,1]
	s_waitcnt lgkmcnt(6)
	v_pk_fma_f32 v[4:5], v[120:121], v[16:17], v[4:5] op_sel_hi:[0,1,1]
	s_waitcnt lgkmcnt(5)
	v_pk_fma_f32 v[4:5], v[0:1], v[20:21], v[4:5] op_sel_hi:[0,1,1]
	s_waitcnt lgkmcnt(4)
	v_pk_fma_f32 v[4:5], v[0:1], v[24:25], v[4:5] op_sel_hi:[0,1,1]
	s_waitcnt lgkmcnt(3)
	v_pk_fma_f32 v[4:5], v[0:1], v[28:29], v[4:5] op_sel_hi:[0,1,1]
	s_waitcnt lgkmcnt(2)
	v_pk_fma_f32 v[4:5], v[0:1], v[32:33], v[4:5] op_sel_hi:[0,1,1]
	s_waitcnt lgkmcnt(1)
	v_pk_fma_f32 v[48:49], v[0:1], v[36:37], v[4:5] op_sel_hi:[0,1,1]
	v_pk_mul_f32 v[4:5], v[0:1], v[6:7] op_sel_hi:[0,1]
	v_pk_fma_f32 v[4:5], v[112:113], v[44:45], v[4:5]
	v_fmac_f32_e32 v3, v125, v45
	v_pk_fma_f32 v[4:5], v[116:117], v[10:11], v[4:5] op_sel_hi:[0,1,1]
	v_pk_fma_f32 v[4:5], v[118:119], v[14:15], v[4:5] op_sel_hi:[0,1,1]
	v_pk_fma_f32 v[4:5], v[120:121], v[18:19], v[4:5] op_sel_hi:[0,1,1]
	v_pk_fma_f32 v[4:5], v[0:1], v[22:23], v[4:5] op_sel_hi:[0,1,1]
	v_pk_fma_f32 v[4:5], v[0:1], v[26:27], v[4:5] op_sel_hi:[0,1,1]
	v_pk_fma_f32 v[4:5], v[0:1], v[30:31], v[4:5] op_sel_hi:[0,1,1]
	v_pk_fma_f32 v[4:5], v[0:1], v[34:35], v[4:5] op_sel_hi:[0,1,1]
	v_pk_fma_f32 v[50:51], v[0:1], v[38:39], v[4:5] op_sel_hi:[0,1,1]
	ds_read_b128 v[4:7], v57 offset:18592
	ds_read_b128 v[8:11], v57 offset:18608
	ds_read_b128 v[12:15], v57 offset:18624
	ds_read_b128 v[16:19], v57 offset:18640
	ds_read_b128 v[20:23], v57 offset:18656
	ds_read_b128 v[24:27], v57 offset:18672
	ds_read_b128 v[28:31], v57 offset:18688
	ds_read_b128 v[32:35], v57 offset:18704
	ds_read_b128 v[36:39], v57 offset:18720
	ds_read_b128 v[44:47], v57 offset:18736
	s_waitcnt lgkmcnt(10)
	v_pk_fma_f32 v[40:41], v[0:1], v[40:41], v[48:49] op_sel_hi:[0,1,1]
	s_waitcnt lgkmcnt(9)
	v_pk_fma_f32 v[4:5], v[0:1], v[4:5], v[40:41] op_sel_hi:[0,1,1]
	s_waitcnt lgkmcnt(8)
	v_pk_fma_f32 v[4:5], v[0:1], v[8:9], v[4:5] op_sel_hi:[0,1,1]
	s_waitcnt lgkmcnt(7)
	v_pk_fma_f32 v[4:5], v[0:1], v[12:13], v[4:5] op_sel_hi:[0,1,1]
	s_waitcnt lgkmcnt(6)
	v_pk_fma_f32 v[4:5], v[0:1], v[16:17], v[4:5] op_sel_hi:[0,1,1]
	s_waitcnt lgkmcnt(5)
	v_pk_fma_f32 v[4:5], v[0:1], v[20:21], v[4:5] op_sel_hi:[0,1,1]
	s_waitcnt lgkmcnt(4)
	v_pk_fma_f32 v[4:5], v[0:1], v[24:25], v[4:5] op_sel_hi:[0,1,1]
	s_waitcnt lgkmcnt(3)
	v_pk_fma_f32 v[4:5], v[0:1], v[28:29], v[4:5] op_sel_hi:[0,1,1]
	s_waitcnt lgkmcnt(2)
	v_pk_fma_f32 v[4:5], v[0:1], v[32:33], v[4:5] op_sel_hi:[0,1,1]
	s_waitcnt lgkmcnt(1)
	v_pk_fma_f32 v[4:5], v[0:1], v[36:37], v[4:5] op_sel_hi:[0,1,1]
	s_waitcnt lgkmcnt(0)
	v_pk_fma_f32 v[48:49], v[0:1], v[44:45], v[4:5] op_sel_hi:[0,1,1]
	v_pk_fma_f32 v[4:5], v[0:1], v[42:43], v[50:51] op_sel_hi:[0,1,1]
	v_pk_fma_f32 v[4:5], v[0:1], v[6:7], v[4:5] op_sel_hi:[0,1,1]
	v_pk_fma_f32 v[4:5], v[0:1], v[10:11], v[4:5] op_sel_hi:[0,1,1]
	v_pk_fma_f32 v[4:5], v[0:1], v[14:15], v[4:5] op_sel_hi:[0,1,1]
	v_pk_fma_f32 v[4:5], v[0:1], v[18:19], v[4:5] op_sel_hi:[0,1,1]
	v_pk_fma_f32 v[4:5], v[0:1], v[22:23], v[4:5] op_sel_hi:[0,1,1]
	v_pk_fma_f32 v[4:5], v[0:1], v[26:27], v[4:5] op_sel_hi:[0,1,1]
	v_pk_fma_f32 v[4:5], v[0:1], v[30:31], v[4:5] op_sel_hi:[0,1,1]
	v_pk_fma_f32 v[4:5], v[0:1], v[34:35], v[4:5] op_sel_hi:[0,1,1]
	v_pk_fma_f32 v[4:5], v[0:1], v[38:39], v[4:5] op_sel_hi:[0,1,1]
	v_pk_fma_f32 v[52:53], v[0:1], v[46:47], v[4:5] op_sel_hi:[0,1,1]
	ds_read_b128 v[4:7], v57 offset:18752
	ds_read_b128 v[8:11], v57 offset:18768
	ds_read_b128 v[12:15], v57 offset:18784
	ds_read_b128 v[16:19], v57 offset:18800
	ds_read_b128 v[20:23], v57 offset:18816
	ds_read_b128 v[24:27], v57 offset:18832
	ds_read_b128 v[28:31], v57 offset:18848
	ds_read_b128 v[32:35], v57 offset:18864
	ds_read_b128 v[36:39], v57 offset:18880
	ds_read_b128 v[40:43], v57 offset:18896
	ds_read_b128 v[44:47], v57 offset:18912
	s_waitcnt lgkmcnt(10)
	v_pk_fma_f32 v[4:5], v[0:1], v[4:5], v[48:49] op_sel_hi:[0,1,1]
	s_waitcnt lgkmcnt(9)
	v_pk_fma_f32 v[4:5], v[0:1], v[8:9], v[4:5] op_sel_hi:[0,1,1]
	s_waitcnt lgkmcnt(8)
	v_pk_fma_f32 v[4:5], v[0:1], v[12:13], v[4:5] op_sel_hi:[0,1,1]
	s_waitcnt lgkmcnt(7)
	v_pk_fma_f32 v[4:5], v[0:1], v[16:17], v[4:5] op_sel_hi:[0,1,1]
	s_waitcnt lgkmcnt(6)
	v_pk_fma_f32 v[4:5], v[0:1], v[20:21], v[4:5] op_sel_hi:[0,1,1]
	s_waitcnt lgkmcnt(5)
	v_pk_fma_f32 v[4:5], v[0:1], v[24:25], v[4:5] op_sel_hi:[0,1,1]
	s_waitcnt lgkmcnt(4)
	v_pk_fma_f32 v[4:5], v[0:1], v[28:29], v[4:5] op_sel_hi:[0,1,1]
	s_waitcnt lgkmcnt(3)
	v_pk_fma_f32 v[4:5], v[0:1], v[32:33], v[4:5] op_sel_hi:[0,1,1]
	s_waitcnt lgkmcnt(2)
	v_pk_fma_f32 v[4:5], v[0:1], v[36:37], v[4:5] op_sel_hi:[0,1,1]
	s_waitcnt lgkmcnt(1)
	v_pk_fma_f32 v[4:5], v[0:1], v[40:41], v[4:5] op_sel_hi:[0,1,1]
	s_waitcnt lgkmcnt(0)
	v_pk_fma_f32 v[44:45], v[0:1], v[44:45], v[4:5] op_sel_hi:[0,1,1]
	v_pk_fma_f32 v[4:5], v[0:1], v[6:7], v[52:53] op_sel_hi:[0,1,1]
	v_pk_fma_f32 v[4:5], v[0:1], v[10:11], v[4:5] op_sel_hi:[0,1,1]
	v_pk_fma_f32 v[4:5], v[0:1], v[14:15], v[4:5] op_sel_hi:[0,1,1]
	v_pk_fma_f32 v[4:5], v[0:1], v[18:19], v[4:5] op_sel_hi:[0,1,1]
	v_pk_fma_f32 v[4:5], v[0:1], v[22:23], v[4:5] op_sel_hi:[0,1,1]
	ds_read_b128 v[48:51], v57 offset:18928
	v_pk_fma_f32 v[4:5], v[0:1], v[26:27], v[4:5] op_sel_hi:[0,1,1]
	v_pk_fma_f32 v[4:5], v[0:1], v[30:31], v[4:5] op_sel_hi:[0,1,1]
	v_pk_fma_f32 v[4:5], v[0:1], v[34:35], v[4:5] op_sel_hi:[0,1,1]
	v_pk_fma_f32 v[4:5], v[0:1], v[38:39], v[4:5] op_sel_hi:[0,1,1]
	v_pk_fma_f32 v[4:5], v[0:1], v[42:43], v[4:5] op_sel_hi:[0,1,1]
	v_pk_fma_f32 v[46:47], v[0:1], v[46:47], v[4:5] op_sel_hi:[0,1,1]
	ds_read_b128 v[4:7], v57 offset:18944
	ds_read_b128 v[8:11], v57 offset:18960
	ds_read_b128 v[12:15], v57 offset:18976
	ds_read_b128 v[16:19], v57 offset:18992
	ds_read_b128 v[20:23], v57 offset:19008
	ds_read_b128 v[24:27], v57 offset:19024
	ds_read_b128 v[28:31], v57 offset:19040
	ds_read_b128 v[32:35], v57 offset:19056
	ds_read_b128 v[36:39], v57 offset:19072
	ds_read_b128 v[40:43], v57 offset:19088
	s_waitcnt lgkmcnt(10)
; #define LAS __attribute__((address_space(3)))
; __device__ __forceinline__ void seg_attend(SegAcc& A, const float* base, int kvh, int nk, bool valid, const LAS float* qs, LAS float* pt, int lane) {
;     ...
; #pragma unroll
;     for (int k = 0; k < 64; ++k) { const f32x4 pk = *(const LAS f32x4*)(pt + 4 * k);
; #pragma unroll
;         for (int gq = 0; gq < 4; ++gq) A.o[gq] += pk[gq] * vv[k]; }
	v_pk_fma_f32 v[44:45], v[0:1], v[48:49], v[44:45] op_sel_hi:[0,1,1]
	s_waitcnt lgkmcnt(9)
	v_pk_fma_f32 v[4:5], v[0:1], v[4:5], v[44:45] op_sel_hi:[0,1,1]
	s_waitcnt lgkmcnt(8)
	v_pk_fma_f32 v[4:5], v[0:1], v[8:9], v[4:5] op_sel_hi:[0,1,1]
	s_waitcnt lgkmcnt(7)
	v_pk_fma_f32 v[4:5], v[0:1], v[12:13], v[4:5] op_sel_hi:[0,1,1]
	s_waitcnt lgkmcnt(6)
	v_pk_fma_f32 v[4:5], v[0:1], v[16:17], v[4:5] op_sel_hi:[0,1,1]
	s_waitcnt lgkmcnt(5)
	v_pk_fma_f32 v[4:5], v[0:1], v[20:21], v[4:5] op_sel_hi:[0,1,1]
	s_waitcnt lgkmcnt(4)
	v_pk_fma_f32 v[4:5], v[0:1], v[24:25], v[4:5] op_sel_hi:[0,1,1]
	s_waitcnt lgkmcnt(3)
	v_pk_fma_f32 v[4:5], v[0:1], v[28:29], v[4:5] op_sel_hi:[0,1,1]
	s_waitcnt lgkmcnt(2)
	v_pk_fma_f32 v[4:5], v[0:1], v[32:33], v[4:5] op_sel_hi:[0,1,1]
	s_waitcnt lgkmcnt(1)
	v_pk_fma_f32 v[4:5], v[0:1], v[36:37], v[4:5] op_sel_hi:[0,1,1]
	s_waitcnt lgkmcnt(0)
	v_pk_fma_f32 v[48:49], v[0:1], v[40:41], v[4:5] op_sel_hi:[0,1,1]
	v_pk_fma_f32 v[4:5], v[0:1], v[50:51], v[46:47] op_sel_hi:[0,1,1]
	v_pk_fma_f32 v[4:5], v[0:1], v[6:7], v[4:5] op_sel_hi:[0,1,1]
	v_pk_fma_f32 v[4:5], v[0:1], v[10:11], v[4:5] op_sel_hi:[0,1,1]
	v_pk_fma_f32 v[4:5], v[0:1], v[14:15], v[4:5] op_sel_hi:[0,1,1]
	v_pk_fma_f32 v[4:5], v[0:1], v[18:19], v[4:5] op_sel_hi:[0,1,1]
	v_pk_fma_f32 v[4:5], v[0:1], v[22:23], v[4:5] op_sel_hi:[0,1,1]
	v_pk_fma_f32 v[4:5], v[0:1], v[26:27], v[4:5] op_sel_hi:[0,1,1]
	v_pk_fma_f32 v[4:5], v[0:1], v[30:31], v[4:5] op_sel_hi:[0,1,1]
	v_pk_fma_f32 v[4:5], v[0:1], v[34:35], v[4:5] op_sel_hi:[0,1,1]
	v_pk_fma_f32 v[4:5], v[0:1], v[38:39], v[4:5] op_sel_hi:[0,1,1]
	v_pk_fma_f32 v[52:53], v[0:1], v[42:43], v[4:5] op_sel_hi:[0,1,1]
	ds_read_b128 v[4:7], v57 offset:19104
	ds_read_b128 v[8:11], v57 offset:19120
	ds_read_b128 v[12:15], v57 offset:19136
	ds_read_b128 v[16:19], v57 offset:19152
	ds_read_b128 v[20:23], v57 offset:19168
	ds_read_b128 v[24:27], v57 offset:19184
	ds_read_b128 v[28:31], v57 offset:19200
	ds_read_b128 v[32:35], v57 offset:19216
	ds_read_b128 v[36:39], v57 offset:19232
	ds_read_b128 v[40:43], v57 offset:19248
	ds_read_b128 v[44:47], v57 offset:19264
	s_waitcnt lgkmcnt(10)
	v_pk_fma_f32 v[4:5], v[0:1], v[4:5], v[48:49] op_sel_hi:[0,1,1]
	s_waitcnt lgkmcnt(9)
	v_pk_fma_f32 v[4:5], v[0:1], v[8:9], v[4:5] op_sel_hi:[0,1,1]
	s_waitcnt lgkmcnt(8)
	v_pk_fma_f32 v[4:5], v[0:1], v[12:13], v[4:5] op_sel_hi:[0,1,1]
	s_waitcnt lgkmcnt(7)
	v_pk_fma_f32 v[4:5], v[0:1], v[16:17], v[4:5] op_sel_hi:[0,1,1]
	s_waitcnt lgkmcnt(6)
	v_pk_fma_f32 v[4:5], v[0:1], v[20:21], v[4:5] op_sel_hi:[0,1,1]
	s_waitcnt lgkmcnt(5)
	v_pk_fma_f32 v[4:5], v[0:1], v[24:25], v[4:5] op_sel_hi:[0,1,1]
	s_waitcnt lgkmcnt(4)
	v_pk_fma_f32 v[4:5], v[0:1], v[28:29], v[4:5] op_sel_hi:[0,1,1]
	s_waitcnt lgkmcnt(3)
	v_pk_fma_f32 v[4:5], v[0:1], v[32:33], v[4:5] op_sel_hi:[0,1,1]
	s_waitcnt lgkmcnt(2)
	v_pk_fma_f32 v[4:5], v[0:1], v[36:37], v[4:5] op_sel_hi:[0,1,1]
	s_waitcnt lgkmcnt(1)
	v_pk_fma_f32 v[4:5], v[0:1], v[40:41], v[4:5] op_sel_hi:[0,1,1]
	s_waitcnt lgkmcnt(0)
	v_pk_fma_f32 v[44:45], v[0:1], v[44:45], v[4:5] op_sel_hi:[0,1,1]
	v_pk_fma_f32 v[4:5], v[0:1], v[6:7], v[52:53] op_sel_hi:[0,1,1]
	v_pk_fma_f32 v[4:5], v[0:1], v[10:11], v[4:5] op_sel_hi:[0,1,1]
	v_pk_fma_f32 v[4:5], v[0:1], v[14:15], v[4:5] op_sel_hi:[0,1,1]
	v_pk_fma_f32 v[4:5], v[0:1], v[18:19], v[4:5] op_sel_hi:[0,1,1]
	v_pk_fma_f32 v[4:5], v[0:1], v[22:23], v[4:5] op_sel_hi:[0,1,1]
	ds_read_b128 v[48:51], v57 offset:19280
	v_pk_fma_f32 v[4:5], v[0:1], v[26:27], v[4:5] op_sel_hi:[0,1,1]
	v_pk_fma_f32 v[4:5], v[0:1], v[30:31], v[4:5] op_sel_hi:[0,1,1]
	v_pk_fma_f32 v[4:5], v[0:1], v[34:35], v[4:5] op_sel_hi:[0,1,1]
	v_pk_fma_f32 v[4:5], v[0:1], v[38:39], v[4:5] op_sel_hi:[0,1,1]
	v_pk_fma_f32 v[4:5], v[0:1], v[42:43], v[4:5] op_sel_hi:[0,1,1]
	v_pk_fma_f32 v[46:47], v[0:1], v[46:47], v[4:5] op_sel_hi:[0,1,1]
	ds_read_b128 v[4:7], v57 offset:19296
	ds_read_b128 v[8:11], v57 offset:19312
	ds_read_b128 v[12:15], v57 offset:19328
	ds_read_b128 v[16:19], v57 offset:19344
	ds_read_b128 v[20:23], v57 offset:19360
	ds_read_b128 v[24:27], v57 offset:19376
	ds_read_b128 v[28:31], v57 offset:19392
	ds_read_b128 v[32:35], v57 offset:19408
	ds_read_b128 v[36:39], v57 offset:19424
	ds_read_b128 v[40:43], v57 offset:19440
	s_waitcnt lgkmcnt(10)
	v_pk_fma_f32 v[44:45], v[0:1], v[48:49], v[44:45] op_sel_hi:[0,1,1]
	s_waitcnt lgkmcnt(9)
	v_pk_fma_f32 v[4:5], v[0:1], v[4:5], v[44:45] op_sel_hi:[0,1,1]
	s_waitcnt lgkmcnt(8)
	v_pk_fma_f32 v[4:5], v[0:1], v[8:9], v[4:5] op_sel_hi:[0,1,1]
	s_waitcnt lgkmcnt(7)
	v_pk_fma_f32 v[4:5], v[0:1], v[12:13], v[4:5] op_sel_hi:[0,1,1]
	s_waitcnt lgkmcnt(6)
	v_pk_fma_f32 v[4:5], v[0:1], v[16:17], v[4:5] op_sel_hi:[0,1,1]
	s_waitcnt lgkmcnt(5)
	v_pk_fma_f32 v[4:5], v[0:1], v[20:21], v[4:5] op_sel_hi:[0,1,1]
	s_waitcnt lgkmcnt(4)
	v_pk_fma_f32 v[4:5], v[0:1], v[24:25], v[4:5] op_sel_hi:[0,1,1]
	s_waitcnt lgkmcnt(3)
	v_pk_fma_f32 v[4:5], v[0:1], v[28:29], v[4:5] op_sel_hi:[0,1,1]
	s_waitcnt lgkmcnt(2)
	v_pk_fma_f32 v[4:5], v[0:1], v[32:33], v[4:5] op_sel_hi:[0,1,1]
	s_waitcnt lgkmcnt(1)
	v_pk_fma_f32 v[4:5], v[0:1], v[36:37], v[4:5] op_sel_hi:[0,1,1]
	s_waitcnt lgkmcnt(0)
	v_pk_fma_f32 v[114:115], v[0:1], v[40:41], v[4:5] op_sel_hi:[0,1,1]
	v_pk_fma_f32 v[4:5], v[0:1], v[50:51], v[46:47] op_sel_hi:[0,1,1]
	v_pk_fma_f32 v[4:5], v[0:1], v[6:7], v[4:5] op_sel_hi:[0,1,1]
	v_pk_fma_f32 v[4:5], v[0:1], v[10:11], v[4:5] op_sel_hi:[0,1,1]
	v_pk_fma_f32 v[4:5], v[0:1], v[14:15], v[4:5] op_sel_hi:[0,1,1]
	v_pk_fma_f32 v[4:5], v[0:1], v[18:19], v[4:5] op_sel_hi:[0,1,1]
	v_pk_fma_f32 v[4:5], v[0:1], v[22:23], v[4:5] op_sel_hi:[0,1,1]
	v_pk_fma_f32 v[4:5], v[0:1], v[26:27], v[4:5] op_sel_hi:[0,1,1]
	v_pk_fma_f32 v[4:5], v[0:1], v[30:31], v[4:5] op_sel_hi:[0,1,1]
	v_pk_fma_f32 v[4:5], v[0:1], v[34:35], v[4:5] op_sel_hi:[0,1,1]
	s_waitcnt lgkmcnt(0)
	v_pk_fma_f32 v[4:5], v[0:1], v[38:39], v[4:5] op_sel_hi:[0,1,1]
	v_pk_fma_f32 v[112:113], v[0:1], v[42:43], v[4:5] op_sel_hi:[0,1,1]
	v_mov_b32_e32 v125, v3
